# lever 4 A/B: v12 + all per-segment s_setprio flips deleted in the 8 K-loops
# speedup vs baseline: 1.0162x; 1.0162x over previous
; #define PG8_STAGE(bufoff, gbase, voff) do { _Pragma("unroll") for (int _i = 0; _i < 2; ++_i) \
;         __builtin_amdgcn_global_load_lds((const unsigned*)((const char*)(gbase) + (voff)[_i]), (PG8_LAS unsigned*)(lds + (bufoff) + ldsw + _i * 8192), 16, 0, 0); } while (0)
; #define PG8_LDA(dst, b, h) do { _Pragma("unroll") for (int m = 0; m < 4; ++m) _Pragma("unroll") for (int k = 0; k < 2; ++k) dst[m][k] = *(const PG8_LAS bf16x8*)(lds + PG8_SA(b, h) + aoff + m * 2048 + k * 1024); } while (0)
; #define PG8_LDB(dst, b, h) do { _Pragma("unroll") for (int n = 0; n < 2; ++n) _Pragma("unroll") for (int k = 0; k < 2; ++k) dst[n][k] = *(const PG8_LAS bf16x8*)(lds + PG8_SB(b, h) + boff + n * 2048 + k * 1024); } while (0)
; #define PG8_WAIT_V(n) asm volatile("s_waitcnt vmcnt(" #n ")" ::: "memory")
; #define PG8_WAIT_L(n) asm volatile("s_waitcnt lgkmcnt(" #n ")" ::: "memory")
; #define PG8_BAR __builtin_amdgcn_s_barrier()
; #define PG8_SCHED __builtin_amdgcn_sched_barrier(0)
; template <class Epi, class Sched, bool ALIGN_EPI = false, bool SP2 = false>
; __device__ __forceinline__ void gemm_phase(PG8_LAS unsigned char* lds, const Gemm g, const Sched& S, const Epi& E) {
;     ...
;             const char* a1 = cA + (size_t)(t + 1) * kstep;
;             const char* a2 = last ? nA : cA + (size_t)(t + 2) * kstep; const char* b2 = last ? nB : cB + (size_t)(t + 2) * kstep;
;             const char* a3 = a2 + kstep; const char* b3 = b2 + kstep;
;             if (last && has_next) S.a_ready(nxt);
;             if constexpr (SP2) {
;             PG8_LDB(B0, 0, 0); PG8_LDB(B1, 0, 1); PG8_SCHED; PG8_LDA(At, 0, 0); PG8_STAGE(PG8_SA(1, 1), a1 + hstep, voffA);
;             PG8_WAIT_V(8); PG8_WAIT_L(0); PG8_BAR; PG8_MMA(0, 0, At, B0); PG8_MMA(0, 1, At, B1); PG8_BAR; PG8_SCHED;
;             PG8_LDA(At, 0, 1); PG8_STAGE(PG8_SB(0, 0), b2, voffB); PG8_STAGE(PG8_SB(0, 1), b2 + hstep, voffB); PG8_STAGE(PG8_SA(0, 0), a2, voffA);
;             PG8_WAIT_V(8); PG8_WAIT_L(0); PG8_BAR; PG8_MMA(1, 0, At, B0); PG8_MMA(1, 1, At, B1); PG8_BAR; PG8_SCHED;
;             PG8_LDB(B0, 1, 0); PG8_LDB(B1, 1, 1); PG8_SCHED; PG8_LDA(At, 1, 0); PG8_STAGE(PG8_SA(0, 1), a2 + hstep, voffA);
;             PG8_WAIT_V(8); PG8_WAIT_L(0); PG8_BAR; PG8_MMA(0, 0, At, B0); PG8_MMA(0, 1, At, B1); PG8_BAR; PG8_SCHED;
.LBB0_115:
	ds_read_b128 v[154:157], v150
	ds_read_b128 v[158:161], v150 offset:1024
	ds_read_b128 v[162:165], v150 offset:2048
	ds_read_b128 v[166:169], v150 offset:3072
	ds_read_b128 v[170:173], v151
	ds_read_b128 v[174:177], v151 offset:1024
	ds_read_b128 v[180:183], v151 offset:2048
	ds_read_b128 v[184:187], v151 offset:3072
	s_add_u32 s50, s48, 0x4000
	s_addc_u32 s51, s49, 0
	s_cmp_eq_u32 s76, 60
	s_cselect_b32 s74, s64, s50
	s_cselect_b32 s75, s25, s51
	s_cselect_b32 s72, s65, s68
	s_cselect_b32 s73, s19, s69
	s_add_u32 s50, s74, 0x8000
	s_addc_u32 s51, s75, 0
	s_sub_u32 s50, s48, 0x4000
	s_subb_u32 s51, s49, 0
	s_mov_b32 m0, s58
	s_nop 0
	global_load_lds_dwordx4 v130, s[50:51]
	s_mov_b32 m0, s59
	s_nop 0
	global_load_lds_dwordx4 v134, s[50:51]
	s_add_i32 m0, s28, 0xc000
	ds_read_b128 v[188:191], v152
	ds_read_b128 v[196:199], v152 offset:1024
	ds_read_b128 v[200:203], v152 offset:2048
	ds_read_b128 v[204:207], v152 offset:3072
	ds_read_b128 v[208:211], v152 offset:4096
	ds_read_b128 v[212:215], v152 offset:5120
	ds_read_b128 v[216:219], v152 offset:6144
	ds_read_b128 v[220:223], v152 offset:7168
	global_load_lds_dwordx4 v140, s[48:49]
	s_add_i32 m0, s28, 0xe000
	s_nop 0
	global_load_lds_dwordx4 v142, s[48:49]
	s_waitcnt vmcnt(8)
	s_waitcnt lgkmcnt(0)
	s_barrier
	s_waitcnt lgkmcnt(0)
	v_mfma_f32_16x16x32_bf16 v[126:129], v[154:157], v[188:191], v[126:129]
	v_mfma_f32_16x16x32_bf16 v[126:129], v[158:161], v[196:199], v[126:129]
	v_mfma_f32_16x16x32_bf16 v[110:113], v[154:157], v[200:203], v[110:113]
	v_mfma_f32_16x16x32_bf16 v[110:113], v[158:161], v[204:207], v[110:113]
	v_mfma_f32_16x16x32_bf16 v[94:97], v[154:157], v[208:211], v[94:97]
	v_mfma_f32_16x16x32_bf16 v[94:97], v[158:161], v[212:215], v[94:97]
	v_mfma_f32_16x16x32_bf16 v[78:81], v[154:157], v[216:219], v[78:81]
	v_mfma_f32_16x16x32_bf16 v[78:81], v[158:161], v[220:223], v[78:81]
	v_mfma_f32_16x16x32_bf16 v[70:73], v[162:165], v[216:219], v[70:73]
	v_mfma_f32_16x16x32_bf16 v[70:73], v[166:169], v[220:223], v[70:73]
	v_mfma_f32_16x16x32_bf16 v[86:89], v[162:165], v[208:211], v[86:89]
	v_mfma_f32_16x16x32_bf16 v[86:89], v[166:169], v[212:215], v[86:89]
	v_mfma_f32_16x16x32_bf16 v[102:105], v[162:165], v[200:203], v[102:105]
	v_mfma_f32_16x16x32_bf16 v[102:105], v[166:169], v[204:207], v[102:105]
	v_mfma_f32_16x16x32_bf16 v[118:121], v[162:165], v[188:191], v[118:121]
	v_mfma_f32_16x16x32_bf16 v[118:121], v[166:169], v[196:199], v[118:121]
	v_mfma_f32_16x16x32_bf16 v[122:125], v[170:173], v[188:191], v[122:125]
	v_mfma_f32_16x16x32_bf16 v[122:125], v[174:177], v[196:199], v[122:125]
	v_mfma_f32_16x16x32_bf16 v[106:109], v[170:173], v[200:203], v[106:109]
	v_mfma_f32_16x16x32_bf16 v[106:109], v[174:177], v[204:207], v[106:109]
	v_mfma_f32_16x16x32_bf16 v[90:93], v[170:173], v[208:211], v[90:93]
	v_mfma_f32_16x16x32_bf16 v[90:93], v[174:177], v[212:215], v[90:93]
	v_mfma_f32_16x16x32_bf16 v[74:77], v[170:173], v[216:219], v[74:77]
	v_mfma_f32_16x16x32_bf16 v[74:77], v[174:177], v[220:223], v[74:77]
	v_mfma_f32_16x16x32_bf16 v[66:69], v[180:183], v[216:219], v[66:69]
	v_mfma_f32_16x16x32_bf16 v[66:69], v[184:187], v[220:223], v[66:69]
	v_mfma_f32_16x16x32_bf16 v[82:85], v[180:183], v[208:211], v[82:85]
	v_mfma_f32_16x16x32_bf16 v[82:85], v[184:187], v[212:215], v[82:85]
	v_mfma_f32_16x16x32_bf16 v[98:101], v[180:183], v[200:203], v[98:101]
	v_mfma_f32_16x16x32_bf16 v[98:101], v[184:187], v[204:207], v[98:101]
	v_mfma_f32_16x16x32_bf16 v[114:117], v[180:183], v[188:191], v[114:117]
	v_mfma_f32_16x16x32_bf16 v[114:117], v[184:187], v[196:199], v[114:117]
	s_barrier
	s_add_i32 s77, s61, s3
	s_mov_b32 m0, s77
	ds_read_b128 v[188:191], v152 offset:16384
	ds_read_b128 v[196:199], v152 offset:17408
	ds_read_b128 v[200:203], v152 offset:18432
	ds_read_b128 v[204:207], v152 offset:19456
	ds_read_b128 v[208:211], v152 offset:20480
	ds_read_b128 v[212:215], v152 offset:21504
	ds_read_b128 v[216:219], v152 offset:22528
	ds_read_b128 v[220:223], v152 offset:23552
	global_load_lds_dwordx4 v132, s[72:73]
	s_add_i32 m0, s77, 0x2000
	s_add_u32 s78, s72, 0x4000
	s_addc_u32 s79, s73, 0
	s_add_i32 s77, s62, s3
	global_load_lds_dwordx4 v136, s[72:73]
	s_mov_b32 m0, s77
	s_nop 0
	global_load_lds_dwordx4 v132, s[78:79]
	s_add_i32 m0, s77, 0x2000
	s_nop 0
	global_load_lds_dwordx4 v136, s[78:79]
	s_waitcnt vmcnt(6)
	s_waitcnt lgkmcnt(0)
	s_barrier
	s_waitcnt lgkmcnt(0)
	v_mfma_f32_16x16x32_bf16 v[62:65], v[154:157], v[188:191], v[62:65]
	v_mfma_f32_16x16x32_bf16 v[62:65], v[158:161], v[196:199], v[62:65]
	v_mfma_f32_16x16x32_bf16 v[46:49], v[154:157], v[200:203], v[46:49]
	v_mfma_f32_16x16x32_bf16 v[46:49], v[158:161], v[204:207], v[46:49]
	v_mfma_f32_16x16x32_bf16 v[30:33], v[154:157], v[208:211], v[30:33]
	v_mfma_f32_16x16x32_bf16 v[30:33], v[158:161], v[212:215], v[30:33]
	v_mfma_f32_16x16x32_bf16 v[14:17], v[154:157], v[216:219], v[14:17]
	v_mfma_f32_16x16x32_bf16 v[14:17], v[158:161], v[220:223], v[14:17]
	v_mfma_f32_16x16x32_bf16 v[6:9], v[162:165], v[216:219], v[6:9]
	v_mfma_f32_16x16x32_bf16 v[6:9], v[166:169], v[220:223], v[6:9]
	v_mfma_f32_16x16x32_bf16 v[22:25], v[162:165], v[208:211], v[22:25]
	v_mfma_f32_16x16x32_bf16 v[22:25], v[166:169], v[212:215], v[22:25]
	v_mfma_f32_16x16x32_bf16 v[38:41], v[162:165], v[200:203], v[38:41]
	v_mfma_f32_16x16x32_bf16 v[38:41], v[166:169], v[204:207], v[38:41]
	v_mfma_f32_16x16x32_bf16 v[54:57], v[162:165], v[188:191], v[54:57]
	v_mfma_f32_16x16x32_bf16 v[54:57], v[166:169], v[196:199], v[54:57]
	v_mfma_f32_16x16x32_bf16 v[58:61], v[170:173], v[188:191], v[58:61]
	v_mfma_f32_16x16x32_bf16 v[58:61], v[174:177], v[196:199], v[58:61]
	v_mfma_f32_16x16x32_bf16 v[42:45], v[170:173], v[200:203], v[42:45]
	v_mfma_f32_16x16x32_bf16 v[42:45], v[174:177], v[204:207], v[42:45]
	v_mfma_f32_16x16x32_bf16 v[26:29], v[170:173], v[208:211], v[26:29]
	v_mfma_f32_16x16x32_bf16 v[26:29], v[174:177], v[212:215], v[26:29]
	v_mfma_f32_16x16x32_bf16 v[10:13], v[170:173], v[216:219], v[10:13]
	v_mfma_f32_16x16x32_bf16 v[10:13], v[174:177], v[220:223], v[10:13]
	v_mfma_f32_16x16x32_bf16 v[2:5], v[180:183], v[216:219], v[2:5]
	v_mfma_f32_16x16x32_bf16 v[2:5], v[184:187], v[220:223], v[2:5]
	v_mfma_f32_16x16x32_bf16 v[18:21], v[180:183], v[208:211], v[18:21]
	v_mfma_f32_16x16x32_bf16 v[18:21], v[184:187], v[212:215], v[18:21]
	v_mfma_f32_16x16x32_bf16 v[34:37], v[180:183], v[200:203], v[34:37]
	v_mfma_f32_16x16x32_bf16 v[34:37], v[184:187], v[204:207], v[34:37]
	v_mfma_f32_16x16x32_bf16 v[50:53], v[180:183], v[188:191], v[50:53]
	v_mfma_f32_16x16x32_bf16 v[50:53], v[184:187], v[196:199], v[50:53]
	s_barrier
; #define PG8_STAGE(bufoff, gbase, voff) do { _Pragma("unroll") for (int _i = 0; _i < 2; ++_i) \
;         __builtin_amdgcn_global_load_lds((const unsigned*)((const char*)(gbase) + (voff)[_i]), (PG8_LAS unsigned*)(lds + (bufoff) + ldsw + _i * 8192), 16, 0, 0); } while (0)
; #define PG8_LDA(dst, b, h) do { _Pragma("unroll") for (int m = 0; m < 4; ++m) _Pragma("unroll") for (int k = 0; k < 2; ++k) dst[m][k] = *(const PG8_LAS bf16x8*)(lds + PG8_SA(b, h) + aoff + m * 2048 + k * 1024); } while (0)
; #define PG8_LDB(dst, b, h) do { _Pragma("unroll") for (int n = 0; n < 2; ++n) _Pragma("unroll") for (int k = 0; k < 2; ++k) dst[n][k] = *(const PG8_LAS bf16x8*)(lds + PG8_SB(b, h) + boff + n * 2048 + k * 1024); } while (0)
; #define PG8_MMA(ai, bj, At, Bt) do { __builtin_amdgcn_s_setprio(1); _Pragma("unroll") for (int m = 0; m < 4; ++m) _Pragma("unroll") for (int n = 0; n < 2; ++n) _Pragma("unroll") for (int k = 0; k < 2; ++k) \
;         acc[ai][bj][m][n] = __builtin_amdgcn_mfma_f32_16x16x32_bf16(Bt[n][k], At[m][k], acc[ai][bj][m][n], 0, 0, 0); __builtin_amdgcn_s_setprio(0); } while (0)
; #define PG8_WAIT_V(n) asm volatile("s_waitcnt vmcnt(" #n ")" ::: "memory")
; #define PG8_WAIT_L(n) asm volatile("s_waitcnt lgkmcnt(" #n ")" ::: "memory")
; #define PG8_BAR __builtin_amdgcn_s_barrier()
; #define PG8_SCHED __builtin_amdgcn_sched_barrier(0)
; template <class Epi, class Sched, bool ALIGN_EPI = false, bool SP2 = false>
; __device__ __forceinline__ void gemm_phase(PG8_LAS unsigned char* lds, const Gemm g, const Sched& S, const Epi& E) {
;     ...
;             PG8_LDB(B0, 1, 0); PG8_LDB(B1, 1, 1); PG8_SCHED; PG8_LDA(At, 1, 0); PG8_STAGE(PG8_SA(0, 1), a2 + hstep, voffA);
;             PG8_WAIT_V(8); PG8_WAIT_L(0); PG8_BAR; PG8_MMA(0, 0, At, B0); PG8_MMA(0, 1, At, B1); PG8_BAR; PG8_SCHED;
;             PG8_LDA(At, 1, 1); PG8_STAGE(PG8_SB(1, 0), b3, voffB); PG8_STAGE(PG8_SB(1, 1), b3 + hstep, voffB); PG8_STAGE(PG8_SA(1, 0), a3, voffA);
;             PG8_WAIT_V(8); PG8_WAIT_L(0); PG8_BAR; PG8_MMA(1, 0, At, B0); PG8_MMA(1, 1, At, B1); PG8_BAR; PG8_SCHED;
;     ...
;         if constexpr (ALIGN_EPI) { if (wr == 0) PG8_BAR; }
	s_add_i32 s77, 0, 0x18000
	v_add_u32_e32 v138, s77, v148
	s_add_i32 s78, 0, 0x1c000
	ds_read_b128 v[154:157], v138
	ds_read_b128 v[158:161], v138 offset:1024
	ds_read_b128 v[162:165], v138 offset:2048
	ds_read_b128 v[166:169], v138 offset:3072
	v_add_u32_e32 v138, s78, v148
	ds_read_b128 v[170:173], v138
	ds_read_b128 v[174:177], v138 offset:1024
	ds_read_b128 v[180:183], v138 offset:2048
	ds_read_b128 v[184:187], v138 offset:3072
	s_mov_b32 m0, s28
	s_nop 0
	global_load_lds_dwordx4 v130, s[74:75]
	s_mov_b32 m0, s29
	s_nop 0
	global_load_lds_dwordx4 v134, s[74:75]
	s_add_u32 s74, s74, 0x4000
	s_addc_u32 s75, s75, 0
	s_mov_b32 m0, s30
	ds_read_b128 v[188:191], v152 offset:32768
	ds_read_b128 v[196:199], v152 offset:33792
	ds_read_b128 v[200:203], v152 offset:34816
	ds_read_b128 v[204:207], v152 offset:35840
	ds_read_b128 v[208:211], v152 offset:36864
	ds_read_b128 v[212:215], v152 offset:37888
	ds_read_b128 v[216:219], v152 offset:38912
	ds_read_b128 v[220:223], v152 offset:39936
	global_load_lds_dwordx4 v130, s[74:75]
	s_mov_b32 m0, s31
	s_nop 0
	global_load_lds_dwordx4 v134, s[74:75]
	s_waitcnt vmcnt(8)
	s_waitcnt lgkmcnt(0)
	s_barrier
	s_waitcnt lgkmcnt(0)
	v_mfma_f32_16x16x32_bf16 v[126:129], v[154:157], v[188:191], v[126:129]
	v_mfma_f32_16x16x32_bf16 v[126:129], v[158:161], v[196:199], v[126:129]
	v_mfma_f32_16x16x32_bf16 v[110:113], v[154:157], v[200:203], v[110:113]
	v_mfma_f32_16x16x32_bf16 v[110:113], v[158:161], v[204:207], v[110:113]
	v_mfma_f32_16x16x32_bf16 v[94:97], v[154:157], v[208:211], v[94:97]
	v_mfma_f32_16x16x32_bf16 v[94:97], v[158:161], v[212:215], v[94:97]
	v_mfma_f32_16x16x32_bf16 v[78:81], v[154:157], v[216:219], v[78:81]
	v_mfma_f32_16x16x32_bf16 v[78:81], v[158:161], v[220:223], v[78:81]
	v_mfma_f32_16x16x32_bf16 v[70:73], v[162:165], v[216:219], v[70:73]
	v_mfma_f32_16x16x32_bf16 v[70:73], v[166:169], v[220:223], v[70:73]
	v_mfma_f32_16x16x32_bf16 v[86:89], v[162:165], v[208:211], v[86:89]
	v_mfma_f32_16x16x32_bf16 v[86:89], v[166:169], v[212:215], v[86:89]
	v_mfma_f32_16x16x32_bf16 v[102:105], v[162:165], v[200:203], v[102:105]
	v_mfma_f32_16x16x32_bf16 v[102:105], v[166:169], v[204:207], v[102:105]
	v_mfma_f32_16x16x32_bf16 v[118:121], v[162:165], v[188:191], v[118:121]
	v_mfma_f32_16x16x32_bf16 v[118:121], v[166:169], v[196:199], v[118:121]
	v_mfma_f32_16x16x32_bf16 v[122:125], v[170:173], v[188:191], v[122:125]
	v_mfma_f32_16x16x32_bf16 v[122:125], v[174:177], v[196:199], v[122:125]
	v_mfma_f32_16x16x32_bf16 v[106:109], v[170:173], v[200:203], v[106:109]
	v_mfma_f32_16x16x32_bf16 v[106:109], v[174:177], v[204:207], v[106:109]
	v_mfma_f32_16x16x32_bf16 v[90:93], v[170:173], v[208:211], v[90:93]
	v_mfma_f32_16x16x32_bf16 v[90:93], v[174:177], v[212:215], v[90:93]
	v_mfma_f32_16x16x32_bf16 v[74:77], v[170:173], v[216:219], v[74:77]
	v_mfma_f32_16x16x32_bf16 v[74:77], v[174:177], v[220:223], v[74:77]
	v_mfma_f32_16x16x32_bf16 v[66:69], v[180:183], v[216:219], v[66:69]
	v_mfma_f32_16x16x32_bf16 v[66:69], v[184:187], v[220:223], v[66:69]
	v_mfma_f32_16x16x32_bf16 v[82:85], v[180:183], v[208:211], v[82:85]
	v_mfma_f32_16x16x32_bf16 v[82:85], v[184:187], v[212:215], v[82:85]
	v_mfma_f32_16x16x32_bf16 v[98:101], v[180:183], v[200:203], v[98:101]
	v_mfma_f32_16x16x32_bf16 v[98:101], v[184:187], v[204:207], v[98:101]
	v_mfma_f32_16x16x32_bf16 v[114:117], v[180:183], v[188:191], v[114:117]
	v_mfma_f32_16x16x32_bf16 v[114:117], v[184:187], v[196:199], v[114:117]
	s_barrier
	s_add_u32 s74, s72, 0x8000
	s_addc_u32 s75, s73, 0
	s_add_i32 s77, s77, s3
	s_mov_b32 m0, s77
	ds_read_b128 v[188:191], v152 offset:49152
	ds_read_b128 v[196:199], v152 offset:50176
	ds_read_b128 v[200:203], v152 offset:51200
	ds_read_b128 v[204:207], v152 offset:52224
	ds_read_b128 v[208:211], v152 offset:53248
	ds_read_b128 v[212:215], v152 offset:54272
	ds_read_b128 v[216:219], v152 offset:55296
	ds_read_b128 v[220:223], v152 offset:56320
	global_load_lds_dwordx4 v132, s[74:75]
	s_add_i32 m0, s77, 0x2000
	s_add_u32 s72, s72, 0xc000
	v_lshl_add_u64 v[224:225], s[74:75], 0, v[136:137]
	s_addc_u32 s73, s73, 0
	s_add_i32 s74, s78, s3
	global_load_lds_dwordx4 v[224:225], off
	s_mov_b32 m0, s74
	s_nop 0
	global_load_lds_dwordx4 v132, s[72:73]
	s_add_i32 m0, s74, 0x2000
	s_nop 0
	global_load_lds_dwordx4 v136, s[72:73]
	s_waitcnt vmcnt(6)
	s_waitcnt lgkmcnt(0)
	s_barrier
	s_waitcnt lgkmcnt(0)
	v_mfma_f32_16x16x32_bf16 v[62:65], v[154:157], v[188:191], v[62:65]
	v_mfma_f32_16x16x32_bf16 v[62:65], v[158:161], v[196:199], v[62:65]
	v_mfma_f32_16x16x32_bf16 v[46:49], v[154:157], v[200:203], v[46:49]
	v_mfma_f32_16x16x32_bf16 v[46:49], v[158:161], v[204:207], v[46:49]
	v_mfma_f32_16x16x32_bf16 v[30:33], v[154:157], v[208:211], v[30:33]
	v_mfma_f32_16x16x32_bf16 v[30:33], v[158:161], v[212:215], v[30:33]
	v_mfma_f32_16x16x32_bf16 v[14:17], v[154:157], v[216:219], v[14:17]
	v_mfma_f32_16x16x32_bf16 v[14:17], v[158:161], v[220:223], v[14:17]
	v_mfma_f32_16x16x32_bf16 v[6:9], v[162:165], v[216:219], v[6:9]
	v_mfma_f32_16x16x32_bf16 v[6:9], v[166:169], v[220:223], v[6:9]
	v_mfma_f32_16x16x32_bf16 v[22:25], v[162:165], v[208:211], v[22:25]
	v_mfma_f32_16x16x32_bf16 v[22:25], v[166:169], v[212:215], v[22:25]
	v_mfma_f32_16x16x32_bf16 v[38:41], v[162:165], v[200:203], v[38:41]
	v_mfma_f32_16x16x32_bf16 v[38:41], v[166:169], v[204:207], v[38:41]
	v_mfma_f32_16x16x32_bf16 v[54:57], v[162:165], v[188:191], v[54:57]
	v_mfma_f32_16x16x32_bf16 v[54:57], v[166:169], v[196:199], v[54:57]
	v_mfma_f32_16x16x32_bf16 v[58:61], v[170:173], v[188:191], v[58:61]
	v_mfma_f32_16x16x32_bf16 v[58:61], v[174:177], v[196:199], v[58:61]
	v_mfma_f32_16x16x32_bf16 v[42:45], v[170:173], v[200:203], v[42:45]
	v_mfma_f32_16x16x32_bf16 v[42:45], v[174:177], v[204:207], v[42:45]
	v_mfma_f32_16x16x32_bf16 v[26:29], v[170:173], v[208:211], v[26:29]
	v_mfma_f32_16x16x32_bf16 v[26:29], v[174:177], v[212:215], v[26:29]
	v_mfma_f32_16x16x32_bf16 v[10:13], v[170:173], v[216:219], v[10:13]
	v_mfma_f32_16x16x32_bf16 v[10:13], v[174:177], v[220:223], v[10:13]
	v_mfma_f32_16x16x32_bf16 v[2:5], v[180:183], v[216:219], v[2:5]
	v_mfma_f32_16x16x32_bf16 v[2:5], v[184:187], v[220:223], v[2:5]
	v_mfma_f32_16x16x32_bf16 v[18:21], v[180:183], v[208:211], v[18:21]
	v_mfma_f32_16x16x32_bf16 v[18:21], v[184:187], v[212:215], v[18:21]
	v_mfma_f32_16x16x32_bf16 v[34:37], v[180:183], v[200:203], v[34:37]
	v_mfma_f32_16x16x32_bf16 v[34:37], v[184:187], v[204:207], v[34:37]
	v_mfma_f32_16x16x32_bf16 v[50:53], v[180:183], v[188:191], v[50:53]
	v_mfma_f32_16x16x32_bf16 v[50:53], v[184:187], v[196:199], v[50:53]
	s_barrier
	s_add_i32 s76, s76, 2
	s_add_u32 s48, s48, 0x10000
	s_addc_u32 s49, s49, 0
	s_add_u32 s68, s68, 0x10000
	s_addc_u32 s69, s69, 0
	s_cmp_gt_u32 s76, 61
	s_cbranch_scc0 .LBB0_115
	s_and_b64 vcc, exec, s[14:15]
	s_cbranch_vccz .LBB0_118
	s_barrier

; #define PG8_STAGE(bufoff, gbase, voff) do { _Pragma("unroll") for (int _i = 0; _i < 2; ++_i) \
;         __builtin_amdgcn_global_load_lds((const unsigned*)((const char*)(gbase) + (voff)[_i]), (PG8_LAS unsigned*)(lds + (bufoff) + ldsw + _i * 8192), 16, 0, 0); } while (0)
; #define PG8_LDA(dst, b, h) do { _Pragma("unroll") for (int m = 0; m < 4; ++m) _Pragma("unroll") for (int k = 0; k < 2; ++k) dst[m][k] = *(const PG8_LAS bf16x8*)(lds + PG8_SA(b, h) + aoff + m * 2048 + k * 1024); } while (0)
; #define PG8_LDB(dst, b, h) do { _Pragma("unroll") for (int n = 0; n < 2; ++n) _Pragma("unroll") for (int k = 0; k < 2; ++k) dst[n][k] = *(const PG8_LAS bf16x8*)(lds + PG8_SB(b, h) + boff + n * 2048 + k * 1024); } while (0)
; #define PG8_WAIT_V(n) asm volatile("s_waitcnt vmcnt(" #n ")" ::: "memory")
; #define PG8_WAIT_L(n) asm volatile("s_waitcnt lgkmcnt(" #n ")" ::: "memory")
; #define PG8_BAR __builtin_amdgcn_s_barrier()
; #define PG8_SCHED __builtin_amdgcn_sched_barrier(0)
; template <class Epi, class Sched, bool ALIGN_EPI = false, bool SP2 = false>
; __device__ __forceinline__ void gemm_phase(PG8_LAS unsigned char* lds, const Gemm g, const Sched& S, const Epi& E) {
;     ...
;             const char* a1 = cA + (size_t)(t + 1) * kstep;
;             const char* a2 = last ? nA : cA + (size_t)(t + 2) * kstep; const char* b2 = last ? nB : cB + (size_t)(t + 2) * kstep;
;             const char* a3 = a2 + kstep; const char* b3 = b2 + kstep;
;             if (last && has_next) S.a_ready(nxt);
;             if constexpr (SP2) {
;             PG8_LDB(B0, 0, 0); PG8_LDB(B1, 0, 1); PG8_SCHED; PG8_LDA(At, 0, 0); PG8_STAGE(PG8_SA(1, 1), a1 + hstep, voffA);
;             PG8_WAIT_V(8); PG8_WAIT_L(0); PG8_BAR; PG8_MMA(0, 0, At, B0); PG8_MMA(0, 1, At, B1); PG8_BAR; PG8_SCHED;
;             PG8_LDA(At, 0, 1); PG8_STAGE(PG8_SB(0, 0), b2, voffB); PG8_STAGE(PG8_SB(0, 1), b2 + hstep, voffB); PG8_STAGE(PG8_SA(0, 0), a2, voffA);
;             PG8_WAIT_V(8); PG8_WAIT_L(0); PG8_BAR; PG8_MMA(1, 0, At, B0); PG8_MMA(1, 1, At, B1); PG8_BAR; PG8_SCHED;
;             PG8_LDB(B0, 1, 0); PG8_LDB(B1, 1, 1); PG8_SCHED; PG8_LDA(At, 1, 0); PG8_STAGE(PG8_SA(0, 1), a2 + hstep, voffA);
;             PG8_WAIT_V(8); PG8_WAIT_L(0); PG8_BAR; PG8_MMA(0, 0, At, B0); PG8_MMA(0, 1, At, B1); PG8_BAR; PG8_SCHED;
.LBB0_200:
	ds_read_b128 v[148:151], v154
	ds_read_b128 v[158:161], v154 offset:1024
	ds_read_b128 v[162:165], v154 offset:2048
	ds_read_b128 v[166:169], v154 offset:3072
	ds_read_b128 v[170:173], v155
	ds_read_b128 v[174:177], v155 offset:1024
	ds_read_b128 v[180:183], v155 offset:2048
	ds_read_b128 v[184:187], v155 offset:3072
	s_add_u32 s46, s44, 0x4000
	s_addc_u32 s47, s45, 0
	s_cmpk_eq_i32 s76, 0xa8
	s_cselect_b32 s50, s6, s46
	s_cselect_b32 s51, s7, s47
	s_cselect_b32 s48, s24, s74
	s_cselect_b32 s49, s25, s75
	s_add_u32 s46, s50, 0x8000
	s_addc_u32 s47, s51, 0
	s_sub_u32 s46, s44, 0x4000
	s_subb_u32 s47, s45, 0
	s_mov_b32 m0, s57
	s_nop 0
	global_load_lds_dwordx4 v130, s[46:47]
	s_mov_b32 m0, s58
	s_nop 0
	global_load_lds_dwordx4 v134, s[46:47]
	s_add_i32 m0, s26, 0xc000
	ds_read_b128 v[188:191], v156
	ds_read_b128 v[196:199], v156 offset:1024
	ds_read_b128 v[200:203], v156 offset:2048
	ds_read_b128 v[204:207], v156 offset:3072
	ds_read_b128 v[208:211], v156 offset:4096
	ds_read_b128 v[212:215], v156 offset:5120
	ds_read_b128 v[216:219], v156 offset:6144
	ds_read_b128 v[220:223], v156 offset:7168
	global_load_lds_dwordx4 v140, s[44:45]
	s_add_i32 m0, s26, 0xe000
	s_nop 0
	global_load_lds_dwordx4 v142, s[44:45]
	s_waitcnt vmcnt(8)
	s_waitcnt lgkmcnt(0)
	s_barrier
	s_waitcnt lgkmcnt(0)
	v_mfma_f32_16x16x32_bf16 v[126:129], v[148:151], v[188:191], v[126:129]
	v_mfma_f32_16x16x32_bf16 v[126:129], v[158:161], v[196:199], v[126:129]
	v_mfma_f32_16x16x32_bf16 v[110:113], v[148:151], v[200:203], v[110:113]
	v_mfma_f32_16x16x32_bf16 v[110:113], v[158:161], v[204:207], v[110:113]
	v_mfma_f32_16x16x32_bf16 v[94:97], v[148:151], v[208:211], v[94:97]
	v_mfma_f32_16x16x32_bf16 v[94:97], v[158:161], v[212:215], v[94:97]
	v_mfma_f32_16x16x32_bf16 v[78:81], v[148:151], v[216:219], v[78:81]
	v_mfma_f32_16x16x32_bf16 v[78:81], v[158:161], v[220:223], v[78:81]
	v_mfma_f32_16x16x32_bf16 v[74:77], v[162:165], v[216:219], v[74:77]
	v_mfma_f32_16x16x32_bf16 v[74:77], v[166:169], v[220:223], v[74:77]
	v_mfma_f32_16x16x32_bf16 v[90:93], v[162:165], v[208:211], v[90:93]
	v_mfma_f32_16x16x32_bf16 v[90:93], v[166:169], v[212:215], v[90:93]
	v_mfma_f32_16x16x32_bf16 v[106:109], v[162:165], v[200:203], v[106:109]
	v_mfma_f32_16x16x32_bf16 v[106:109], v[166:169], v[204:207], v[106:109]
	v_mfma_f32_16x16x32_bf16 v[122:125], v[162:165], v[188:191], v[122:125]
	v_mfma_f32_16x16x32_bf16 v[122:125], v[166:169], v[196:199], v[122:125]
	v_mfma_f32_16x16x32_bf16 v[118:121], v[170:173], v[188:191], v[118:121]
	v_mfma_f32_16x16x32_bf16 v[118:121], v[174:177], v[196:199], v[118:121]
	v_mfma_f32_16x16x32_bf16 v[102:105], v[170:173], v[200:203], v[102:105]
	v_mfma_f32_16x16x32_bf16 v[102:105], v[174:177], v[204:207], v[102:105]
	v_mfma_f32_16x16x32_bf16 v[86:89], v[170:173], v[208:211], v[86:89]
	v_mfma_f32_16x16x32_bf16 v[86:89], v[174:177], v[212:215], v[86:89]
	v_mfma_f32_16x16x32_bf16 v[70:73], v[170:173], v[216:219], v[70:73]
	v_mfma_f32_16x16x32_bf16 v[70:73], v[174:177], v[220:223], v[70:73]
	v_mfma_f32_16x16x32_bf16 v[66:69], v[180:183], v[216:219], v[66:69]
	v_mfma_f32_16x16x32_bf16 v[66:69], v[184:187], v[220:223], v[66:69]
	v_mfma_f32_16x16x32_bf16 v[82:85], v[180:183], v[208:211], v[82:85]
	v_mfma_f32_16x16x32_bf16 v[82:85], v[184:187], v[212:215], v[82:85]
	v_mfma_f32_16x16x32_bf16 v[98:101], v[180:183], v[200:203], v[98:101]
	v_mfma_f32_16x16x32_bf16 v[98:101], v[184:187], v[204:207], v[98:101]
	v_mfma_f32_16x16x32_bf16 v[114:117], v[180:183], v[188:191], v[114:117]
	v_mfma_f32_16x16x32_bf16 v[114:117], v[184:187], v[196:199], v[114:117]
	s_barrier
	s_add_i32 s77, s59, s3
	s_mov_b32 m0, s77
	ds_read_b128 v[188:191], v156 offset:16384
	ds_read_b128 v[196:199], v156 offset:17408
	ds_read_b128 v[200:203], v156 offset:18432
	ds_read_b128 v[204:207], v156 offset:19456
	ds_read_b128 v[208:211], v156 offset:20480
	ds_read_b128 v[212:215], v156 offset:21504
	ds_read_b128 v[216:219], v156 offset:22528
	ds_read_b128 v[220:223], v156 offset:23552
	global_load_lds_dwordx4 v132, s[48:49]
	s_add_i32 m0, s77, 0x2000
	s_add_u32 s78, s48, 0x4000
	s_addc_u32 s79, s49, 0
	s_add_i32 s77, s61, s3
	global_load_lds_dwordx4 v136, s[48:49]
	s_mov_b32 m0, s77
	s_nop 0
	global_load_lds_dwordx4 v132, s[78:79]
	s_add_i32 m0, s77, 0x2000
	s_nop 0
	global_load_lds_dwordx4 v136, s[78:79]
	s_waitcnt vmcnt(6)
	s_waitcnt lgkmcnt(0)
	s_barrier
	s_waitcnt lgkmcnt(0)
	v_mfma_f32_16x16x32_bf16 v[62:65], v[148:151], v[188:191], v[62:65]
	v_mfma_f32_16x16x32_bf16 v[62:65], v[158:161], v[196:199], v[62:65]
	v_mfma_f32_16x16x32_bf16 v[46:49], v[148:151], v[200:203], v[46:49]
	v_mfma_f32_16x16x32_bf16 v[46:49], v[158:161], v[204:207], v[46:49]
	v_mfma_f32_16x16x32_bf16 v[30:33], v[148:151], v[208:211], v[30:33]
	v_mfma_f32_16x16x32_bf16 v[30:33], v[158:161], v[212:215], v[30:33]
	v_mfma_f32_16x16x32_bf16 v[14:17], v[148:151], v[216:219], v[14:17]
	v_mfma_f32_16x16x32_bf16 v[14:17], v[158:161], v[220:223], v[14:17]
	v_mfma_f32_16x16x32_bf16 v[10:13], v[162:165], v[216:219], v[10:13]
	v_mfma_f32_16x16x32_bf16 v[10:13], v[166:169], v[220:223], v[10:13]
	v_mfma_f32_16x16x32_bf16 v[26:29], v[162:165], v[208:211], v[26:29]
	v_mfma_f32_16x16x32_bf16 v[26:29], v[166:169], v[212:215], v[26:29]
	v_mfma_f32_16x16x32_bf16 v[42:45], v[162:165], v[200:203], v[42:45]
	v_mfma_f32_16x16x32_bf16 v[42:45], v[166:169], v[204:207], v[42:45]
	v_mfma_f32_16x16x32_bf16 v[58:61], v[162:165], v[188:191], v[58:61]
	v_mfma_f32_16x16x32_bf16 v[58:61], v[166:169], v[196:199], v[58:61]
	v_mfma_f32_16x16x32_bf16 v[54:57], v[170:173], v[188:191], v[54:57]
	v_mfma_f32_16x16x32_bf16 v[54:57], v[174:177], v[196:199], v[54:57]
	v_mfma_f32_16x16x32_bf16 v[38:41], v[170:173], v[200:203], v[38:41]
	v_mfma_f32_16x16x32_bf16 v[38:41], v[174:177], v[204:207], v[38:41]
	v_mfma_f32_16x16x32_bf16 v[22:25], v[170:173], v[208:211], v[22:25]
	v_mfma_f32_16x16x32_bf16 v[22:25], v[174:177], v[212:215], v[22:25]
	v_mfma_f32_16x16x32_bf16 v[6:9], v[170:173], v[216:219], v[6:9]
	v_mfma_f32_16x16x32_bf16 v[6:9], v[174:177], v[220:223], v[6:9]
	v_mfma_f32_16x16x32_bf16 v[2:5], v[180:183], v[216:219], v[2:5]
	v_mfma_f32_16x16x32_bf16 v[2:5], v[184:187], v[220:223], v[2:5]
	v_mfma_f32_16x16x32_bf16 v[18:21], v[180:183], v[208:211], v[18:21]
	v_mfma_f32_16x16x32_bf16 v[18:21], v[184:187], v[212:215], v[18:21]
	v_mfma_f32_16x16x32_bf16 v[34:37], v[180:183], v[200:203], v[34:37]
	v_mfma_f32_16x16x32_bf16 v[34:37], v[184:187], v[204:207], v[34:37]
	v_mfma_f32_16x16x32_bf16 v[50:53], v[180:183], v[188:191], v[50:53]
	v_mfma_f32_16x16x32_bf16 v[50:53], v[184:187], v[196:199], v[50:53]
	s_barrier
; #define PG8_STAGE(bufoff, gbase, voff) do { _Pragma("unroll") for (int _i = 0; _i < 2; ++_i) \
;         __builtin_amdgcn_global_load_lds((const unsigned*)((const char*)(gbase) + (voff)[_i]), (PG8_LAS unsigned*)(lds + (bufoff) + ldsw + _i * 8192), 16, 0, 0); } while (0)
; #define PG8_LDA(dst, b, h) do { _Pragma("unroll") for (int m = 0; m < 4; ++m) _Pragma("unroll") for (int k = 0; k < 2; ++k) dst[m][k] = *(const PG8_LAS bf16x8*)(lds + PG8_SA(b, h) + aoff + m * 2048 + k * 1024); } while (0)
; #define PG8_LDB(dst, b, h) do { _Pragma("unroll") for (int n = 0; n < 2; ++n) _Pragma("unroll") for (int k = 0; k < 2; ++k) dst[n][k] = *(const PG8_LAS bf16x8*)(lds + PG8_SB(b, h) + boff + n * 2048 + k * 1024); } while (0)
; #define PG8_MMA(ai, bj, At, Bt) do { __builtin_amdgcn_s_setprio(1); _Pragma("unroll") for (int m = 0; m < 4; ++m) _Pragma("unroll") for (int n = 0; n < 2; ++n) _Pragma("unroll") for (int k = 0; k < 2; ++k) \
;         acc[ai][bj][m][n] = __builtin_amdgcn_mfma_f32_16x16x32_bf16(Bt[n][k], At[m][k], acc[ai][bj][m][n], 0, 0, 0); __builtin_amdgcn_s_setprio(0); } while (0)
; #define PG8_WAIT_V(n) asm volatile("s_waitcnt vmcnt(" #n ")" ::: "memory")
; #define PG8_WAIT_L(n) asm volatile("s_waitcnt lgkmcnt(" #n ")" ::: "memory")
; #define PG8_BAR __builtin_amdgcn_s_barrier()
; #define PG8_SCHED __builtin_amdgcn_sched_barrier(0)
; template <class Epi, class Sched, bool ALIGN_EPI = false, bool SP2 = false>
; __device__ __forceinline__ void gemm_phase(PG8_LAS unsigned char* lds, const Gemm g, const Sched& S, const Epi& E) {
;     ...
;             PG8_LDB(B0, 1, 0); PG8_LDB(B1, 1, 1); PG8_SCHED; PG8_LDA(At, 1, 0); PG8_STAGE(PG8_SA(0, 1), a2 + hstep, voffA);
;             PG8_WAIT_V(8); PG8_WAIT_L(0); PG8_BAR; PG8_MMA(0, 0, At, B0); PG8_MMA(0, 1, At, B1); PG8_BAR; PG8_SCHED;
;             PG8_LDA(At, 1, 1); PG8_STAGE(PG8_SB(1, 0), b3, voffB); PG8_STAGE(PG8_SB(1, 1), b3 + hstep, voffB); PG8_STAGE(PG8_SA(1, 0), a3, voffA);
;             PG8_WAIT_V(8); PG8_WAIT_L(0); PG8_BAR; PG8_MMA(1, 0, At, B0); PG8_MMA(1, 1, At, B1); PG8_BAR; PG8_SCHED;
;     ...
;         if constexpr (ALIGN_EPI) { if (wr == 0) PG8_BAR; }
	s_add_i32 s77, 0, 0x18000
	v_add_u32_e32 v138, s77, v153
	s_add_i32 s78, 0, 0x1c000
	ds_read_b128 v[148:151], v138
	ds_read_b128 v[158:161], v138 offset:1024
	ds_read_b128 v[162:165], v138 offset:2048
	ds_read_b128 v[166:169], v138 offset:3072
	v_add_u32_e32 v138, s78, v153
	ds_read_b128 v[170:173], v138
	ds_read_b128 v[174:177], v138 offset:1024
	ds_read_b128 v[180:183], v138 offset:2048
	ds_read_b128 v[184:187], v138 offset:3072
	s_mov_b32 m0, s26
	s_nop 0
	global_load_lds_dwordx4 v130, s[50:51]
	s_mov_b32 m0, s27
	s_nop 0
	global_load_lds_dwordx4 v134, s[50:51]
	s_add_u32 s50, s50, 0x4000
	s_addc_u32 s51, s51, 0
	s_mov_b32 m0, s28
	ds_read_b128 v[188:191], v156 offset:32768
	ds_read_b128 v[196:199], v156 offset:33792
	ds_read_b128 v[200:203], v156 offset:34816
	ds_read_b128 v[204:207], v156 offset:35840
	ds_read_b128 v[208:211], v156 offset:36864
	ds_read_b128 v[212:215], v156 offset:37888
	ds_read_b128 v[216:219], v156 offset:38912
	ds_read_b128 v[220:223], v156 offset:39936
	global_load_lds_dwordx4 v130, s[50:51]
	s_mov_b32 m0, s29
	s_nop 0
	global_load_lds_dwordx4 v134, s[50:51]
	s_waitcnt vmcnt(8)
	s_waitcnt lgkmcnt(0)
	s_barrier
	s_waitcnt lgkmcnt(0)
	v_mfma_f32_16x16x32_bf16 v[126:129], v[148:151], v[188:191], v[126:129]
	v_mfma_f32_16x16x32_bf16 v[126:129], v[158:161], v[196:199], v[126:129]
	v_mfma_f32_16x16x32_bf16 v[110:113], v[148:151], v[200:203], v[110:113]
	v_mfma_f32_16x16x32_bf16 v[110:113], v[158:161], v[204:207], v[110:113]
	v_mfma_f32_16x16x32_bf16 v[94:97], v[148:151], v[208:211], v[94:97]
	v_mfma_f32_16x16x32_bf16 v[94:97], v[158:161], v[212:215], v[94:97]
	v_mfma_f32_16x16x32_bf16 v[78:81], v[148:151], v[216:219], v[78:81]
	v_mfma_f32_16x16x32_bf16 v[78:81], v[158:161], v[220:223], v[78:81]
	v_mfma_f32_16x16x32_bf16 v[74:77], v[162:165], v[216:219], v[74:77]
	v_mfma_f32_16x16x32_bf16 v[74:77], v[166:169], v[220:223], v[74:77]
	v_mfma_f32_16x16x32_bf16 v[90:93], v[162:165], v[208:211], v[90:93]
	v_mfma_f32_16x16x32_bf16 v[90:93], v[166:169], v[212:215], v[90:93]
	v_mfma_f32_16x16x32_bf16 v[106:109], v[162:165], v[200:203], v[106:109]
	v_mfma_f32_16x16x32_bf16 v[106:109], v[166:169], v[204:207], v[106:109]
	v_mfma_f32_16x16x32_bf16 v[122:125], v[162:165], v[188:191], v[122:125]
	v_mfma_f32_16x16x32_bf16 v[122:125], v[166:169], v[196:199], v[122:125]
	v_mfma_f32_16x16x32_bf16 v[118:121], v[170:173], v[188:191], v[118:121]
	v_mfma_f32_16x16x32_bf16 v[118:121], v[174:177], v[196:199], v[118:121]
	v_mfma_f32_16x16x32_bf16 v[102:105], v[170:173], v[200:203], v[102:105]
	v_mfma_f32_16x16x32_bf16 v[102:105], v[174:177], v[204:207], v[102:105]
	v_mfma_f32_16x16x32_bf16 v[86:89], v[170:173], v[208:211], v[86:89]
	v_mfma_f32_16x16x32_bf16 v[86:89], v[174:177], v[212:215], v[86:89]
	v_mfma_f32_16x16x32_bf16 v[70:73], v[170:173], v[216:219], v[70:73]
	v_mfma_f32_16x16x32_bf16 v[70:73], v[174:177], v[220:223], v[70:73]
	v_mfma_f32_16x16x32_bf16 v[66:69], v[180:183], v[216:219], v[66:69]
	v_mfma_f32_16x16x32_bf16 v[66:69], v[184:187], v[220:223], v[66:69]
	v_mfma_f32_16x16x32_bf16 v[82:85], v[180:183], v[208:211], v[82:85]
	v_mfma_f32_16x16x32_bf16 v[82:85], v[184:187], v[212:215], v[82:85]
	v_mfma_f32_16x16x32_bf16 v[98:101], v[180:183], v[200:203], v[98:101]
	v_mfma_f32_16x16x32_bf16 v[98:101], v[184:187], v[204:207], v[98:101]
	v_mfma_f32_16x16x32_bf16 v[114:117], v[180:183], v[188:191], v[114:117]
	v_mfma_f32_16x16x32_bf16 v[114:117], v[184:187], v[196:199], v[114:117]
	s_barrier
	s_add_u32 s50, s48, 0x8000
	s_addc_u32 s51, s49, 0
	s_add_i32 s77, s77, s3
	s_mov_b32 m0, s77
	ds_read_b128 v[188:191], v156 offset:49152
	ds_read_b128 v[196:199], v156 offset:50176
	ds_read_b128 v[200:203], v156 offset:51200
	ds_read_b128 v[204:207], v156 offset:52224
	ds_read_b128 v[208:211], v156 offset:53248
	ds_read_b128 v[212:215], v156 offset:54272
	ds_read_b128 v[216:219], v156 offset:55296
	ds_read_b128 v[220:223], v156 offset:56320
	global_load_lds_dwordx4 v132, s[50:51]
	s_add_i32 m0, s77, 0x2000
	s_add_u32 s48, s48, 0xc000
	v_lshl_add_u64 v[224:225], s[50:51], 0, v[136:137]
	s_addc_u32 s49, s49, 0
	s_add_i32 s50, s78, s3
	global_load_lds_dwordx4 v[224:225], off
	s_mov_b32 m0, s50
	s_nop 0
	global_load_lds_dwordx4 v132, s[48:49]
	s_add_i32 m0, s50, 0x2000
	s_nop 0
	global_load_lds_dwordx4 v136, s[48:49]
	s_waitcnt vmcnt(6)
	s_waitcnt lgkmcnt(0)
	s_barrier
	s_waitcnt lgkmcnt(0)
	v_mfma_f32_16x16x32_bf16 v[62:65], v[148:151], v[188:191], v[62:65]
	v_mfma_f32_16x16x32_bf16 v[62:65], v[158:161], v[196:199], v[62:65]
	v_mfma_f32_16x16x32_bf16 v[46:49], v[148:151], v[200:203], v[46:49]
	v_mfma_f32_16x16x32_bf16 v[46:49], v[158:161], v[204:207], v[46:49]
	v_mfma_f32_16x16x32_bf16 v[30:33], v[148:151], v[208:211], v[30:33]
	v_mfma_f32_16x16x32_bf16 v[30:33], v[158:161], v[212:215], v[30:33]
	v_mfma_f32_16x16x32_bf16 v[14:17], v[148:151], v[216:219], v[14:17]
	v_mfma_f32_16x16x32_bf16 v[14:17], v[158:161], v[220:223], v[14:17]
	v_mfma_f32_16x16x32_bf16 v[10:13], v[162:165], v[216:219], v[10:13]
	v_mfma_f32_16x16x32_bf16 v[10:13], v[166:169], v[220:223], v[10:13]
	v_mfma_f32_16x16x32_bf16 v[26:29], v[162:165], v[208:211], v[26:29]
	v_mfma_f32_16x16x32_bf16 v[26:29], v[166:169], v[212:215], v[26:29]
	v_mfma_f32_16x16x32_bf16 v[42:45], v[162:165], v[200:203], v[42:45]
	v_mfma_f32_16x16x32_bf16 v[42:45], v[166:169], v[204:207], v[42:45]
	v_mfma_f32_16x16x32_bf16 v[58:61], v[162:165], v[188:191], v[58:61]
	v_mfma_f32_16x16x32_bf16 v[58:61], v[166:169], v[196:199], v[58:61]
	v_mfma_f32_16x16x32_bf16 v[54:57], v[170:173], v[188:191], v[54:57]
	v_mfma_f32_16x16x32_bf16 v[54:57], v[174:177], v[196:199], v[54:57]
	v_mfma_f32_16x16x32_bf16 v[38:41], v[170:173], v[200:203], v[38:41]
	v_mfma_f32_16x16x32_bf16 v[38:41], v[174:177], v[204:207], v[38:41]
	v_mfma_f32_16x16x32_bf16 v[22:25], v[170:173], v[208:211], v[22:25]
	v_mfma_f32_16x16x32_bf16 v[22:25], v[174:177], v[212:215], v[22:25]
	v_mfma_f32_16x16x32_bf16 v[6:9], v[170:173], v[216:219], v[6:9]
	v_mfma_f32_16x16x32_bf16 v[6:9], v[174:177], v[220:223], v[6:9]
	v_mfma_f32_16x16x32_bf16 v[2:5], v[180:183], v[216:219], v[2:5]
	v_mfma_f32_16x16x32_bf16 v[2:5], v[184:187], v[220:223], v[2:5]
	v_mfma_f32_16x16x32_bf16 v[18:21], v[180:183], v[208:211], v[18:21]
	v_mfma_f32_16x16x32_bf16 v[18:21], v[184:187], v[212:215], v[18:21]
	v_mfma_f32_16x16x32_bf16 v[34:37], v[180:183], v[200:203], v[34:37]
	v_mfma_f32_16x16x32_bf16 v[34:37], v[184:187], v[204:207], v[34:37]
	v_mfma_f32_16x16x32_bf16 v[50:53], v[180:183], v[188:191], v[50:53]
	v_mfma_f32_16x16x32_bf16 v[50:53], v[184:187], v[196:199], v[50:53]
	s_barrier
	s_add_i32 s76, s76, 2
	s_add_u32 s44, s44, 0x10000
	s_addc_u32 s45, s45, 0
	s_add_u32 s74, s74, 0x10000
	s_addc_u32 s75, s75, 0
	s_cmpk_gt_u32 s76, 0xa9
	s_cbranch_scc0 .LBB0_200
	s_and_b64 vcc, exec, s[18:19]
	s_cbranch_vccz .LBB0_203
	s_barrier

; #define PG8_STAGE(bufoff, gbase, voff) do { _Pragma("unroll") for (int _i = 0; _i < 2; ++_i) \
;         __builtin_amdgcn_global_load_lds((const unsigned*)((const char*)(gbase) + (voff)[_i]), (PG8_LAS unsigned*)(lds + (bufoff) + ldsw + _i * 8192), 16, 0, 0); } while (0)
; #define PG8_LDA(dst, b, h) do { _Pragma("unroll") for (int m = 0; m < 4; ++m) _Pragma("unroll") for (int k = 0; k < 2; ++k) dst[m][k] = *(const PG8_LAS bf16x8*)(lds + PG8_SA(b, h) + aoff + m * 2048 + k * 1024); } while (0)
; #define PG8_LDB(dst, b, h) do { _Pragma("unroll") for (int n = 0; n < 2; ++n) _Pragma("unroll") for (int k = 0; k < 2; ++k) dst[n][k] = *(const PG8_LAS bf16x8*)(lds + PG8_SB(b, h) + boff + n * 2048 + k * 1024); } while (0)
; #define PG8_WAIT_V(n) asm volatile("s_waitcnt vmcnt(" #n ")" ::: "memory")
; #define PG8_WAIT_L(n) asm volatile("s_waitcnt lgkmcnt(" #n ")" ::: "memory")
; #define PG8_BAR __builtin_amdgcn_s_barrier()
; #define PG8_SCHED __builtin_amdgcn_sched_barrier(0)
; template <class Epi, class Sched, bool ALIGN_EPI = false, bool SP2 = false>
; __device__ __forceinline__ void gemm_phase(PG8_LAS unsigned char* lds, const Gemm g, const Sched& S, const Epi& E) {
;     ...
;             const char* a1 = cA + (size_t)(t + 1) * kstep;
;             const char* a2 = last ? nA : cA + (size_t)(t + 2) * kstep; const char* b2 = last ? nB : cB + (size_t)(t + 2) * kstep;
;             const char* a3 = a2 + kstep; const char* b3 = b2 + kstep;
;             if (last && has_next) S.a_ready(nxt);
;             if constexpr (SP2) {
;             PG8_LDB(B0, 0, 0); PG8_LDB(B1, 0, 1); PG8_SCHED; PG8_LDA(At, 0, 0); PG8_STAGE(PG8_SA(1, 1), a1 + hstep, voffA);
;             PG8_WAIT_V(8); PG8_WAIT_L(0); PG8_BAR; PG8_MMA(0, 0, At, B0); PG8_MMA(0, 1, At, B1); PG8_BAR; PG8_SCHED;
;             PG8_LDA(At, 0, 1); PG8_STAGE(PG8_SB(0, 0), b2, voffB); PG8_STAGE(PG8_SB(0, 1), b2 + hstep, voffB); PG8_STAGE(PG8_SA(0, 0), a2, voffA);
;             PG8_WAIT_V(8); PG8_WAIT_L(0); PG8_BAR; PG8_MMA(1, 0, At, B0); PG8_MMA(1, 1, At, B1); PG8_BAR; PG8_SCHED;
;             PG8_LDB(B0, 1, 0); PG8_LDB(B1, 1, 1); PG8_SCHED; PG8_LDA(At, 1, 0); PG8_STAGE(PG8_SA(0, 1), a2 + hstep, voffA);
;             PG8_WAIT_V(8); PG8_WAIT_L(0); PG8_BAR; PG8_MMA(0, 0, At, B0); PG8_MMA(0, 1, At, B1); PG8_BAR; PG8_SCHED;
.LBB0_290:
	ds_read_b128 v[146:149], v162
	ds_read_b128 v[150:153], v162 offset:1024
	ds_read_b128 v[154:157], v162 offset:2048
	ds_read_b128 v[168:171], v162 offset:3072
	ds_read_b128 v[172:175], v163
	ds_read_b128 v[180:183], v163 offset:1024
	ds_read_b128 v[184:187], v163 offset:2048
	ds_read_b128 v[188:191], v163 offset:3072
	s_add_u32 s59, s72, 0x4000
	s_addc_u32 s62, s73, 0
	s_cmp_eq_u32 s58, 60
	s_cselect_b32 s78, s19, s59
	s_cselect_b32 s79, s5, s62
	s_cselect_b32 s76, s26, s33
	s_cselect_b32 s77, s17, s56
	s_add_u32 s74, s78, 0x8000
	s_addc_u32 s75, s79, 0
	s_sub_u32 s74, s72, 0x4000
	s_subb_u32 s75, s73, 0
	s_mov_b32 m0, s51
	s_nop 0
	global_load_lds_dwordx4 v130, s[74:75]
	s_mov_b32 m0, s57
	s_nop 0
	global_load_lds_dwordx4 v134, s[74:75]
	s_add_i32 m0, s15, 0xc000
	ds_read_b128 v[198:201], v164
	ds_read_b128 v[202:205], v164 offset:1024
	ds_read_b128 v[206:209], v164 offset:2048
	ds_read_b128 v[210:213], v164 offset:3072
	ds_read_b128 v[214:217], v164 offset:4096
	ds_read_b128 v[218:221], v164 offset:5120
	ds_read_b128 v[222:225], v164 offset:6144
	ds_read_b128 v[226:229], v164 offset:7168
	global_load_lds_dwordx4 v138, s[72:73]
	s_add_i32 m0, s15, 0xe000
	s_nop 0
	global_load_lds_dwordx4 v140, s[72:73]
	s_waitcnt vmcnt(8)
	s_waitcnt lgkmcnt(0)
	s_barrier
	s_waitcnt lgkmcnt(0)
	v_mfma_f32_16x16x32_bf16 v[126:129], v[146:149], v[198:201], v[126:129]
	v_mfma_f32_16x16x32_bf16 v[126:129], v[150:153], v[202:205], v[126:129]
	v_mfma_f32_16x16x32_bf16 v[110:113], v[146:149], v[206:209], v[110:113]
	v_mfma_f32_16x16x32_bf16 v[110:113], v[150:153], v[210:213], v[110:113]
	v_mfma_f32_16x16x32_bf16 v[94:97], v[146:149], v[214:217], v[94:97]
	v_mfma_f32_16x16x32_bf16 v[94:97], v[150:153], v[218:221], v[94:97]
	v_mfma_f32_16x16x32_bf16 v[78:81], v[146:149], v[222:225], v[78:81]
	v_mfma_f32_16x16x32_bf16 v[78:81], v[150:153], v[226:229], v[78:81]
	v_mfma_f32_16x16x32_bf16 v[74:77], v[154:157], v[222:225], v[74:77]
	v_mfma_f32_16x16x32_bf16 v[74:77], v[168:171], v[226:229], v[74:77]
	v_mfma_f32_16x16x32_bf16 v[90:93], v[154:157], v[214:217], v[90:93]
	v_mfma_f32_16x16x32_bf16 v[90:93], v[168:171], v[218:221], v[90:93]
	v_mfma_f32_16x16x32_bf16 v[106:109], v[154:157], v[206:209], v[106:109]
	v_mfma_f32_16x16x32_bf16 v[106:109], v[168:171], v[210:213], v[106:109]
	v_mfma_f32_16x16x32_bf16 v[122:125], v[154:157], v[198:201], v[122:125]
	v_mfma_f32_16x16x32_bf16 v[122:125], v[168:171], v[202:205], v[122:125]
	v_mfma_f32_16x16x32_bf16 v[118:121], v[172:175], v[198:201], v[118:121]
	v_mfma_f32_16x16x32_bf16 v[118:121], v[180:183], v[202:205], v[118:121]
	v_mfma_f32_16x16x32_bf16 v[102:105], v[172:175], v[206:209], v[102:105]
	v_mfma_f32_16x16x32_bf16 v[102:105], v[180:183], v[210:213], v[102:105]
	v_mfma_f32_16x16x32_bf16 v[86:89], v[172:175], v[214:217], v[86:89]
	v_mfma_f32_16x16x32_bf16 v[86:89], v[180:183], v[218:221], v[86:89]
	v_mfma_f32_16x16x32_bf16 v[70:73], v[172:175], v[222:225], v[70:73]
	v_mfma_f32_16x16x32_bf16 v[70:73], v[180:183], v[226:229], v[70:73]
	v_mfma_f32_16x16x32_bf16 v[66:69], v[184:187], v[222:225], v[66:69]
	v_mfma_f32_16x16x32_bf16 v[66:69], v[188:191], v[226:229], v[66:69]
	v_mfma_f32_16x16x32_bf16 v[82:85], v[184:187], v[214:217], v[82:85]
	v_mfma_f32_16x16x32_bf16 v[82:85], v[188:191], v[218:221], v[82:85]
	v_mfma_f32_16x16x32_bf16 v[98:101], v[184:187], v[206:209], v[98:101]
	v_mfma_f32_16x16x32_bf16 v[98:101], v[188:191], v[210:213], v[98:101]
	v_mfma_f32_16x16x32_bf16 v[114:117], v[184:187], v[198:201], v[114:117]
	v_mfma_f32_16x16x32_bf16 v[114:117], v[188:191], v[202:205], v[114:117]
	s_barrier
	s_add_i32 s59, s81, s3
	s_mov_b32 m0, s59
	ds_read_b128 v[198:201], v164 offset:16384
	ds_read_b128 v[202:205], v164 offset:17408
	ds_read_b128 v[206:209], v164 offset:18432
	ds_read_b128 v[210:213], v164 offset:19456
	ds_read_b128 v[214:217], v164 offset:20480
	ds_read_b128 v[218:221], v164 offset:21504
	ds_read_b128 v[222:225], v164 offset:22528
	ds_read_b128 v[226:229], v164 offset:23552
	global_load_lds_dwordx4 v132, s[76:77]
	s_add_i32 m0, s59, 0x2000
	s_add_u32 s62, s76, 0x4000
	s_addc_u32 s63, s77, 0
	s_add_i32 s59, s82, s3
	global_load_lds_dwordx4 v136, s[76:77]
	s_mov_b32 m0, s59
	s_nop 0
	global_load_lds_dwordx4 v132, s[62:63]
	s_add_i32 m0, s59, 0x2000
	s_nop 0
	global_load_lds_dwordx4 v136, s[62:63]
	s_waitcnt vmcnt(6)
	s_waitcnt lgkmcnt(0)
	s_barrier
	s_waitcnt lgkmcnt(0)
	v_mfma_f32_16x16x32_bf16 v[62:65], v[146:149], v[198:201], v[62:65]
	v_mfma_f32_16x16x32_bf16 v[62:65], v[150:153], v[202:205], v[62:65]
	v_mfma_f32_16x16x32_bf16 v[46:49], v[146:149], v[206:209], v[46:49]
	v_mfma_f32_16x16x32_bf16 v[46:49], v[150:153], v[210:213], v[46:49]
	v_mfma_f32_16x16x32_bf16 v[30:33], v[146:149], v[214:217], v[30:33]
	v_mfma_f32_16x16x32_bf16 v[30:33], v[150:153], v[218:221], v[30:33]
	v_mfma_f32_16x16x32_bf16 v[14:17], v[146:149], v[222:225], v[14:17]
	v_mfma_f32_16x16x32_bf16 v[14:17], v[150:153], v[226:229], v[14:17]
	v_mfma_f32_16x16x32_bf16 v[10:13], v[154:157], v[222:225], v[10:13]
	v_mfma_f32_16x16x32_bf16 v[10:13], v[168:171], v[226:229], v[10:13]
	v_mfma_f32_16x16x32_bf16 v[26:29], v[154:157], v[214:217], v[26:29]
	v_mfma_f32_16x16x32_bf16 v[26:29], v[168:171], v[218:221], v[26:29]
	v_mfma_f32_16x16x32_bf16 v[42:45], v[154:157], v[206:209], v[42:45]
	v_mfma_f32_16x16x32_bf16 v[42:45], v[168:171], v[210:213], v[42:45]
	v_mfma_f32_16x16x32_bf16 v[58:61], v[154:157], v[198:201], v[58:61]
	v_mfma_f32_16x16x32_bf16 v[58:61], v[168:171], v[202:205], v[58:61]
	v_mfma_f32_16x16x32_bf16 v[54:57], v[172:175], v[198:201], v[54:57]
	v_mfma_f32_16x16x32_bf16 v[54:57], v[180:183], v[202:205], v[54:57]
	v_mfma_f32_16x16x32_bf16 v[38:41], v[172:175], v[206:209], v[38:41]
	v_mfma_f32_16x16x32_bf16 v[38:41], v[180:183], v[210:213], v[38:41]
	v_mfma_f32_16x16x32_bf16 v[22:25], v[172:175], v[214:217], v[22:25]
	v_mfma_f32_16x16x32_bf16 v[22:25], v[180:183], v[218:221], v[22:25]
	v_mfma_f32_16x16x32_bf16 v[6:9], v[172:175], v[222:225], v[6:9]
	v_mfma_f32_16x16x32_bf16 v[6:9], v[180:183], v[226:229], v[6:9]
	v_mfma_f32_16x16x32_bf16 v[2:5], v[184:187], v[222:225], v[2:5]
	v_mfma_f32_16x16x32_bf16 v[2:5], v[188:191], v[226:229], v[2:5]
	v_mfma_f32_16x16x32_bf16 v[18:21], v[184:187], v[214:217], v[18:21]
	v_mfma_f32_16x16x32_bf16 v[18:21], v[188:191], v[218:221], v[18:21]
	v_mfma_f32_16x16x32_bf16 v[34:37], v[184:187], v[206:209], v[34:37]
	v_mfma_f32_16x16x32_bf16 v[34:37], v[188:191], v[210:213], v[34:37]
	v_mfma_f32_16x16x32_bf16 v[50:53], v[184:187], v[198:201], v[50:53]
	v_mfma_f32_16x16x32_bf16 v[50:53], v[188:191], v[202:205], v[50:53]
	s_barrier
; #define PG8_STAGE(bufoff, gbase, voff) do { _Pragma("unroll") for (int _i = 0; _i < 2; ++_i) \
;         __builtin_amdgcn_global_load_lds((const unsigned*)((const char*)(gbase) + (voff)[_i]), (PG8_LAS unsigned*)(lds + (bufoff) + ldsw + _i * 8192), 16, 0, 0); } while (0)
; #define PG8_LDA(dst, b, h) do { _Pragma("unroll") for (int m = 0; m < 4; ++m) _Pragma("unroll") for (int k = 0; k < 2; ++k) dst[m][k] = *(const PG8_LAS bf16x8*)(lds + PG8_SA(b, h) + aoff + m * 2048 + k * 1024); } while (0)
; #define PG8_LDB(dst, b, h) do { _Pragma("unroll") for (int n = 0; n < 2; ++n) _Pragma("unroll") for (int k = 0; k < 2; ++k) dst[n][k] = *(const PG8_LAS bf16x8*)(lds + PG8_SB(b, h) + boff + n * 2048 + k * 1024); } while (0)
; #define PG8_MMA(ai, bj, At, Bt) do { __builtin_amdgcn_s_setprio(1); _Pragma("unroll") for (int m = 0; m < 4; ++m) _Pragma("unroll") for (int n = 0; n < 2; ++n) _Pragma("unroll") for (int k = 0; k < 2; ++k) \
;         acc[ai][bj][m][n] = __builtin_amdgcn_mfma_f32_16x16x32_bf16(Bt[n][k], At[m][k], acc[ai][bj][m][n], 0, 0, 0); __builtin_amdgcn_s_setprio(0); } while (0)
; #define PG8_WAIT_V(n) asm volatile("s_waitcnt vmcnt(" #n ")" ::: "memory")
; #define PG8_WAIT_L(n) asm volatile("s_waitcnt lgkmcnt(" #n ")" ::: "memory")
; #define PG8_BAR __builtin_amdgcn_s_barrier()
; #define PG8_SCHED __builtin_amdgcn_sched_barrier(0)
; template <class Epi, class Sched, bool ALIGN_EPI = false, bool SP2 = false>
; __device__ __forceinline__ void gemm_phase(PG8_LAS unsigned char* lds, const Gemm g, const Sched& S, const Epi& E) {
;     ...
;             PG8_LDB(B0, 1, 0); PG8_LDB(B1, 1, 1); PG8_SCHED; PG8_LDA(At, 1, 0); PG8_STAGE(PG8_SA(0, 1), a2 + hstep, voffA);
;             PG8_WAIT_V(8); PG8_WAIT_L(0); PG8_BAR; PG8_MMA(0, 0, At, B0); PG8_MMA(0, 1, At, B1); PG8_BAR; PG8_SCHED;
;             PG8_LDA(At, 1, 1); PG8_STAGE(PG8_SB(1, 0), b3, voffB); PG8_STAGE(PG8_SB(1, 1), b3 + hstep, voffB); PG8_STAGE(PG8_SA(1, 0), a3, voffA);
;             PG8_WAIT_V(8); PG8_WAIT_L(0); PG8_BAR; PG8_MMA(1, 0, At, B0); PG8_MMA(1, 1, At, B1); PG8_BAR; PG8_SCHED;
;     ...
;         if constexpr (ALIGN_EPI) { if (wr == 0) PG8_BAR; }
	s_add_i32 s59, 0, 0x18000
	v_add_u32_e32 v158, s59, v160
	s_add_i32 s64, 0, 0x1c000
	ds_read_b128 v[146:149], v158
	ds_read_b128 v[150:153], v158 offset:1024
	ds_read_b128 v[154:157], v158 offset:2048
	ds_read_b128 v[168:171], v158 offset:3072
	v_add_u32_e32 v158, s64, v160
	ds_read_b128 v[172:175], v158
	ds_read_b128 v[180:183], v158 offset:1024
	ds_read_b128 v[184:187], v158 offset:2048
	ds_read_b128 v[188:191], v158 offset:3072
	s_mov_b32 m0, s15
	s_nop 0
	global_load_lds_dwordx4 v130, s[78:79]
	s_mov_b32 m0, s27
	s_nop 0
	global_load_lds_dwordx4 v134, s[78:79]
	s_add_u32 s62, s78, 0x4000
	s_addc_u32 s63, s79, 0
	s_mov_b32 m0, s28
	ds_read_b128 v[198:201], v164 offset:32768
	ds_read_b128 v[202:205], v164 offset:33792
	ds_read_b128 v[206:209], v164 offset:34816
	ds_read_b128 v[210:213], v164 offset:35840
	ds_read_b128 v[214:217], v164 offset:36864
	ds_read_b128 v[218:221], v164 offset:37888
	ds_read_b128 v[222:225], v164 offset:38912
	ds_read_b128 v[226:229], v164 offset:39936
	global_load_lds_dwordx4 v130, s[62:63]
	s_mov_b32 m0, s29
	s_nop 0
	global_load_lds_dwordx4 v134, s[62:63]
	s_waitcnt vmcnt(8)
	s_waitcnt lgkmcnt(0)
	s_barrier
	s_waitcnt lgkmcnt(0)
	v_mfma_f32_16x16x32_bf16 v[126:129], v[146:149], v[198:201], v[126:129]
	v_mfma_f32_16x16x32_bf16 v[126:129], v[150:153], v[202:205], v[126:129]
	v_mfma_f32_16x16x32_bf16 v[110:113], v[146:149], v[206:209], v[110:113]
	v_mfma_f32_16x16x32_bf16 v[110:113], v[150:153], v[210:213], v[110:113]
	v_mfma_f32_16x16x32_bf16 v[94:97], v[146:149], v[214:217], v[94:97]
	v_mfma_f32_16x16x32_bf16 v[94:97], v[150:153], v[218:221], v[94:97]
	v_mfma_f32_16x16x32_bf16 v[78:81], v[146:149], v[222:225], v[78:81]
	v_mfma_f32_16x16x32_bf16 v[78:81], v[150:153], v[226:229], v[78:81]
	v_mfma_f32_16x16x32_bf16 v[74:77], v[154:157], v[222:225], v[74:77]
	v_mfma_f32_16x16x32_bf16 v[74:77], v[168:171], v[226:229], v[74:77]
	v_mfma_f32_16x16x32_bf16 v[90:93], v[154:157], v[214:217], v[90:93]
	v_mfma_f32_16x16x32_bf16 v[90:93], v[168:171], v[218:221], v[90:93]
	v_mfma_f32_16x16x32_bf16 v[106:109], v[154:157], v[206:209], v[106:109]
	v_mfma_f32_16x16x32_bf16 v[106:109], v[168:171], v[210:213], v[106:109]
	v_mfma_f32_16x16x32_bf16 v[122:125], v[154:157], v[198:201], v[122:125]
	v_mfma_f32_16x16x32_bf16 v[122:125], v[168:171], v[202:205], v[122:125]
	v_mfma_f32_16x16x32_bf16 v[118:121], v[172:175], v[198:201], v[118:121]
	v_mfma_f32_16x16x32_bf16 v[118:121], v[180:183], v[202:205], v[118:121]
	v_mfma_f32_16x16x32_bf16 v[102:105], v[172:175], v[206:209], v[102:105]
	v_mfma_f32_16x16x32_bf16 v[102:105], v[180:183], v[210:213], v[102:105]
	v_mfma_f32_16x16x32_bf16 v[86:89], v[172:175], v[214:217], v[86:89]
	v_mfma_f32_16x16x32_bf16 v[86:89], v[180:183], v[218:221], v[86:89]
	v_mfma_f32_16x16x32_bf16 v[70:73], v[172:175], v[222:225], v[70:73]
	v_mfma_f32_16x16x32_bf16 v[70:73], v[180:183], v[226:229], v[70:73]
	v_mfma_f32_16x16x32_bf16 v[66:69], v[184:187], v[222:225], v[66:69]
	v_mfma_f32_16x16x32_bf16 v[66:69], v[188:191], v[226:229], v[66:69]
	v_mfma_f32_16x16x32_bf16 v[82:85], v[184:187], v[214:217], v[82:85]
	v_mfma_f32_16x16x32_bf16 v[82:85], v[188:191], v[218:221], v[82:85]
	v_mfma_f32_16x16x32_bf16 v[98:101], v[184:187], v[206:209], v[98:101]
	v_mfma_f32_16x16x32_bf16 v[98:101], v[188:191], v[210:213], v[98:101]
	v_mfma_f32_16x16x32_bf16 v[114:117], v[184:187], v[198:201], v[114:117]
	v_mfma_f32_16x16x32_bf16 v[114:117], v[188:191], v[202:205], v[114:117]
	s_barrier
	s_add_u32 s62, s76, 0x8000
	s_addc_u32 s63, s77, 0
	s_add_i32 s59, s59, s3
	s_mov_b32 m0, s59
	ds_read_b128 v[198:201], v164 offset:49152
	ds_read_b128 v[202:205], v164 offset:50176
	ds_read_b128 v[206:209], v164 offset:51200
	ds_read_b128 v[210:213], v164 offset:52224
	ds_read_b128 v[214:217], v164 offset:53248
	ds_read_b128 v[218:221], v164 offset:54272
	ds_read_b128 v[222:225], v164 offset:55296
	ds_read_b128 v[226:229], v164 offset:56320
	global_load_lds_dwordx4 v132, s[62:63]
	s_add_i32 m0, s59, 0x2000
	v_lshl_add_u64 v[158:159], s[62:63], 0, v[136:137]
	s_add_u32 s62, s76, 0xc000
	s_addc_u32 s63, s77, 0
	s_add_i32 s59, s64, s3
	global_load_lds_dwordx4 v[158:159], off
	s_mov_b32 m0, s59
	s_nop 0
	global_load_lds_dwordx4 v132, s[62:63]
	s_add_i32 m0, s59, 0x2000
	s_nop 0
	global_load_lds_dwordx4 v136, s[62:63]
	s_waitcnt vmcnt(6)
	s_waitcnt lgkmcnt(0)
	s_barrier
	s_waitcnt lgkmcnt(0)
	v_mfma_f32_16x16x32_bf16 v[62:65], v[146:149], v[198:201], v[62:65]
	v_mfma_f32_16x16x32_bf16 v[62:65], v[150:153], v[202:205], v[62:65]
	v_mfma_f32_16x16x32_bf16 v[46:49], v[146:149], v[206:209], v[46:49]
	v_mfma_f32_16x16x32_bf16 v[46:49], v[150:153], v[210:213], v[46:49]
	v_mfma_f32_16x16x32_bf16 v[30:33], v[146:149], v[214:217], v[30:33]
	v_mfma_f32_16x16x32_bf16 v[30:33], v[150:153], v[218:221], v[30:33]
	v_mfma_f32_16x16x32_bf16 v[14:17], v[146:149], v[222:225], v[14:17]
	v_mfma_f32_16x16x32_bf16 v[14:17], v[150:153], v[226:229], v[14:17]
	v_mfma_f32_16x16x32_bf16 v[10:13], v[154:157], v[222:225], v[10:13]
	v_mfma_f32_16x16x32_bf16 v[10:13], v[168:171], v[226:229], v[10:13]
	v_mfma_f32_16x16x32_bf16 v[26:29], v[154:157], v[214:217], v[26:29]
	v_mfma_f32_16x16x32_bf16 v[26:29], v[168:171], v[218:221], v[26:29]
	v_mfma_f32_16x16x32_bf16 v[42:45], v[154:157], v[206:209], v[42:45]
	v_mfma_f32_16x16x32_bf16 v[42:45], v[168:171], v[210:213], v[42:45]
	v_mfma_f32_16x16x32_bf16 v[58:61], v[154:157], v[198:201], v[58:61]
	v_mfma_f32_16x16x32_bf16 v[58:61], v[168:171], v[202:205], v[58:61]
	v_mfma_f32_16x16x32_bf16 v[54:57], v[172:175], v[198:201], v[54:57]
	v_mfma_f32_16x16x32_bf16 v[54:57], v[180:183], v[202:205], v[54:57]
	v_mfma_f32_16x16x32_bf16 v[38:41], v[172:175], v[206:209], v[38:41]
	v_mfma_f32_16x16x32_bf16 v[38:41], v[180:183], v[210:213], v[38:41]
	v_mfma_f32_16x16x32_bf16 v[22:25], v[172:175], v[214:217], v[22:25]
	v_mfma_f32_16x16x32_bf16 v[22:25], v[180:183], v[218:221], v[22:25]
	v_mfma_f32_16x16x32_bf16 v[6:9], v[172:175], v[222:225], v[6:9]
	v_mfma_f32_16x16x32_bf16 v[6:9], v[180:183], v[226:229], v[6:9]
	v_mfma_f32_16x16x32_bf16 v[2:5], v[184:187], v[222:225], v[2:5]
	v_mfma_f32_16x16x32_bf16 v[2:5], v[188:191], v[226:229], v[2:5]
	v_mfma_f32_16x16x32_bf16 v[18:21], v[184:187], v[214:217], v[18:21]
	v_mfma_f32_16x16x32_bf16 v[18:21], v[188:191], v[218:221], v[18:21]
	v_mfma_f32_16x16x32_bf16 v[34:37], v[184:187], v[206:209], v[34:37]
	v_mfma_f32_16x16x32_bf16 v[34:37], v[188:191], v[210:213], v[34:37]
	v_mfma_f32_16x16x32_bf16 v[50:53], v[184:187], v[198:201], v[50:53]
	v_mfma_f32_16x16x32_bf16 v[50:53], v[188:191], v[202:205], v[50:53]
	s_barrier
	s_add_i32 s58, s58, 2
	s_add_u32 s72, s72, 0x10000
	s_addc_u32 s73, s73, 0
	s_add_u32 s33, s33, 0x10000
	s_addc_u32 s56, s56, 0
	s_cmp_gt_u32 s58, 61
	s_cbranch_scc0 .LBB0_290
	s_and_b64 vcc, exec, s[12:13]
	s_cbranch_vccz .LBB0_293
	s_barrier

; #define PG8_STAGE(bufoff, gbase, voff) do { _Pragma("unroll") for (int _i = 0; _i < 2; ++_i) \
;         __builtin_amdgcn_global_load_lds((const unsigned*)((const char*)(gbase) + (voff)[_i]), (PG8_LAS unsigned*)(lds + (bufoff) + ldsw + _i * 8192), 16, 0, 0); } while (0)
; #define PG8_LDA(dst, b, h) do { _Pragma("unroll") for (int m = 0; m < 4; ++m) _Pragma("unroll") for (int k = 0; k < 2; ++k) dst[m][k] = *(const PG8_LAS bf16x8*)(lds + PG8_SA(b, h) + aoff + m * 2048 + k * 1024); } while (0)
; #define PG8_LDB(dst, b, h) do { _Pragma("unroll") for (int n = 0; n < 2; ++n) _Pragma("unroll") for (int k = 0; k < 2; ++k) dst[n][k] = *(const PG8_LAS bf16x8*)(lds + PG8_SB(b, h) + boff + n * 2048 + k * 1024); } while (0)
; #define PG8_MMA(ai, bj, At, Bt) do { __builtin_amdgcn_s_setprio(1); _Pragma("unroll") for (int m = 0; m < 4; ++m) _Pragma("unroll") for (int n = 0; n < 2; ++n) _Pragma("unroll") for (int k = 0; k < 2; ++k) \
;         acc[ai][bj][m][n] = __builtin_amdgcn_mfma_f32_16x16x32_bf16(Bt[n][k], At[m][k], acc[ai][bj][m][n], 0, 0, 0); __builtin_amdgcn_s_setprio(0); } while (0)
; #define PG8_WAIT_V(n) asm volatile("s_waitcnt vmcnt(" #n ")" ::: "memory")
; #define PG8_WAIT_L(n) asm volatile("s_waitcnt lgkmcnt(" #n ")" ::: "memory")
; #define PG8_BAR __builtin_amdgcn_s_barrier()
; template <class Epi, class Sched, bool ALIGN_EPI = false, bool SP2 = false>
; __device__ __forceinline__ void gemm_phase(PG8_LAS unsigned char* lds, const Gemm g, const Sched& S, const Epi& E) {
;     ...
;             const char* a1 = cA + (size_t)(t + 1) * kstep;
;             const char* a2 = last ? nA : cA + (size_t)(t + 2) * kstep; const char* b2 = last ? nB : cB + (size_t)(t + 2) * kstep;
;             const char* a3 = a2 + kstep; const char* b3 = b2 + kstep;
;             if (last && has_next) S.a_ready(nxt);
;             if constexpr (SP2) {
;             PG8_LDB(B0, 0, 0); PG8_LDB(B1, 0, 1); PG8_SCHED; PG8_LDA(At, 0, 0); PG8_STAGE(PG8_SA(1, 1), a1 + hstep, voffA);
;             PG8_WAIT_V(8); PG8_WAIT_L(0); PG8_BAR; PG8_MMA(0, 0, At, B0); PG8_MMA(0, 1, At, B1); PG8_BAR; PG8_SCHED;
;             PG8_LDA(At, 0, 1); PG8_STAGE(PG8_SB(0, 0), b2, voffB); PG8_STAGE(PG8_SB(0, 1), b2 + hstep, voffB); PG8_STAGE(PG8_SA(0, 0), a2, voffA);
;             PG8_WAIT_V(8); PG8_WAIT_L(0); PG8_BAR; PG8_MMA(1, 0, At, B0); PG8_MMA(1, 1, At, B1); PG8_BAR; PG8_SCHED;
.LBB0_682:
	ds_read_b128 v[166:169], v163
	ds_read_b128 v[170:173], v163 offset:1024
	ds_read_b128 v[174:177], v163 offset:2048
	ds_read_b128 v[180:183], v163 offset:3072
	ds_read_b128 v[184:187], v164
	ds_read_b128 v[188:191], v164 offset:1024
	ds_read_b128 v[198:201], v164 offset:2048
	ds_read_b128 v[202:205], v164 offset:3072
	v_lshl_add_u64 v[242:243], v[130:131], 0, s[44:45]
	s_add_i32 s83, s29, 0xc000
	v_lshl_add_u64 v[238:239], v[242:243], 0, s[10:11]
	s_mov_b32 m0, s83
	v_lshl_add_u64 v[244:245], v[132:133], 0, s[44:45]
	s_add_i32 s84, s29, 0xe000
	ds_read_b128 v[206:209], v165
	ds_read_b128 v[210:213], v165 offset:1024
	ds_read_b128 v[214:217], v165 offset:2048
	ds_read_b128 v[218:221], v165 offset:3072
	ds_read_b128 v[222:225], v165 offset:4096
	ds_read_b128 v[226:229], v165 offset:5120
	ds_read_b128 v[230:233], v165 offset:6144
	ds_read_b128 v[234:237], v165 offset:7168
	global_load_lds_dwordx4 v[238:239], off
	v_lshl_add_u64 v[238:239], v[244:245], 0, s[10:11]
	s_mov_b32 m0, s84
	s_nop 0
	global_load_lds_dwordx4 v[238:239], off
	s_waitcnt vmcnt(8)
	s_waitcnt lgkmcnt(0)
	s_barrier
	s_waitcnt lgkmcnt(0)
	v_mfma_f32_16x16x32_bf16 v[14:17], v[166:169], v[206:209], v[14:17]
	v_mfma_f32_16x16x32_bf16 v[14:17], v[170:173], v[210:213], v[14:17]
	v_mfma_f32_16x16x32_bf16 v[38:41], v[166:169], v[214:217], v[38:41]
	v_mfma_f32_16x16x32_bf16 v[38:41], v[170:173], v[218:221], v[38:41]
	v_mfma_f32_16x16x32_bf16 v[70:73], v[166:169], v[222:225], v[70:73]
	v_mfma_f32_16x16x32_bf16 v[70:73], v[170:173], v[226:229], v[70:73]
	v_mfma_f32_16x16x32_bf16 v[94:97], v[166:169], v[230:233], v[94:97]
	v_mfma_f32_16x16x32_bf16 v[94:97], v[170:173], v[234:237], v[94:97]
	v_mfma_f32_16x16x32_bf16 v[90:93], v[174:177], v[230:233], v[90:93]
	v_mfma_f32_16x16x32_bf16 v[90:93], v[180:183], v[234:237], v[90:93]
	v_mfma_f32_16x16x32_bf16 v[66:69], v[174:177], v[222:225], v[66:69]
	v_mfma_f32_16x16x32_bf16 v[66:69], v[180:183], v[226:229], v[66:69]
	v_mfma_f32_16x16x32_bf16 v[34:37], v[174:177], v[214:217], v[34:37]
	v_mfma_f32_16x16x32_bf16 v[34:37], v[180:183], v[218:221], v[34:37]
	v_mfma_f32_16x16x32_bf16 v[10:13], v[174:177], v[206:209], v[10:13]
	v_mfma_f32_16x16x32_bf16 v[10:13], v[180:183], v[210:213], v[10:13]
	v_mfma_f32_16x16x32_bf16 v[30:33], v[184:187], v[206:209], v[30:33]
	v_mfma_f32_16x16x32_bf16 v[30:33], v[188:191], v[210:213], v[30:33]
	v_mfma_f32_16x16x32_bf16 v[54:57], v[184:187], v[214:217], v[54:57]
	v_mfma_f32_16x16x32_bf16 v[54:57], v[188:191], v[218:221], v[54:57]
	v_mfma_f32_16x16x32_bf16 v[86:89], v[184:187], v[222:225], v[86:89]
	v_mfma_f32_16x16x32_bf16 v[86:89], v[188:191], v[226:229], v[86:89]
	v_mfma_f32_16x16x32_bf16 v[110:113], v[184:187], v[230:233], v[110:113]
	v_mfma_f32_16x16x32_bf16 v[110:113], v[188:191], v[234:237], v[110:113]
	v_mfma_f32_16x16x32_bf16 v[106:109], v[198:201], v[230:233], v[106:109]
	v_mfma_f32_16x16x32_bf16 v[106:109], v[202:205], v[234:237], v[106:109]
	v_mfma_f32_16x16x32_bf16 v[82:85], v[198:201], v[222:225], v[82:85]
	v_mfma_f32_16x16x32_bf16 v[82:85], v[202:205], v[226:229], v[82:85]
	v_mfma_f32_16x16x32_bf16 v[50:53], v[198:201], v[214:217], v[50:53]
	v_mfma_f32_16x16x32_bf16 v[50:53], v[202:205], v[218:221], v[50:53]
	v_mfma_f32_16x16x32_bf16 v[26:29], v[198:201], v[206:209], v[26:29]
	v_mfma_f32_16x16x32_bf16 v[26:29], v[202:205], v[210:213], v[26:29]
	s_barrier
	v_lshl_add_u64 v[246:247], v[156:157], 0, s[44:45]
	s_add_i32 s85, s80, s28
	v_lshl_add_u64 v[238:239], v[246:247], 0, s[14:15]
	s_mov_b32 m0, s85
	v_lshl_add_u64 v[248:249], v[158:159], 0, s[44:45]
	s_add_i32 s86, s85, 0x2000
	ds_read_b128 v[206:209], v165 offset:16384
	ds_read_b128 v[210:213], v165 offset:17408
	ds_read_b128 v[214:217], v165 offset:18432
	ds_read_b128 v[218:221], v165 offset:19456
	ds_read_b128 v[222:225], v165 offset:20480
	ds_read_b128 v[226:229], v165 offset:21504
	ds_read_b128 v[230:233], v165 offset:22528
	ds_read_b128 v[234:237], v165 offset:23552
	global_load_lds_dwordx4 v[238:239], off
	v_lshl_add_u64 v[238:239], v[248:249], 0, s[14:15]
	s_mov_b32 m0, s86
	s_add_i32 s87, s81, s28
	global_load_lds_dwordx4 v[238:239], off
	v_lshl_add_u64 v[238:239], v[246:247], 0, s[16:17]
	s_mov_b32 m0, s87
	s_add_i32 s88, s87, 0x2000
	global_load_lds_dwordx4 v[238:239], off
	v_lshl_add_u64 v[238:239], v[248:249], 0, s[16:17]
	s_mov_b32 m0, s88
	s_nop 0
	global_load_lds_dwordx4 v[238:239], off
	v_lshl_add_u64 v[238:239], v[242:243], 0, s[14:15]
	s_mov_b32 m0, s29
	s_nop 0
	global_load_lds_dwordx4 v[238:239], off
	v_lshl_add_u64 v[238:239], v[244:245], 0, s[14:15]
	s_mov_b32 m0, s30
	s_nop 0
	global_load_lds_dwordx4 v[238:239], off
	s_waitcnt vmcnt(8)
	s_waitcnt lgkmcnt(0)
	s_barrier
; #define PG8_STAGE(bufoff, gbase, voff) do { _Pragma("unroll") for (int _i = 0; _i < 2; ++_i) \
;         __builtin_amdgcn_global_load_lds((const unsigned*)((const char*)(gbase) + (voff)[_i]), (PG8_LAS unsigned*)(lds + (bufoff) + ldsw + _i * 8192), 16, 0, 0); } while (0)
; #define PG8_LDA(dst, b, h) do { _Pragma("unroll") for (int m = 0; m < 4; ++m) _Pragma("unroll") for (int k = 0; k < 2; ++k) dst[m][k] = *(const PG8_LAS bf16x8*)(lds + PG8_SA(b, h) + aoff + m * 2048 + k * 1024); } while (0)
; #define PG8_LDB(dst, b, h) do { _Pragma("unroll") for (int n = 0; n < 2; ++n) _Pragma("unroll") for (int k = 0; k < 2; ++k) dst[n][k] = *(const PG8_LAS bf16x8*)(lds + PG8_SB(b, h) + boff + n * 2048 + k * 1024); } while (0)
; #define PG8_MMA(ai, bj, At, Bt) do { __builtin_amdgcn_s_setprio(1); _Pragma("unroll") for (int m = 0; m < 4; ++m) _Pragma("unroll") for (int n = 0; n < 2; ++n) _Pragma("unroll") for (int k = 0; k < 2; ++k) \
;         acc[ai][bj][m][n] = __builtin_amdgcn_mfma_f32_16x16x32_bf16(Bt[n][k], At[m][k], acc[ai][bj][m][n], 0, 0, 0); __builtin_amdgcn_s_setprio(0); } while (0)
; #define PG8_WAIT_V(n) asm volatile("s_waitcnt vmcnt(" #n ")" ::: "memory")
; #define PG8_WAIT_L(n) asm volatile("s_waitcnt lgkmcnt(" #n ")" ::: "memory")
; #define PG8_BAR __builtin_amdgcn_s_barrier()
; #define PG8_SCHED __builtin_amdgcn_sched_barrier(0)
; template <class Epi, class Sched, bool ALIGN_EPI = false, bool SP2 = false>
; __device__ __forceinline__ void gemm_phase(PG8_LAS unsigned char* lds, const Gemm g, const Sched& S, const Epi& E) {
;     ...
;             PG8_WAIT_V(8); PG8_WAIT_L(0); PG8_BAR; PG8_MMA(1, 0, At, B0); PG8_MMA(1, 1, At, B1); PG8_BAR; PG8_SCHED;
;             PG8_LDB(B0, 1, 0); PG8_LDB(B1, 1, 1); PG8_SCHED; PG8_LDA(At, 1, 0); PG8_STAGE(PG8_SA(0, 1), a2 + hstep, voffA);
;             PG8_WAIT_V(8); PG8_WAIT_L(0); PG8_BAR; PG8_MMA(0, 0, At, B0); PG8_MMA(0, 1, At, B1); PG8_BAR; PG8_SCHED;
	s_waitcnt lgkmcnt(0)
	v_mfma_f32_16x16x32_bf16 v[126:129], v[166:169], v[206:209], v[126:129]
	v_mfma_f32_16x16x32_bf16 v[126:129], v[170:173], v[210:213], v[126:129]
	v_mfma_f32_16x16x32_bf16 v[102:105], v[166:169], v[214:217], v[102:105]
	v_mfma_f32_16x16x32_bf16 v[102:105], v[170:173], v[218:221], v[102:105]
	v_mfma_f32_16x16x32_bf16 v[62:65], v[166:169], v[222:225], v[62:65]
	v_mfma_f32_16x16x32_bf16 v[62:65], v[170:173], v[226:229], v[62:65]
	v_mfma_f32_16x16x32_bf16 v[22:25], v[166:169], v[230:233], v[22:25]
	v_mfma_f32_16x16x32_bf16 v[22:25], v[170:173], v[234:237], v[22:25]
	v_mfma_f32_16x16x32_bf16 v[18:21], v[174:177], v[230:233], v[18:21]
	v_mfma_f32_16x16x32_bf16 v[18:21], v[180:183], v[234:237], v[18:21]
	v_mfma_f32_16x16x32_bf16 v[58:61], v[174:177], v[222:225], v[58:61]
	v_mfma_f32_16x16x32_bf16 v[58:61], v[180:183], v[226:229], v[58:61]
	v_mfma_f32_16x16x32_bf16 v[98:101], v[174:177], v[214:217], v[98:101]
	v_mfma_f32_16x16x32_bf16 v[98:101], v[180:183], v[218:221], v[98:101]
	v_mfma_f32_16x16x32_bf16 v[122:125], v[174:177], v[206:209], v[122:125]
	v_mfma_f32_16x16x32_bf16 v[122:125], v[180:183], v[210:213], v[122:125]
	v_mfma_f32_16x16x32_bf16 v[118:121], v[184:187], v[206:209], v[118:121]
	v_mfma_f32_16x16x32_bf16 v[118:121], v[188:191], v[210:213], v[118:121]
	v_mfma_f32_16x16x32_bf16 v[78:81], v[184:187], v[214:217], v[78:81]
	v_mfma_f32_16x16x32_bf16 v[78:81], v[188:191], v[218:221], v[78:81]
	v_mfma_f32_16x16x32_bf16 v[46:49], v[184:187], v[222:225], v[46:49]
	v_mfma_f32_16x16x32_bf16 v[46:49], v[188:191], v[226:229], v[46:49]
	v_mfma_f32_16x16x32_bf16 v[6:9], v[184:187], v[230:233], v[6:9]
	v_mfma_f32_16x16x32_bf16 v[6:9], v[188:191], v[234:237], v[6:9]
	v_mfma_f32_16x16x32_bf16 v[2:5], v[198:201], v[230:233], v[2:5]
	v_mfma_f32_16x16x32_bf16 v[2:5], v[202:205], v[234:237], v[2:5]
	v_mfma_f32_16x16x32_bf16 v[42:45], v[198:201], v[222:225], v[42:45]
	v_mfma_f32_16x16x32_bf16 v[42:45], v[202:205], v[226:229], v[42:45]
	v_mfma_f32_16x16x32_bf16 v[74:77], v[198:201], v[214:217], v[74:77]
	v_mfma_f32_16x16x32_bf16 v[74:77], v[202:205], v[218:221], v[74:77]
	v_mfma_f32_16x16x32_bf16 v[114:117], v[198:201], v[206:209], v[114:117]
	v_mfma_f32_16x16x32_bf16 v[114:117], v[202:205], v[210:213], v[114:117]
	s_barrier
	s_add_i32 s89, 0, 0x18000
	s_add_i32 s91, 0, 0x1c000
	v_add_u32_e32 v142, s89, v161
	v_add_u32_e32 v167, s91, v161
	ds_read_b128 v[168:171], v142
	ds_read_b128 v[172:175], v142 offset:1024
	ds_read_b128 v[180:183], v142 offset:2048
	ds_read_b128 v[184:187], v142 offset:3072
	ds_read_b128 v[188:191], v167
	ds_read_b128 v[198:201], v167 offset:1024
	ds_read_b128 v[202:205], v167 offset:2048
	ds_read_b128 v[206:209], v167 offset:3072
	s_mov_b32 m0, s31
	v_lshl_add_u64 v[176:177], v[242:243], 0, s[16:17]
	ds_read_b128 v[210:213], v165 offset:32768
	ds_read_b128 v[214:217], v165 offset:33792
	ds_read_b128 v[218:221], v165 offset:34816
	ds_read_b128 v[222:225], v165 offset:35840
	ds_read_b128 v[226:229], v165 offset:36864
	ds_read_b128 v[230:233], v165 offset:37888
	ds_read_b128 v[234:237], v165 offset:38912
	ds_read_b128 v[238:241], v165 offset:39936
	global_load_lds_dwordx4 v[176:177], off
	v_lshl_add_u64 v[176:177], v[244:245], 0, s[16:17]
	s_mov_b32 m0, s35
	s_nop 0
	global_load_lds_dwordx4 v[176:177], off
	s_waitcnt vmcnt(8)
	s_waitcnt lgkmcnt(0)
	s_barrier
	s_waitcnt lgkmcnt(0)
	v_mfma_f32_16x16x32_bf16 v[14:17], v[168:171], v[210:213], v[14:17]
	v_mfma_f32_16x16x32_bf16 v[14:17], v[172:175], v[214:217], v[14:17]
	v_mfma_f32_16x16x32_bf16 v[38:41], v[168:171], v[218:221], v[38:41]
	v_mfma_f32_16x16x32_bf16 v[38:41], v[172:175], v[222:225], v[38:41]
	v_mfma_f32_16x16x32_bf16 v[70:73], v[168:171], v[226:229], v[70:73]
	v_mfma_f32_16x16x32_bf16 v[70:73], v[172:175], v[230:233], v[70:73]
	v_mfma_f32_16x16x32_bf16 v[94:97], v[168:171], v[234:237], v[94:97]
	v_mfma_f32_16x16x32_bf16 v[94:97], v[172:175], v[238:241], v[94:97]
	v_mfma_f32_16x16x32_bf16 v[90:93], v[180:183], v[234:237], v[90:93]
	v_mfma_f32_16x16x32_bf16 v[90:93], v[184:187], v[238:241], v[90:93]
	v_mfma_f32_16x16x32_bf16 v[66:69], v[180:183], v[226:229], v[66:69]
	v_mfma_f32_16x16x32_bf16 v[66:69], v[184:187], v[230:233], v[66:69]
	v_mfma_f32_16x16x32_bf16 v[34:37], v[180:183], v[218:221], v[34:37]
	v_mfma_f32_16x16x32_bf16 v[34:37], v[184:187], v[222:225], v[34:37]
	v_mfma_f32_16x16x32_bf16 v[10:13], v[180:183], v[210:213], v[10:13]
	v_mfma_f32_16x16x32_bf16 v[10:13], v[184:187], v[214:217], v[10:13]
	v_mfma_f32_16x16x32_bf16 v[30:33], v[188:191], v[210:213], v[30:33]
	v_mfma_f32_16x16x32_bf16 v[30:33], v[198:201], v[214:217], v[30:33]
	v_mfma_f32_16x16x32_bf16 v[54:57], v[188:191], v[218:221], v[54:57]
	v_mfma_f32_16x16x32_bf16 v[54:57], v[198:201], v[222:225], v[54:57]
	v_mfma_f32_16x16x32_bf16 v[86:89], v[188:191], v[226:229], v[86:89]
	v_mfma_f32_16x16x32_bf16 v[86:89], v[198:201], v[230:233], v[86:89]
	v_mfma_f32_16x16x32_bf16 v[110:113], v[188:191], v[234:237], v[110:113]
	v_mfma_f32_16x16x32_bf16 v[110:113], v[198:201], v[238:241], v[110:113]
	v_mfma_f32_16x16x32_bf16 v[106:109], v[202:205], v[234:237], v[106:109]
	v_mfma_f32_16x16x32_bf16 v[106:109], v[206:209], v[238:241], v[106:109]
	v_mfma_f32_16x16x32_bf16 v[82:85], v[202:205], v[226:229], v[82:85]
	v_mfma_f32_16x16x32_bf16 v[82:85], v[206:209], v[230:233], v[82:85]
	v_mfma_f32_16x16x32_bf16 v[50:53], v[202:205], v[218:221], v[50:53]
	v_mfma_f32_16x16x32_bf16 v[50:53], v[206:209], v[222:225], v[50:53]
	v_mfma_f32_16x16x32_bf16 v[26:29], v[202:205], v[210:213], v[26:29]
	v_mfma_f32_16x16x32_bf16 v[26:29], v[206:209], v[214:217], v[26:29]
	s_barrier
; __device__ __forceinline__ float bflo(unsigned w) { return __uint_as_float(w << 16); }
; __device__ __forceinline__ float bfhi(unsigned w) { return __uint_as_float(w & 0xffff0000u); }
; #define PG8_STAGE(bufoff, gbase, voff) do { _Pragma("unroll") for (int _i = 0; _i < 2; ++_i) \
;         __builtin_amdgcn_global_load_lds((const unsigned*)((const char*)(gbase) + (voff)[_i]), (PG8_LAS unsigned*)(lds + (bufoff) + ldsw + _i * 8192), 16, 0, 0); } while (0)
; #define PG8_LDA(dst, b, h) do { _Pragma("unroll") for (int m = 0; m < 4; ++m) _Pragma("unroll") for (int k = 0; k < 2; ++k) dst[m][k] = *(const PG8_LAS bf16x8*)(lds + PG8_SA(b, h) + aoff + m * 2048 + k * 1024); } while (0)
;     __device__ __forceinline__ void mid(f32x4 (&acc)[2][2][4][2], const Unit& u, int wr, int wc, int fr, int fq) const {
;         int row0 = u.pm * BM + wr * 64 + fr; const int col0 = u.pn * BM + wc * 32 + 8 * fq;
;         asm volatile("" : "+v"(row0));
; #pragma unroll
;         for (int ai = 0; ai < 2; ++ai)
; #pragma unroll
;             for (int m = 0; m < 4; ++m) { const bf16_t* pr = P + (size_t)(row0 + ai * HALF + m * 16) * NP + col0;
; #pragma unroll
;                 for (int bj = 0; bj < 2; ++bj) { const u32x4 a = *(const u32x4*)(pr + PC_GA + bj * HALF), b = *(const u32x4*)(pr + PC_GB + bj * HALF);
;                     const f32x4 b0 = {bflo(b.x), bfhi(b.x), bflo(b.y), bfhi(b.y)}, b1 = {bflo(b.z), bfhi(b.z), bflo(b.w), bfhi(b.w)};
;                     const f32x4 a0 = {bflo(a.x), bfhi(a.x), bflo(a.y), bfhi(a.y)}, a1 = {bflo(a.z), bfhi(a.z), bflo(a.w), bfhi(a.w)};
;                     f32x4 r0, r1;
; #pragma unroll
;                     for (int j = 0; j < 4; ++j) { r0[j] = a0[j] * __builtin_amdgcn_rcpf(fmaxf(b0[j], 1e-30f)); r1[j] = a1[j] * __builtin_amdgcn_rcpf(fmaxf(b1[j], 1e-30f)); }
;                     acc[ai][bj][m][0] *= r0; acc[ai][bj][m][1] *= r1; }
;                 asm volatile("" ::: "memory"); }
; template <class Epi, class Sched, bool ALIGN_EPI = false, bool SP2 = false>
; __device__ __forceinline__ void gemm_phase(PG8_LAS unsigned char* lds, const Gemm g, const Sched& S, const Epi& E) {
;     ...
;             PG8_LDA(At, 1, 1); PG8_STAGE(PG8_SB(1, 0), b3, voffB); PG8_STAGE(PG8_SB(1, 1), b3 + hstep, voffB); PG8_STAGE(PG8_SA(1, 0), a3, voffA);
;             PG8_WAIT_V(8); PG8_WAIT_L(0); PG8_BAR; PG8_MMA(1, 0, At, B0); PG8_MMA(1, 1, At, B1); PG8_BAR; PG8_SCHED;
	s_add_i32 s89, s89, s28
	v_lshl_add_u64 v[176:177], v[246:247], 0, s[22:23]
	s_mov_b32 m0, s89
	s_add_i32 s90, s89, 0x2000
	ds_read_b128 v[210:213], v165 offset:49152
	ds_read_b128 v[214:217], v165 offset:50176
	ds_read_b128 v[218:221], v165 offset:51200
	ds_read_b128 v[222:225], v165 offset:52224
	ds_read_b128 v[226:229], v165 offset:53248
	ds_read_b128 v[230:233], v165 offset:54272
	ds_read_b128 v[234:237], v165 offset:55296
	ds_read_b128 v[238:241], v165 offset:56320
	global_load_lds_dwordx4 v[176:177], off
	v_lshl_add_u64 v[176:177], v[248:249], 0, s[22:23]
	s_mov_b32 m0, s90
	s_add_i32 s91, s91, s28
	global_load_lds_dwordx4 v[176:177], off
	v_lshl_add_u64 v[176:177], v[246:247], 0, s[36:37]
	s_mov_b32 m0, s91
	s_add_i32 s92, s91, 0x2000
	global_load_lds_dwordx4 v[176:177], off
	v_lshl_add_u64 v[176:177], v[248:249], 0, s[36:37]
	s_mov_b32 m0, s92
	s_nop 0
	global_load_lds_dwordx4 v[176:177], off
	v_lshl_add_u64 v[176:177], v[242:243], 0, s[22:23]
	s_mov_b32 m0, s75
	s_nop 0
	global_load_lds_dwordx4 v[176:177], off
	v_lshl_add_u64 v[176:177], v[244:245], 0, s[22:23]
	s_mov_b32 m0, s76
	s_nop 0
	global_load_lds_dwordx4 v[176:177], off
	s_waitcnt vmcnt(8)
	s_waitcnt lgkmcnt(0)
	s_barrier
	s_waitcnt lgkmcnt(0)
	v_mfma_f32_16x16x32_bf16 v[126:129], v[168:171], v[210:213], v[126:129]
	v_mfma_f32_16x16x32_bf16 v[126:129], v[172:175], v[214:217], v[126:129]
	v_mfma_f32_16x16x32_bf16 v[102:105], v[168:171], v[218:221], v[102:105]
	v_mfma_f32_16x16x32_bf16 v[102:105], v[172:175], v[222:225], v[102:105]
	v_mfma_f32_16x16x32_bf16 v[62:65], v[168:171], v[226:229], v[62:65]
	v_mfma_f32_16x16x32_bf16 v[62:65], v[172:175], v[230:233], v[62:65]
	v_mfma_f32_16x16x32_bf16 v[22:25], v[168:171], v[234:237], v[22:25]
	v_mfma_f32_16x16x32_bf16 v[22:25], v[172:175], v[238:241], v[22:25]
	v_mfma_f32_16x16x32_bf16 v[18:21], v[180:183], v[234:237], v[18:21]
	v_mfma_f32_16x16x32_bf16 v[18:21], v[184:187], v[238:241], v[18:21]
	v_mfma_f32_16x16x32_bf16 v[58:61], v[180:183], v[226:229], v[58:61]
	v_mfma_f32_16x16x32_bf16 v[58:61], v[184:187], v[230:233], v[58:61]
	v_mfma_f32_16x16x32_bf16 v[98:101], v[180:183], v[218:221], v[98:101]
	v_mfma_f32_16x16x32_bf16 v[98:101], v[184:187], v[222:225], v[98:101]
	v_mfma_f32_16x16x32_bf16 v[122:125], v[180:183], v[210:213], v[122:125]
	v_mfma_f32_16x16x32_bf16 v[122:125], v[184:187], v[214:217], v[122:125]
	v_mfma_f32_16x16x32_bf16 v[118:121], v[188:191], v[210:213], v[118:121]
	v_mfma_f32_16x16x32_bf16 v[118:121], v[198:201], v[214:217], v[118:121]
	v_mfma_f32_16x16x32_bf16 v[78:81], v[188:191], v[218:221], v[78:81]
	v_mfma_f32_16x16x32_bf16 v[78:81], v[198:201], v[222:225], v[78:81]
	v_mfma_f32_16x16x32_bf16 v[46:49], v[188:191], v[226:229], v[46:49]
	v_mfma_f32_16x16x32_bf16 v[46:49], v[198:201], v[230:233], v[46:49]
	v_mfma_f32_16x16x32_bf16 v[6:9], v[188:191], v[234:237], v[6:9]
	v_mfma_f32_16x16x32_bf16 v[6:9], v[198:201], v[238:241], v[6:9]
	v_mfma_f32_16x16x32_bf16 v[2:5], v[202:205], v[234:237], v[2:5]
	v_mfma_f32_16x16x32_bf16 v[2:5], v[206:209], v[238:241], v[2:5]
	v_mfma_f32_16x16x32_bf16 v[42:45], v[202:205], v[226:229], v[42:45]
	v_mfma_f32_16x16x32_bf16 v[42:45], v[206:209], v[230:233], v[42:45]
	v_mfma_f32_16x16x32_bf16 v[74:77], v[202:205], v[218:221], v[74:77]
	v_mfma_f32_16x16x32_bf16 v[74:77], v[206:209], v[222:225], v[74:77]
	v_mfma_f32_16x16x32_bf16 v[114:117], v[202:205], v[210:213], v[114:117]
	v_mfma_f32_16x16x32_bf16 v[114:117], v[206:209], v[214:217], v[114:117]
	s_barrier
	s_add_i32 s27, s27, 2
	s_add_u32 s44, s44, 0x10000
	s_addc_u32 s45, s45, 0
	s_cmp_lt_u32 s27, 30
	s_cbranch_scc1 .LBB0_682
	s_ashr_i32 s41, s40, 31
	s_lshl_b64 s[44:45], s[40:41], 21
	s_add_u32 s44, s18, s44
	s_addc_u32 s45, s19, s45
	s_ashr_i32 s39, s38, 31
	s_lshl_b64 s[46:47], s[38:39], 21
	v_readlane_b32 s58, v255, 15
	v_readlane_b32 s59, v255, 16
	s_add_u32 s46, s58, s46
	s_addc_u32 s47, s59, s47
	s_lshl_b32 s39, s26, 8
	v_or_b32_e32 v130, s39, v162
	v_ashrrev_i32_e32 v131, 31, v130
	v_lshl_add_u32 v166, s70, 8, v160
	v_lshl_add_u64 v[156:157], v[130:131], 1, s[24:25]
	v_mov_b32_e32 v168, v166
	s_and_b64 s[26:27], s[0:1], exec
	v_mad_i64_i32 v[158:159], s[58:59], v168, s78, v[156:157]
	v_add_co_u32_e32 v174, vcc, s61, v158
	s_cselect_b32 s41, s45, s51
	s_nop 0
	v_addc_co_u32_e32 v175, vcc, 0, v159, vcc
	v_add_co_u32_e32 v158, vcc, s77, v158
	global_load_dwordx4 v[130:133], v[174:175], off
	s_nop 0
	v_addc_co_u32_e32 v159, vcc, 0, v159, vcc
	global_load_dwordx4 v[170:173], v[158:159], off
	s_cselect_b32 s93, s44, s50
	s_cselect_b32 s27, s47, s49
	s_cselect_b32 s97, s46, s48
	s_add_u32 s50, s50, 0x10c000
	s_addc_u32 s51, s51, 0
	s_add_u32 s26, s48, 0x110000
	s_addc_u32 s33, s49, 0
	s_mov_b32 s56, 30
	s_waitcnt vmcnt(0)
	v_and_b32_e32 v177, 0xffff0000, v130
	v_lshlrev_b32_e32 v169, 16, v170
	v_max_f32_e32 v169, v169, v169
	v_lshlrev_b32_e32 v178, 16, v171
	v_and_b32_e32 v179, 0xffff0000, v171
	v_lshlrev_b32_e32 v171, 16, v172
	v_max_f32_e32 v169, 0xda24260, v169
	v_and_b32_e32 v176, 0xffff0000, v170
	v_rcp_f32_e32 v170, v169
	v_max_f32_e32 v169, v171, v171
	v_max_f32_e32 v169, 0xda24260, v169
	v_and_b32_e32 v180, 0xffff0000, v172
	v_rcp_f32_e32 v172, v169
	v_max_f32_e32 v169, v176, v176
	v_max_f32_e32 v169, 0xda24260, v169
	v_lshlrev_b32_e32 v176, 16, v130
	v_max_f32_e32 v130, v180, v180
	v_rcp_f32_e32 v171, v169
	v_max_f32_e32 v130, 0xda24260, v130
	v_lshlrev_b32_e32 v181, 16, v173
	v_and_b32_e32 v182, 0xffff0000, v173
	v_rcp_f32_e32 v173, v130
	v_max_f32_e32 v130, v178, v178
	v_pk_mul_f32 v[170:171], v[170:171], v[176:177]
	v_lshlrev_b32_e32 v176, 16, v132
	v_and_b32_e32 v177, 0xffff0000, v132
	v_max_f32_e32 v130, 0xda24260, v130
	v_pk_mul_f32 v[172:173], v[172:173], v[176:177]
	v_rcp_f32_e32 v176, v130
	v_max_f32_e32 v130, v181, v181
	v_lshlrev_b32_e32 v180, 16, v131
	v_and_b32_e32 v181, 0xffff0000, v131
	v_max_f32_e32 v131, v182, v182
	v_max_f32_e32 v130, 0xda24260, v130
	v_max_f32_e32 v131, 0xda24260, v131
	v_rcp_f32_e32 v130, v130
	v_rcp_f32_e32 v131, v131
	v_max_f32_e32 v132, v179, v179
	v_max_f32_e32 v132, 0xda24260, v132
	v_rcp_f32_e32 v177, v132
	v_lshlrev_b32_e32 v132, 16, v133
	v_and_b32_e32 v133, 0xffff0000, v133
	v_pk_mul_f32 v[130:131], v[130:131], v[132:133]
	v_pk_mul_f32 v[14:15], v[14:15], v[170:171]
	v_pk_mul_f32 v[12:13], v[12:13], v[130:131]
	v_pk_mul_f32 v[10:11], v[10:11], v[172:173]
	global_load_dwordx4 v[130:133], v[174:175], off offset:256
	global_load_dwordx4 v[170:173], v[158:159], off offset:256
	v_pk_mul_f32 v[176:177], v[176:177], v[180:181]
	s_waitcnt vmcnt(0)
; __device__ __forceinline__ float bflo(unsigned w) { return __uint_as_float(w << 16); }
; __device__ __forceinline__ float bfhi(unsigned w) { return __uint_as_float(w & 0xffff0000u); }
;     __device__ __forceinline__ void mid(f32x4 (&acc)[2][2][4][2], const Unit& u, int wr, int wc, int fr, int fq) const {
;         int row0 = u.pm * BM + wr * 64 + fr; const int col0 = u.pn * BM + wc * 32 + 8 * fq;
;         asm volatile("" : "+v"(row0));
; #pragma unroll
;         for (int ai = 0; ai < 2; ++ai)
; #pragma unroll
;             for (int m = 0; m < 4; ++m) { const bf16_t* pr = P + (size_t)(row0 + ai * HALF + m * 16) * NP + col0;
; #pragma unroll
;                 for (int bj = 0; bj < 2; ++bj) { const u32x4 a = *(const u32x4*)(pr + PC_GA + bj * HALF), b = *(const u32x4*)(pr + PC_GB + bj * HALF);
;                     const f32x4 b0 = {bflo(b.x), bfhi(b.x), bflo(b.y), bfhi(b.y)}, b1 = {bflo(b.z), bfhi(b.z), bflo(b.w), bfhi(b.w)};
;                     const f32x4 a0 = {bflo(a.x), bfhi(a.x), bflo(a.y), bfhi(a.y)}, a1 = {bflo(a.z), bfhi(a.z), bflo(a.w), bfhi(a.w)};
;                     f32x4 r0, r1;
; #pragma unroll
;                     for (int j = 0; j < 4; ++j) { r0[j] = a0[j] * __builtin_amdgcn_rcpf(fmaxf(b0[j], 1e-30f)); r1[j] = a1[j] * __builtin_amdgcn_rcpf(fmaxf(b1[j], 1e-30f)); }
;                     acc[ai][bj][m][0] *= r0; acc[ai][bj][m][1] *= r1; }
;                 asm volatile("" ::: "memory"); }
	v_lshlrev_b32_e32 v158, 16, v170
	v_and_b32_e32 v159, 0xffff0000, v170
	v_lshlrev_b32_e32 v169, 16, v171
	v_and_b32_e32 v174, 0xffff0000, v171
	v_lshlrev_b32_e32 v170, 16, v172
	v_and_b32_e32 v171, 0xffff0000, v172
	v_max_f32_e32 v158, v158, v158
	v_max_f32_e32 v159, v159, v159
	v_pk_mul_f32 v[16:17], v[16:17], v[176:177]
	v_lshlrev_b32_e32 v175, 16, v173
	v_and_b32_e32 v176, 0xffff0000, v173
	v_max_f32_e32 v158, 0xda24260, v158
	v_max_f32_e32 v170, v170, v170
	v_max_f32_e32 v159, 0xda24260, v159
	v_lshlrev_b32_e32 v172, 16, v130
	v_and_b32_e32 v173, 0xffff0000, v130
	v_max_f32_e32 v130, v171, v171
	v_rcp_f32_e32 v158, v158
	v_max_f32_e32 v170, 0xda24260, v170
	v_rcp_f32_e32 v159, v159
	v_max_f32_e32 v130, 0xda24260, v130
	v_rcp_f32_e32 v170, v170
	v_rcp_f32_e32 v171, v130
	v_max_f32_e32 v130, v169, v169
	v_pk_mul_f32 v[158:159], v[158:159], v[172:173]
	v_lshlrev_b32_e32 v172, 16, v132
	v_and_b32_e32 v173, 0xffff0000, v132
	v_max_f32_e32 v130, 0xda24260, v130
	v_pk_mul_f32 v[170:171], v[170:171], v[172:173]
	v_rcp_f32_e32 v172, v130
	v_max_f32_e32 v130, v175, v175
	v_max_f32_e32 v132, v174, v174
	v_lshlrev_b32_e32 v174, 16, v131
	v_and_b32_e32 v175, 0xffff0000, v131
	v_max_f32_e32 v131, v176, v176
	v_max_f32_e32 v130, 0xda24260, v130
	v_max_f32_e32 v131, 0xda24260, v131
	v_rcp_f32_e32 v130, v130
	v_rcp_f32_e32 v131, v131
	v_max_f32_e32 v132, 0xda24260, v132
	v_rcp_f32_e32 v173, v132
	v_lshlrev_b32_e32 v132, 16, v133
	v_and_b32_e32 v133, 0xffff0000, v133
	v_pk_mul_f32 v[130:131], v[130:131], v[132:133]
	v_pk_mul_f32 v[30:31], v[30:31], v[158:159]
	v_pk_mul_f32 v[28:29], v[28:29], v[130:131]
	v_add_u32_e32 v130, 16, v168
	v_mad_i64_i32 v[158:159], s[58:59], v130, s78, v[156:157]
	v_pk_mul_f32 v[172:173], v[172:173], v[174:175]
	v_add_co_u32_e32 v174, vcc, s61, v158
	v_pk_mul_f32 v[32:33], v[32:33], v[172:173]
	s_nop 0
	v_addc_co_u32_e32 v175, vcc, 0, v159, vcc
	v_add_co_u32_e32 v158, vcc, s77, v158
	v_pk_mul_f32 v[26:27], v[26:27], v[170:171]
	s_nop 0
	v_addc_co_u32_e32 v159, vcc, 0, v159, vcc
	global_load_dwordx4 v[130:133], v[174:175], off
	global_load_dwordx4 v[170:173], v[158:159], off
	s_waitcnt vmcnt(1)
	v_and_b32_e32 v177, 0xffff0000, v130
	s_waitcnt vmcnt(0)
	v_lshlrev_b32_e32 v169, 16, v170
	v_max_f32_e32 v169, v169, v169
	v_lshlrev_b32_e32 v178, 16, v171
	v_and_b32_e32 v179, 0xffff0000, v171
	v_lshlrev_b32_e32 v171, 16, v172
	v_max_f32_e32 v169, 0xda24260, v169
	v_and_b32_e32 v176, 0xffff0000, v170
	v_rcp_f32_e32 v170, v169
	v_max_f32_e32 v169, v171, v171
	v_max_f32_e32 v169, 0xda24260, v169
	v_and_b32_e32 v180, 0xffff0000, v172
	v_rcp_f32_e32 v172, v169
	v_max_f32_e32 v169, v176, v176
	v_max_f32_e32 v169, 0xda24260, v169
	v_lshlrev_b32_e32 v176, 16, v130
	v_max_f32_e32 v130, v180, v180
	v_rcp_f32_e32 v171, v169
	v_max_f32_e32 v130, 0xda24260, v130
	v_lshlrev_b32_e32 v181, 16, v173
	v_and_b32_e32 v182, 0xffff0000, v173
	v_rcp_f32_e32 v173, v130
	v_max_f32_e32 v130, v178, v178
	v_pk_mul_f32 v[170:171], v[170:171], v[176:177]
	v_lshlrev_b32_e32 v176, 16, v132
	v_and_b32_e32 v177, 0xffff0000, v132
	v_max_f32_e32 v130, 0xda24260, v130
	v_pk_mul_f32 v[172:173], v[172:173], v[176:177]
	v_rcp_f32_e32 v176, v130
	v_max_f32_e32 v130, v181, v181
	v_lshlrev_b32_e32 v180, 16, v131
	v_and_b32_e32 v181, 0xffff0000, v131
	v_max_f32_e32 v131, v182, v182
	v_max_f32_e32 v130, 0xda24260, v130
	v_max_f32_e32 v131, 0xda24260, v131
	v_rcp_f32_e32 v130, v130
	v_rcp_f32_e32 v131, v131
	v_max_f32_e32 v132, v179, v179
	v_max_f32_e32 v132, 0xda24260, v132
	v_rcp_f32_e32 v177, v132
	v_lshlrev_b32_e32 v132, 16, v133
	v_and_b32_e32 v133, 0xffff0000, v133
	v_pk_mul_f32 v[130:131], v[130:131], v[132:133]
	v_pk_mul_f32 v[38:39], v[38:39], v[170:171]
	v_pk_mul_f32 v[36:37], v[36:37], v[130:131]
	v_pk_mul_f32 v[34:35], v[34:35], v[172:173]
	global_load_dwordx4 v[130:133], v[174:175], off offset:256
	global_load_dwordx4 v[170:173], v[158:159], off offset:256
	v_pk_mul_f32 v[176:177], v[176:177], v[180:181]
	s_waitcnt vmcnt(0)
	v_lshlrev_b32_e32 v158, 16, v170
	v_and_b32_e32 v159, 0xffff0000, v170
	v_lshlrev_b32_e32 v169, 16, v171
	v_and_b32_e32 v174, 0xffff0000, v171
	v_lshlrev_b32_e32 v170, 16, v172
	v_and_b32_e32 v171, 0xffff0000, v172
	v_max_f32_e32 v158, v158, v158
	v_max_f32_e32 v159, v159, v159
	v_pk_mul_f32 v[40:41], v[40:41], v[176:177]
	v_lshlrev_b32_e32 v175, 16, v173
	v_and_b32_e32 v176, 0xffff0000, v173
	v_max_f32_e32 v158, 0xda24260, v158
	v_max_f32_e32 v170, v170, v170
	v_max_f32_e32 v159, 0xda24260, v159
	v_lshlrev_b32_e32 v172, 16, v130
	v_and_b32_e32 v173, 0xffff0000, v130
	v_max_f32_e32 v130, v171, v171
	v_rcp_f32_e32 v158, v158
	v_max_f32_e32 v170, 0xda24260, v170
	v_rcp_f32_e32 v159, v159
	v_max_f32_e32 v130, 0xda24260, v130
	v_rcp_f32_e32 v170, v170
	v_rcp_f32_e32 v171, v130
	v_max_f32_e32 v130, v169, v169
	v_pk_mul_f32 v[158:159], v[158:159], v[172:173]
	v_lshlrev_b32_e32 v172, 16, v132
	v_and_b32_e32 v173, 0xffff0000, v132
	v_max_f32_e32 v130, 0xda24260, v130
	v_pk_mul_f32 v[170:171], v[170:171], v[172:173]
	v_rcp_f32_e32 v172, v130
	v_max_f32_e32 v130, v175, v175
	v_max_f32_e32 v132, v174, v174
	v_lshlrev_b32_e32 v174, 16, v131
	v_and_b32_e32 v175, 0xffff0000, v131
	v_max_f32_e32 v131, v176, v176
	v_max_f32_e32 v130, 0xda24260, v130
	v_max_f32_e32 v131, 0xda24260, v131
	v_rcp_f32_e32 v130, v130
	v_rcp_f32_e32 v131, v131
	v_max_f32_e32 v132, 0xda24260, v132
	v_rcp_f32_e32 v173, v132
	v_lshlrev_b32_e32 v132, 16, v133
	v_and_b32_e32 v133, 0xffff0000, v133
	v_pk_mul_f32 v[130:131], v[130:131], v[132:133]
	v_pk_mul_f32 v[54:55], v[54:55], v[158:159]
	v_pk_mul_f32 v[52:53], v[52:53], v[130:131]
	v_add_u32_e32 v130, 32, v168
	v_mad_i64_i32 v[158:159], s[58:59], v130, s78, v[156:157]
	v_pk_mul_f32 v[172:173], v[172:173], v[174:175]
	v_add_co_u32_e32 v174, vcc, s61, v158
	v_pk_mul_f32 v[56:57], v[56:57], v[172:173]
	s_nop 0
	v_addc_co_u32_e32 v175, vcc, 0, v159, vcc
	v_add_co_u32_e32 v158, vcc, s77, v158
	v_pk_mul_f32 v[50:51], v[50:51], v[170:171]
	s_nop 0
	v_addc_co_u32_e32 v159, vcc, 0, v159, vcc
	global_load_dwordx4 v[130:133], v[174:175], off
	global_load_dwordx4 v[170:173], v[158:159], off
	s_waitcnt vmcnt(1)
; __device__ __forceinline__ float bflo(unsigned w) { return __uint_as_float(w << 16); }
; __device__ __forceinline__ float bfhi(unsigned w) { return __uint_as_float(w & 0xffff0000u); }
;     __device__ __forceinline__ void mid(f32x4 (&acc)[2][2][4][2], const Unit& u, int wr, int wc, int fr, int fq) const {
;         int row0 = u.pm * BM + wr * 64 + fr; const int col0 = u.pn * BM + wc * 32 + 8 * fq;
;         asm volatile("" : "+v"(row0));
; #pragma unroll
;         for (int ai = 0; ai < 2; ++ai)
; #pragma unroll
;             for (int m = 0; m < 4; ++m) { const bf16_t* pr = P + (size_t)(row0 + ai * HALF + m * 16) * NP + col0;
; #pragma unroll
;                 for (int bj = 0; bj < 2; ++bj) { const u32x4 a = *(const u32x4*)(pr + PC_GA + bj * HALF), b = *(const u32x4*)(pr + PC_GB + bj * HALF);
;                     const f32x4 b0 = {bflo(b.x), bfhi(b.x), bflo(b.y), bfhi(b.y)}, b1 = {bflo(b.z), bfhi(b.z), bflo(b.w), bfhi(b.w)};
;                     const f32x4 a0 = {bflo(a.x), bfhi(a.x), bflo(a.y), bfhi(a.y)}, a1 = {bflo(a.z), bfhi(a.z), bflo(a.w), bfhi(a.w)};
;                     f32x4 r0, r1;
; #pragma unroll
;                     for (int j = 0; j < 4; ++j) { r0[j] = a0[j] * __builtin_amdgcn_rcpf(fmaxf(b0[j], 1e-30f)); r1[j] = a1[j] * __builtin_amdgcn_rcpf(fmaxf(b1[j], 1e-30f)); }
;                     acc[ai][bj][m][0] *= r0; acc[ai][bj][m][1] *= r1; }
;                 asm volatile("" ::: "memory"); }
	v_and_b32_e32 v177, 0xffff0000, v130
	s_waitcnt vmcnt(0)
	v_lshlrev_b32_e32 v169, 16, v170
	v_max_f32_e32 v169, v169, v169
	v_lshlrev_b32_e32 v178, 16, v171
	v_and_b32_e32 v179, 0xffff0000, v171
	v_lshlrev_b32_e32 v171, 16, v172
	v_max_f32_e32 v169, 0xda24260, v169
	v_and_b32_e32 v176, 0xffff0000, v170
	v_rcp_f32_e32 v170, v169
	v_max_f32_e32 v169, v171, v171
	v_max_f32_e32 v169, 0xda24260, v169
	v_and_b32_e32 v180, 0xffff0000, v172
	v_rcp_f32_e32 v172, v169
	v_max_f32_e32 v169, v176, v176
	v_max_f32_e32 v169, 0xda24260, v169
	v_lshlrev_b32_e32 v176, 16, v130
	v_max_f32_e32 v130, v180, v180
	v_rcp_f32_e32 v171, v169
	v_max_f32_e32 v130, 0xda24260, v130
	v_lshlrev_b32_e32 v181, 16, v173
	v_and_b32_e32 v182, 0xffff0000, v173
	v_rcp_f32_e32 v173, v130
	v_max_f32_e32 v130, v178, v178
	v_pk_mul_f32 v[170:171], v[170:171], v[176:177]
	v_lshlrev_b32_e32 v176, 16, v132
	v_and_b32_e32 v177, 0xffff0000, v132
	v_max_f32_e32 v130, 0xda24260, v130
	v_pk_mul_f32 v[172:173], v[172:173], v[176:177]
	v_rcp_f32_e32 v176, v130
	v_max_f32_e32 v130, v181, v181
	v_lshlrev_b32_e32 v180, 16, v131
	v_and_b32_e32 v181, 0xffff0000, v131
	v_max_f32_e32 v131, v182, v182
	v_max_f32_e32 v130, 0xda24260, v130
	v_max_f32_e32 v131, 0xda24260, v131
	v_rcp_f32_e32 v130, v130
	v_rcp_f32_e32 v131, v131
	v_max_f32_e32 v132, v179, v179
	v_max_f32_e32 v132, 0xda24260, v132
	v_rcp_f32_e32 v177, v132
	v_lshlrev_b32_e32 v132, 16, v133
	v_and_b32_e32 v133, 0xffff0000, v133
	v_pk_mul_f32 v[130:131], v[130:131], v[132:133]
	v_pk_mul_f32 v[70:71], v[70:71], v[170:171]
	v_pk_mul_f32 v[68:69], v[68:69], v[130:131]
	v_pk_mul_f32 v[66:67], v[66:67], v[172:173]
	global_load_dwordx4 v[130:133], v[174:175], off offset:256
	global_load_dwordx4 v[170:173], v[158:159], off offset:256
	v_pk_mul_f32 v[176:177], v[176:177], v[180:181]
	s_waitcnt vmcnt(0)
	v_lshlrev_b32_e32 v158, 16, v170
	v_and_b32_e32 v159, 0xffff0000, v170
	v_lshlrev_b32_e32 v169, 16, v171
	v_and_b32_e32 v174, 0xffff0000, v171
	v_lshlrev_b32_e32 v170, 16, v172
	v_and_b32_e32 v171, 0xffff0000, v172
	v_max_f32_e32 v158, v158, v158
	v_max_f32_e32 v159, v159, v159
	v_pk_mul_f32 v[72:73], v[72:73], v[176:177]
	v_lshlrev_b32_e32 v175, 16, v173
	v_and_b32_e32 v176, 0xffff0000, v173
	v_max_f32_e32 v158, 0xda24260, v158
	v_max_f32_e32 v170, v170, v170
	v_max_f32_e32 v159, 0xda24260, v159
	v_lshlrev_b32_e32 v172, 16, v130
	v_and_b32_e32 v173, 0xffff0000, v130
	v_max_f32_e32 v130, v171, v171
	v_rcp_f32_e32 v158, v158
	v_max_f32_e32 v170, 0xda24260, v170
	v_rcp_f32_e32 v159, v159
	v_max_f32_e32 v130, 0xda24260, v130
	v_rcp_f32_e32 v170, v170
	v_rcp_f32_e32 v171, v130
	v_max_f32_e32 v130, v169, v169
	v_pk_mul_f32 v[158:159], v[158:159], v[172:173]
	v_lshlrev_b32_e32 v172, 16, v132
	v_and_b32_e32 v173, 0xffff0000, v132
	v_max_f32_e32 v130, 0xda24260, v130
	v_pk_mul_f32 v[170:171], v[170:171], v[172:173]
	v_rcp_f32_e32 v172, v130
	v_max_f32_e32 v130, v175, v175
	v_max_f32_e32 v132, v174, v174
	v_lshlrev_b32_e32 v174, 16, v131
	v_and_b32_e32 v175, 0xffff0000, v131
	v_max_f32_e32 v131, v176, v176
	v_max_f32_e32 v130, 0xda24260, v130
	v_max_f32_e32 v131, 0xda24260, v131
	v_rcp_f32_e32 v130, v130
	v_rcp_f32_e32 v131, v131
	v_max_f32_e32 v132, 0xda24260, v132
	v_rcp_f32_e32 v173, v132
	v_lshlrev_b32_e32 v132, 16, v133
	v_and_b32_e32 v133, 0xffff0000, v133
	v_pk_mul_f32 v[130:131], v[130:131], v[132:133]
	v_pk_mul_f32 v[86:87], v[86:87], v[158:159]
	v_pk_mul_f32 v[84:85], v[84:85], v[130:131]
	v_add_u32_e32 v130, 48, v168
	v_mad_i64_i32 v[158:159], s[58:59], v130, s78, v[156:157]
	v_pk_mul_f32 v[172:173], v[172:173], v[174:175]
	v_add_co_u32_e32 v174, vcc, s61, v158
	v_pk_mul_f32 v[88:89], v[88:89], v[172:173]
	s_nop 0
	v_addc_co_u32_e32 v175, vcc, 0, v159, vcc
	v_add_co_u32_e32 v158, vcc, s77, v158
	v_pk_mul_f32 v[82:83], v[82:83], v[170:171]
	s_nop 0
	v_addc_co_u32_e32 v159, vcc, 0, v159, vcc
	global_load_dwordx4 v[130:133], v[174:175], off
	global_load_dwordx4 v[170:173], v[158:159], off
	s_waitcnt vmcnt(1)
	v_and_b32_e32 v177, 0xffff0000, v130
	s_waitcnt vmcnt(0)
	v_lshlrev_b32_e32 v169, 16, v170
	v_max_f32_e32 v169, v169, v169
	v_lshlrev_b32_e32 v178, 16, v171
	v_and_b32_e32 v179, 0xffff0000, v171
	v_lshlrev_b32_e32 v171, 16, v172
	v_max_f32_e32 v169, 0xda24260, v169
	v_and_b32_e32 v176, 0xffff0000, v170
	v_rcp_f32_e32 v170, v169
	v_max_f32_e32 v169, v171, v171
	v_max_f32_e32 v169, 0xda24260, v169
	v_and_b32_e32 v180, 0xffff0000, v172
	v_rcp_f32_e32 v172, v169
	v_max_f32_e32 v169, v176, v176
	v_max_f32_e32 v169, 0xda24260, v169
	v_lshlrev_b32_e32 v176, 16, v130
	v_max_f32_e32 v130, v180, v180
	v_rcp_f32_e32 v171, v169
	v_max_f32_e32 v130, 0xda24260, v130
	v_lshlrev_b32_e32 v181, 16, v173
	v_and_b32_e32 v182, 0xffff0000, v173
	v_rcp_f32_e32 v173, v130
	v_max_f32_e32 v130, v178, v178
	v_pk_mul_f32 v[170:171], v[170:171], v[176:177]
	v_lshlrev_b32_e32 v176, 16, v132
	v_and_b32_e32 v177, 0xffff0000, v132
	v_max_f32_e32 v130, 0xda24260, v130
	v_pk_mul_f32 v[172:173], v[172:173], v[176:177]
	v_rcp_f32_e32 v176, v130
	v_max_f32_e32 v130, v181, v181
	v_lshlrev_b32_e32 v180, 16, v131
	v_and_b32_e32 v181, 0xffff0000, v131
	v_max_f32_e32 v131, v182, v182
	v_max_f32_e32 v130, 0xda24260, v130
	v_max_f32_e32 v131, 0xda24260, v131
	v_rcp_f32_e32 v130, v130
	v_rcp_f32_e32 v131, v131
	v_max_f32_e32 v132, v179, v179
	v_max_f32_e32 v132, 0xda24260, v132
	v_rcp_f32_e32 v177, v132
	v_lshlrev_b32_e32 v132, 16, v133
	v_and_b32_e32 v133, 0xffff0000, v133
	v_pk_mul_f32 v[130:131], v[130:131], v[132:133]
	v_pk_mul_f32 v[94:95], v[94:95], v[170:171]
	v_pk_mul_f32 v[92:93], v[92:93], v[130:131]
	v_pk_mul_f32 v[90:91], v[90:91], v[172:173]
	global_load_dwordx4 v[130:133], v[174:175], off offset:256
	global_load_dwordx4 v[170:173], v[158:159], off offset:256
	v_pk_mul_f32 v[176:177], v[176:177], v[180:181]
	s_waitcnt vmcnt(0)
; __device__ __forceinline__ float bflo(unsigned w) { return __uint_as_float(w << 16); }
; __device__ __forceinline__ float bfhi(unsigned w) { return __uint_as_float(w & 0xffff0000u); }
;     __device__ __forceinline__ void mid(f32x4 (&acc)[2][2][4][2], const Unit& u, int wr, int wc, int fr, int fq) const {
;         int row0 = u.pm * BM + wr * 64 + fr; const int col0 = u.pn * BM + wc * 32 + 8 * fq;
;         asm volatile("" : "+v"(row0));
; #pragma unroll
;         for (int ai = 0; ai < 2; ++ai)
; #pragma unroll
;             for (int m = 0; m < 4; ++m) { const bf16_t* pr = P + (size_t)(row0 + ai * HALF + m * 16) * NP + col0;
; #pragma unroll
;                 for (int bj = 0; bj < 2; ++bj) { const u32x4 a = *(const u32x4*)(pr + PC_GA + bj * HALF), b = *(const u32x4*)(pr + PC_GB + bj * HALF);
;                     const f32x4 b0 = {bflo(b.x), bfhi(b.x), bflo(b.y), bfhi(b.y)}, b1 = {bflo(b.z), bfhi(b.z), bflo(b.w), bfhi(b.w)};
;                     const f32x4 a0 = {bflo(a.x), bfhi(a.x), bflo(a.y), bfhi(a.y)}, a1 = {bflo(a.z), bfhi(a.z), bflo(a.w), bfhi(a.w)};
;                     f32x4 r0, r1;
; #pragma unroll
;                     for (int j = 0; j < 4; ++j) { r0[j] = a0[j] * __builtin_amdgcn_rcpf(fmaxf(b0[j], 1e-30f)); r1[j] = a1[j] * __builtin_amdgcn_rcpf(fmaxf(b1[j], 1e-30f)); }
;                     acc[ai][bj][m][0] *= r0; acc[ai][bj][m][1] *= r1; }
;                 asm volatile("" ::: "memory"); }
	v_lshlrev_b32_e32 v158, 16, v170
	v_and_b32_e32 v159, 0xffff0000, v170
	v_lshlrev_b32_e32 v169, 16, v171
	v_and_b32_e32 v174, 0xffff0000, v171
	v_lshlrev_b32_e32 v170, 16, v172
	v_and_b32_e32 v171, 0xffff0000, v172
	v_max_f32_e32 v158, v158, v158
	v_max_f32_e32 v159, v159, v159
	v_pk_mul_f32 v[96:97], v[96:97], v[176:177]
	v_lshlrev_b32_e32 v175, 16, v173
	v_and_b32_e32 v176, 0xffff0000, v173
	v_max_f32_e32 v158, 0xda24260, v158
	v_max_f32_e32 v170, v170, v170
	v_max_f32_e32 v159, 0xda24260, v159
	v_lshlrev_b32_e32 v172, 16, v130
	v_and_b32_e32 v173, 0xffff0000, v130
	v_max_f32_e32 v130, v171, v171
	v_rcp_f32_e32 v158, v158
	v_max_f32_e32 v170, 0xda24260, v170
	v_rcp_f32_e32 v159, v159
	v_max_f32_e32 v130, 0xda24260, v130
	v_rcp_f32_e32 v170, v170
	v_rcp_f32_e32 v171, v130
	v_max_f32_e32 v130, v169, v169
	v_pk_mul_f32 v[158:159], v[158:159], v[172:173]
	v_lshlrev_b32_e32 v172, 16, v132
	v_and_b32_e32 v173, 0xffff0000, v132
	v_max_f32_e32 v130, 0xda24260, v130
	v_pk_mul_f32 v[170:171], v[170:171], v[172:173]
	v_rcp_f32_e32 v172, v130
	v_max_f32_e32 v130, v175, v175
	v_max_f32_e32 v132, v174, v174
	v_lshlrev_b32_e32 v174, 16, v131
	v_and_b32_e32 v175, 0xffff0000, v131
	v_max_f32_e32 v131, v176, v176
	v_max_f32_e32 v130, 0xda24260, v130
	v_max_f32_e32 v131, 0xda24260, v131
	v_rcp_f32_e32 v130, v130
	v_rcp_f32_e32 v131, v131
	v_max_f32_e32 v132, 0xda24260, v132
	v_rcp_f32_e32 v173, v132
	v_lshlrev_b32_e32 v132, 16, v133
	v_and_b32_e32 v133, 0xffff0000, v133
	v_pk_mul_f32 v[130:131], v[130:131], v[132:133]
	v_pk_mul_f32 v[110:111], v[110:111], v[158:159]
	v_pk_mul_f32 v[108:109], v[108:109], v[130:131]
	v_add_u32_e32 v130, 0x80, v168
	v_mad_i64_i32 v[158:159], s[58:59], v130, s78, v[156:157]
	v_pk_mul_f32 v[172:173], v[172:173], v[174:175]
	v_add_co_u32_e32 v174, vcc, s61, v158
	v_pk_mul_f32 v[112:113], v[112:113], v[172:173]
	s_nop 0
	v_addc_co_u32_e32 v175, vcc, 0, v159, vcc
	v_add_co_u32_e32 v158, vcc, s77, v158
	v_pk_mul_f32 v[106:107], v[106:107], v[170:171]
	s_nop 0
	v_addc_co_u32_e32 v159, vcc, 0, v159, vcc
	global_load_dwordx4 v[130:133], v[174:175], off
	global_load_dwordx4 v[170:173], v[158:159], off
	s_waitcnt vmcnt(1)
	v_and_b32_e32 v177, 0xffff0000, v130
	s_waitcnt vmcnt(0)
	v_lshlrev_b32_e32 v169, 16, v170
	v_max_f32_e32 v169, v169, v169
	v_lshlrev_b32_e32 v178, 16, v171
	v_and_b32_e32 v179, 0xffff0000, v171
	v_lshlrev_b32_e32 v171, 16, v172
	v_max_f32_e32 v169, 0xda24260, v169
	v_and_b32_e32 v176, 0xffff0000, v170
	v_rcp_f32_e32 v170, v169
	v_max_f32_e32 v169, v171, v171
	v_max_f32_e32 v169, 0xda24260, v169
	v_and_b32_e32 v180, 0xffff0000, v172
	v_rcp_f32_e32 v172, v169
	v_max_f32_e32 v169, v176, v176
	v_max_f32_e32 v169, 0xda24260, v169
	v_lshlrev_b32_e32 v176, 16, v130
	v_max_f32_e32 v130, v180, v180
	v_rcp_f32_e32 v171, v169
	v_max_f32_e32 v130, 0xda24260, v130
	v_lshlrev_b32_e32 v181, 16, v173
	v_and_b32_e32 v182, 0xffff0000, v173
	v_rcp_f32_e32 v173, v130
	v_max_f32_e32 v130, v178, v178
	v_pk_mul_f32 v[170:171], v[170:171], v[176:177]
	v_lshlrev_b32_e32 v176, 16, v132
	v_and_b32_e32 v177, 0xffff0000, v132
	v_max_f32_e32 v130, 0xda24260, v130
	v_pk_mul_f32 v[172:173], v[172:173], v[176:177]
	v_rcp_f32_e32 v176, v130
	v_max_f32_e32 v130, v181, v181
	v_lshlrev_b32_e32 v180, 16, v131
	v_and_b32_e32 v181, 0xffff0000, v131
	v_max_f32_e32 v131, v182, v182
	v_max_f32_e32 v130, 0xda24260, v130
	v_max_f32_e32 v131, 0xda24260, v131
	v_rcp_f32_e32 v130, v130
	v_rcp_f32_e32 v131, v131
	v_max_f32_e32 v132, v179, v179
	v_max_f32_e32 v132, 0xda24260, v132
	v_rcp_f32_e32 v177, v132
	v_lshlrev_b32_e32 v132, 16, v133
	v_and_b32_e32 v133, 0xffff0000, v133
	v_pk_mul_f32 v[130:131], v[130:131], v[132:133]
	v_pk_mul_f32 v[126:127], v[126:127], v[170:171]
	v_pk_mul_f32 v[124:125], v[124:125], v[130:131]
	v_pk_mul_f32 v[122:123], v[122:123], v[172:173]
	global_load_dwordx4 v[130:133], v[174:175], off offset:256
	global_load_dwordx4 v[170:173], v[158:159], off offset:256
	v_pk_mul_f32 v[176:177], v[176:177], v[180:181]
	s_waitcnt vmcnt(0)
	v_lshlrev_b32_e32 v158, 16, v170
	v_and_b32_e32 v159, 0xffff0000, v170
	v_lshlrev_b32_e32 v169, 16, v171
	v_and_b32_e32 v174, 0xffff0000, v171
	v_lshlrev_b32_e32 v170, 16, v172
	v_and_b32_e32 v171, 0xffff0000, v172
	v_max_f32_e32 v158, v158, v158
	v_max_f32_e32 v159, v159, v159
	v_pk_mul_f32 v[128:129], v[128:129], v[176:177]
	v_lshlrev_b32_e32 v175, 16, v173
	v_and_b32_e32 v176, 0xffff0000, v173
	v_max_f32_e32 v158, 0xda24260, v158
	v_max_f32_e32 v170, v170, v170
	v_max_f32_e32 v159, 0xda24260, v159
	v_lshlrev_b32_e32 v172, 16, v130
	v_and_b32_e32 v173, 0xffff0000, v130
	v_max_f32_e32 v130, v171, v171
	v_rcp_f32_e32 v158, v158
	v_max_f32_e32 v170, 0xda24260, v170
	v_rcp_f32_e32 v159, v159
	v_max_f32_e32 v130, 0xda24260, v130
	v_rcp_f32_e32 v170, v170
	v_rcp_f32_e32 v171, v130
	v_max_f32_e32 v130, v169, v169
	v_pk_mul_f32 v[158:159], v[158:159], v[172:173]
	v_lshlrev_b32_e32 v172, 16, v132
	v_and_b32_e32 v173, 0xffff0000, v132
	v_max_f32_e32 v130, 0xda24260, v130
	v_pk_mul_f32 v[170:171], v[170:171], v[172:173]
	v_rcp_f32_e32 v172, v130
	v_max_f32_e32 v130, v175, v175
	v_max_f32_e32 v132, v174, v174
	v_lshlrev_b32_e32 v174, 16, v131
	v_and_b32_e32 v175, 0xffff0000, v131
	v_max_f32_e32 v131, v176, v176
	v_max_f32_e32 v130, 0xda24260, v130
	v_max_f32_e32 v131, 0xda24260, v131
	v_rcp_f32_e32 v130, v130
	v_rcp_f32_e32 v131, v131
	v_max_f32_e32 v132, 0xda24260, v132
	v_rcp_f32_e32 v173, v132
	v_lshlrev_b32_e32 v132, 16, v133
	v_and_b32_e32 v133, 0xffff0000, v133
	v_pk_mul_f32 v[130:131], v[130:131], v[132:133]
	v_pk_mul_f32 v[118:119], v[118:119], v[158:159]
	v_pk_mul_f32 v[116:117], v[116:117], v[130:131]
	v_add_u32_e32 v130, 0x90, v168
	v_mad_i64_i32 v[158:159], s[58:59], v130, s78, v[156:157]
	v_pk_mul_f32 v[172:173], v[172:173], v[174:175]
	v_add_co_u32_e32 v174, vcc, s61, v158
	v_pk_mul_f32 v[120:121], v[120:121], v[172:173]
	s_nop 0
	v_addc_co_u32_e32 v175, vcc, 0, v159, vcc
	v_add_co_u32_e32 v158, vcc, s77, v158
	v_pk_mul_f32 v[114:115], v[114:115], v[170:171]
	s_nop 0
	v_addc_co_u32_e32 v159, vcc, 0, v159, vcc
	global_load_dwordx4 v[130:133], v[174:175], off
	global_load_dwordx4 v[170:173], v[158:159], off
	s_waitcnt vmcnt(1)
; __device__ __forceinline__ float bflo(unsigned w) { return __uint_as_float(w << 16); }
; __device__ __forceinline__ float bfhi(unsigned w) { return __uint_as_float(w & 0xffff0000u); }
;     __device__ __forceinline__ void mid(f32x4 (&acc)[2][2][4][2], const Unit& u, int wr, int wc, int fr, int fq) const {
;         int row0 = u.pm * BM + wr * 64 + fr; const int col0 = u.pn * BM + wc * 32 + 8 * fq;
;         asm volatile("" : "+v"(row0));
; #pragma unroll
;         for (int ai = 0; ai < 2; ++ai)
; #pragma unroll
;             for (int m = 0; m < 4; ++m) { const bf16_t* pr = P + (size_t)(row0 + ai * HALF + m * 16) * NP + col0;
; #pragma unroll
;                 for (int bj = 0; bj < 2; ++bj) { const u32x4 a = *(const u32x4*)(pr + PC_GA + bj * HALF), b = *(const u32x4*)(pr + PC_GB + bj * HALF);
;                     const f32x4 b0 = {bflo(b.x), bfhi(b.x), bflo(b.y), bfhi(b.y)}, b1 = {bflo(b.z), bfhi(b.z), bflo(b.w), bfhi(b.w)};
;                     const f32x4 a0 = {bflo(a.x), bfhi(a.x), bflo(a.y), bfhi(a.y)}, a1 = {bflo(a.z), bfhi(a.z), bflo(a.w), bfhi(a.w)};
;                     f32x4 r0, r1;
; #pragma unroll
;                     for (int j = 0; j < 4; ++j) { r0[j] = a0[j] * __builtin_amdgcn_rcpf(fmaxf(b0[j], 1e-30f)); r1[j] = a1[j] * __builtin_amdgcn_rcpf(fmaxf(b1[j], 1e-30f)); }
;                     acc[ai][bj][m][0] *= r0; acc[ai][bj][m][1] *= r1; }
;                 asm volatile("" ::: "memory"); }
	v_and_b32_e32 v177, 0xffff0000, v130
	s_waitcnt vmcnt(0)
	v_lshlrev_b32_e32 v169, 16, v170
	v_max_f32_e32 v169, v169, v169
	v_lshlrev_b32_e32 v178, 16, v171
	v_and_b32_e32 v179, 0xffff0000, v171
	v_lshlrev_b32_e32 v171, 16, v172
	v_max_f32_e32 v169, 0xda24260, v169
	v_and_b32_e32 v176, 0xffff0000, v170
	v_rcp_f32_e32 v170, v169
	v_max_f32_e32 v169, v171, v171
	v_max_f32_e32 v169, 0xda24260, v169
	v_and_b32_e32 v180, 0xffff0000, v172
	v_rcp_f32_e32 v172, v169
	v_max_f32_e32 v169, v176, v176
	v_max_f32_e32 v169, 0xda24260, v169
	v_lshlrev_b32_e32 v176, 16, v130
	v_max_f32_e32 v130, v180, v180
	v_rcp_f32_e32 v171, v169
	v_max_f32_e32 v130, 0xda24260, v130
	v_lshlrev_b32_e32 v181, 16, v173
	v_and_b32_e32 v182, 0xffff0000, v173
	v_rcp_f32_e32 v173, v130
	v_max_f32_e32 v130, v178, v178
	v_pk_mul_f32 v[170:171], v[170:171], v[176:177]
	v_lshlrev_b32_e32 v176, 16, v132
	v_and_b32_e32 v177, 0xffff0000, v132
	v_max_f32_e32 v130, 0xda24260, v130
	v_pk_mul_f32 v[172:173], v[172:173], v[176:177]
	v_rcp_f32_e32 v176, v130
	v_max_f32_e32 v130, v181, v181
	v_lshlrev_b32_e32 v180, 16, v131
	v_and_b32_e32 v181, 0xffff0000, v131
	v_max_f32_e32 v131, v182, v182
	v_max_f32_e32 v130, 0xda24260, v130
	v_max_f32_e32 v131, 0xda24260, v131
	v_rcp_f32_e32 v130, v130
	v_rcp_f32_e32 v131, v131
	v_max_f32_e32 v132, v179, v179
	v_max_f32_e32 v132, 0xda24260, v132
	v_rcp_f32_e32 v177, v132
	v_lshlrev_b32_e32 v132, 16, v133
	v_and_b32_e32 v133, 0xffff0000, v133
	v_pk_mul_f32 v[130:131], v[130:131], v[132:133]
	v_pk_mul_f32 v[102:103], v[102:103], v[170:171]
	v_pk_mul_f32 v[100:101], v[100:101], v[130:131]
	v_pk_mul_f32 v[98:99], v[98:99], v[172:173]
	global_load_dwordx4 v[130:133], v[174:175], off offset:256
	global_load_dwordx4 v[170:173], v[158:159], off offset:256
	v_pk_mul_f32 v[176:177], v[176:177], v[180:181]
	s_waitcnt vmcnt(0)
	v_lshlrev_b32_e32 v158, 16, v170
	v_and_b32_e32 v159, 0xffff0000, v170
	v_lshlrev_b32_e32 v169, 16, v171
	v_and_b32_e32 v174, 0xffff0000, v171
	v_lshlrev_b32_e32 v170, 16, v172
	v_and_b32_e32 v171, 0xffff0000, v172
	v_max_f32_e32 v158, v158, v158
	v_max_f32_e32 v159, v159, v159
	v_pk_mul_f32 v[104:105], v[104:105], v[176:177]
	v_lshlrev_b32_e32 v175, 16, v173
	v_and_b32_e32 v176, 0xffff0000, v173
	v_max_f32_e32 v158, 0xda24260, v158
	v_max_f32_e32 v170, v170, v170
	v_max_f32_e32 v159, 0xda24260, v159
	v_lshlrev_b32_e32 v172, 16, v130
	v_and_b32_e32 v173, 0xffff0000, v130
	v_max_f32_e32 v130, v171, v171
	v_rcp_f32_e32 v158, v158
	v_max_f32_e32 v170, 0xda24260, v170
	v_rcp_f32_e32 v159, v159
	v_max_f32_e32 v130, 0xda24260, v130
	v_rcp_f32_e32 v170, v170
	v_rcp_f32_e32 v171, v130
	v_max_f32_e32 v130, v169, v169
	v_pk_mul_f32 v[158:159], v[158:159], v[172:173]
	v_lshlrev_b32_e32 v172, 16, v132
	v_and_b32_e32 v173, 0xffff0000, v132
	v_max_f32_e32 v130, 0xda24260, v130
	v_pk_mul_f32 v[170:171], v[170:171], v[172:173]
	v_rcp_f32_e32 v172, v130
	v_max_f32_e32 v130, v175, v175
	v_max_f32_e32 v132, v174, v174
	v_lshlrev_b32_e32 v174, 16, v131
	v_and_b32_e32 v175, 0xffff0000, v131
	v_max_f32_e32 v131, v176, v176
	v_max_f32_e32 v130, 0xda24260, v130
	v_max_f32_e32 v131, 0xda24260, v131
	v_rcp_f32_e32 v130, v130
	v_rcp_f32_e32 v131, v131
	v_max_f32_e32 v132, 0xda24260, v132
	v_rcp_f32_e32 v173, v132
	v_lshlrev_b32_e32 v132, 16, v133
	v_and_b32_e32 v133, 0xffff0000, v133
	v_pk_mul_f32 v[130:131], v[130:131], v[132:133]
	v_pk_mul_f32 v[78:79], v[78:79], v[158:159]
	v_pk_mul_f32 v[76:77], v[76:77], v[130:131]
	v_add_u32_e32 v130, 0xa0, v168
	v_mad_i64_i32 v[158:159], s[58:59], v130, s78, v[156:157]
	v_pk_mul_f32 v[172:173], v[172:173], v[174:175]
	v_add_co_u32_e32 v174, vcc, s61, v158
	v_pk_mul_f32 v[80:81], v[80:81], v[172:173]
	s_nop 0
	v_addc_co_u32_e32 v175, vcc, 0, v159, vcc
	v_add_co_u32_e32 v158, vcc, s77, v158
	v_pk_mul_f32 v[74:75], v[74:75], v[170:171]
	s_nop 0
	v_addc_co_u32_e32 v159, vcc, 0, v159, vcc
	global_load_dwordx4 v[130:133], v[174:175], off
	global_load_dwordx4 v[170:173], v[158:159], off
	s_waitcnt vmcnt(1)
	v_and_b32_e32 v177, 0xffff0000, v130
	s_waitcnt vmcnt(0)
	v_lshlrev_b32_e32 v169, 16, v170
	v_max_f32_e32 v169, v169, v169
	v_lshlrev_b32_e32 v178, 16, v171
	v_and_b32_e32 v179, 0xffff0000, v171
	v_lshlrev_b32_e32 v171, 16, v172
	v_max_f32_e32 v169, 0xda24260, v169
	v_and_b32_e32 v176, 0xffff0000, v170
	v_rcp_f32_e32 v170, v169
	v_max_f32_e32 v169, v171, v171
	v_max_f32_e32 v169, 0xda24260, v169
	v_and_b32_e32 v180, 0xffff0000, v172
	v_rcp_f32_e32 v172, v169
	v_max_f32_e32 v169, v176, v176
	v_max_f32_e32 v169, 0xda24260, v169
	v_lshlrev_b32_e32 v176, 16, v130
	v_max_f32_e32 v130, v180, v180
	v_rcp_f32_e32 v171, v169
	v_max_f32_e32 v130, 0xda24260, v130
	v_lshlrev_b32_e32 v181, 16, v173
	v_and_b32_e32 v182, 0xffff0000, v173
	v_rcp_f32_e32 v173, v130
	v_max_f32_e32 v130, v178, v178
	v_pk_mul_f32 v[170:171], v[170:171], v[176:177]
	v_lshlrev_b32_e32 v176, 16, v132
	v_and_b32_e32 v177, 0xffff0000, v132
	v_max_f32_e32 v130, 0xda24260, v130
	v_pk_mul_f32 v[172:173], v[172:173], v[176:177]
	v_rcp_f32_e32 v176, v130
	v_max_f32_e32 v130, v181, v181
	v_lshlrev_b32_e32 v180, 16, v131
	v_and_b32_e32 v181, 0xffff0000, v131
	v_max_f32_e32 v131, v182, v182
	v_max_f32_e32 v130, 0xda24260, v130
	v_max_f32_e32 v131, 0xda24260, v131
	v_rcp_f32_e32 v130, v130
	v_rcp_f32_e32 v131, v131
	v_max_f32_e32 v132, v179, v179
	v_max_f32_e32 v132, 0xda24260, v132
	v_rcp_f32_e32 v177, v132
	v_lshlrev_b32_e32 v132, 16, v133
	v_and_b32_e32 v133, 0xffff0000, v133
	v_pk_mul_f32 v[130:131], v[130:131], v[132:133]
	v_pk_mul_f32 v[62:63], v[62:63], v[170:171]
	v_pk_mul_f32 v[60:61], v[60:61], v[130:131]
	v_pk_mul_f32 v[58:59], v[58:59], v[172:173]
	global_load_dwordx4 v[130:133], v[174:175], off offset:256
	global_load_dwordx4 v[170:173], v[158:159], off offset:256
	v_pk_mul_f32 v[176:177], v[176:177], v[180:181]
	s_waitcnt vmcnt(0)
; __device__ __forceinline__ float bflo(unsigned w) { return __uint_as_float(w << 16); }
; __device__ __forceinline__ float bfhi(unsigned w) { return __uint_as_float(w & 0xffff0000u); }
;     __device__ __forceinline__ void mid(f32x4 (&acc)[2][2][4][2], const Unit& u, int wr, int wc, int fr, int fq) const {
;         int row0 = u.pm * BM + wr * 64 + fr; const int col0 = u.pn * BM + wc * 32 + 8 * fq;
;         asm volatile("" : "+v"(row0));
; #pragma unroll
;         for (int ai = 0; ai < 2; ++ai)
; #pragma unroll
;             for (int m = 0; m < 4; ++m) { const bf16_t* pr = P + (size_t)(row0 + ai * HALF + m * 16) * NP + col0;
; #pragma unroll
;                 for (int bj = 0; bj < 2; ++bj) { const u32x4 a = *(const u32x4*)(pr + PC_GA + bj * HALF), b = *(const u32x4*)(pr + PC_GB + bj * HALF);
;                     const f32x4 b0 = {bflo(b.x), bfhi(b.x), bflo(b.y), bfhi(b.y)}, b1 = {bflo(b.z), bfhi(b.z), bflo(b.w), bfhi(b.w)};
;                     const f32x4 a0 = {bflo(a.x), bfhi(a.x), bflo(a.y), bfhi(a.y)}, a1 = {bflo(a.z), bfhi(a.z), bflo(a.w), bfhi(a.w)};
;                     f32x4 r0, r1;
; #pragma unroll
;                     for (int j = 0; j < 4; ++j) { r0[j] = a0[j] * __builtin_amdgcn_rcpf(fmaxf(b0[j], 1e-30f)); r1[j] = a1[j] * __builtin_amdgcn_rcpf(fmaxf(b1[j], 1e-30f)); }
;                     acc[ai][bj][m][0] *= r0; acc[ai][bj][m][1] *= r1; }
;                 asm volatile("" ::: "memory"); }
	v_lshlrev_b32_e32 v158, 16, v170
	v_and_b32_e32 v159, 0xffff0000, v170
	v_lshlrev_b32_e32 v169, 16, v171
	v_and_b32_e32 v174, 0xffff0000, v171
	v_lshlrev_b32_e32 v170, 16, v172
	v_and_b32_e32 v171, 0xffff0000, v172
	v_max_f32_e32 v158, v158, v158
	v_max_f32_e32 v159, v159, v159
	v_pk_mul_f32 v[64:65], v[64:65], v[176:177]
	v_lshlrev_b32_e32 v175, 16, v173
	v_and_b32_e32 v176, 0xffff0000, v173
	v_max_f32_e32 v158, 0xda24260, v158
	v_max_f32_e32 v170, v170, v170
	v_max_f32_e32 v159, 0xda24260, v159
	v_lshlrev_b32_e32 v172, 16, v130
	v_and_b32_e32 v173, 0xffff0000, v130
	v_max_f32_e32 v130, v171, v171
	v_rcp_f32_e32 v158, v158
	v_max_f32_e32 v170, 0xda24260, v170
	v_rcp_f32_e32 v159, v159
	v_max_f32_e32 v130, 0xda24260, v130
	v_rcp_f32_e32 v170, v170
	v_rcp_f32_e32 v171, v130
	v_max_f32_e32 v130, v169, v169
	v_pk_mul_f32 v[158:159], v[158:159], v[172:173]
	v_lshlrev_b32_e32 v172, 16, v132
	v_and_b32_e32 v173, 0xffff0000, v132
	v_max_f32_e32 v130, 0xda24260, v130
	v_pk_mul_f32 v[170:171], v[170:171], v[172:173]
	v_rcp_f32_e32 v172, v130
	v_max_f32_e32 v130, v175, v175
	v_max_f32_e32 v132, v174, v174
	v_lshlrev_b32_e32 v174, 16, v131
	v_and_b32_e32 v175, 0xffff0000, v131
	v_max_f32_e32 v131, v176, v176
	v_max_f32_e32 v130, 0xda24260, v130
	v_max_f32_e32 v131, 0xda24260, v131
	v_rcp_f32_e32 v130, v130
	v_rcp_f32_e32 v131, v131
	v_max_f32_e32 v132, 0xda24260, v132
	v_rcp_f32_e32 v173, v132
	v_lshlrev_b32_e32 v132, 16, v133
	v_and_b32_e32 v133, 0xffff0000, v133
	v_pk_mul_f32 v[130:131], v[130:131], v[132:133]
	v_pk_mul_f32 v[46:47], v[46:47], v[158:159]
	v_pk_mul_f32 v[44:45], v[44:45], v[130:131]
	v_add_u32_e32 v130, 0xb0, v168
	v_mad_i64_i32 v[156:157], s[58:59], v130, s78, v[156:157]
	v_add_co_u32_e32 v158, vcc, s61, v156
	v_pk_mul_f32 v[42:43], v[42:43], v[170:171]
	s_nop 0
	v_addc_co_u32_e32 v159, vcc, 0, v157, vcc
	v_add_co_u32_e32 v156, vcc, s77, v156
	global_load_dwordx4 v[130:133], v[158:159], off
	s_nop 0
	v_addc_co_u32_e32 v157, vcc, 0, v157, vcc
	global_load_dwordx4 v[168:171], v[156:157], off
	v_pk_mul_f32 v[172:173], v[172:173], v[174:175]
	s_waitcnt vmcnt(0)
	v_lshlrev_b32_e32 v174, 16, v169
	v_and_b32_e32 v175, 0xffff0000, v169
	v_lshlrev_b32_e32 v169, 16, v170
	v_max_f32_e32 v169, v169, v169
	v_pk_mul_f32 v[48:49], v[48:49], v[172:173]
	v_lshlrev_b32_e32 v172, 16, v168
	v_and_b32_e32 v173, 0xffff0000, v168
	v_max_f32_e32 v169, 0xda24260, v169
	v_and_b32_e32 v176, 0xffff0000, v170
	v_max_f32_e32 v168, v172, v172
	v_rcp_f32_e32 v170, v169
	v_max_f32_e32 v169, v173, v173
	v_max_f32_e32 v168, 0xda24260, v168
	v_max_f32_e32 v169, 0xda24260, v169
	v_lshlrev_b32_e32 v172, 16, v130
	v_and_b32_e32 v173, 0xffff0000, v130
	v_max_f32_e32 v130, v176, v176
	v_rcp_f32_e32 v168, v168
	v_rcp_f32_e32 v169, v169
	v_max_f32_e32 v130, 0xda24260, v130
	v_lshlrev_b32_e32 v177, 16, v171
	v_and_b32_e32 v178, 0xffff0000, v171
	v_rcp_f32_e32 v171, v130
	v_max_f32_e32 v130, v174, v174
	v_pk_mul_f32 v[168:169], v[168:169], v[172:173]
	v_lshlrev_b32_e32 v172, 16, v132
	v_and_b32_e32 v173, 0xffff0000, v132
	v_max_f32_e32 v130, 0xda24260, v130
	v_pk_mul_f32 v[170:171], v[170:171], v[172:173]
	v_rcp_f32_e32 v172, v130
	v_max_f32_e32 v130, v177, v177
	v_max_f32_e32 v132, v175, v175
	v_lshlrev_b32_e32 v174, 16, v131
	v_and_b32_e32 v175, 0xffff0000, v131
	v_max_f32_e32 v131, v178, v178
	v_max_f32_e32 v130, 0xda24260, v130
	v_max_f32_e32 v131, 0xda24260, v131
	v_rcp_f32_e32 v130, v130
	v_rcp_f32_e32 v131, v131
	v_max_f32_e32 v132, 0xda24260, v132
	v_rcp_f32_e32 v173, v132
	v_lshlrev_b32_e32 v132, 16, v133
	v_and_b32_e32 v133, 0xffff0000, v133
	v_pk_mul_f32 v[130:131], v[130:131], v[132:133]
	v_pk_mul_f32 v[18:19], v[18:19], v[170:171]
	v_pk_mul_f32 v[20:21], v[20:21], v[130:131]
	global_load_dwordx4 v[130:133], v[158:159], off offset:256
	s_nop 0
	global_load_dwordx4 v[156:159], v[156:157], off offset:256
	v_pk_mul_f32 v[172:173], v[172:173], v[174:175]
	v_pk_mul_f32 v[22:23], v[22:23], v[168:169]
	v_pk_mul_f32 v[24:25], v[24:25], v[172:173]
	s_waitcnt vmcnt(0)
	v_lshlrev_b32_e32 v170, 16, v157
	v_and_b32_e32 v171, 0xffff0000, v157
	v_lshlrev_b32_e32 v157, 16, v158
	v_max_f32_e32 v157, v157, v157
	v_lshlrev_b32_e32 v168, 16, v156
	v_and_b32_e32 v169, 0xffff0000, v156
	v_max_f32_e32 v157, 0xda24260, v157
	v_and_b32_e32 v172, 0xffff0000, v158
	v_max_f32_e32 v156, v168, v168
	v_rcp_f32_e32 v158, v157
	v_max_f32_e32 v157, v169, v169
	v_max_f32_e32 v156, 0xda24260, v156
	v_max_f32_e32 v157, 0xda24260, v157
	v_lshlrev_b32_e32 v168, 16, v130
	v_and_b32_e32 v169, 0xffff0000, v130
	v_max_f32_e32 v130, v172, v172
	v_rcp_f32_e32 v156, v156
	v_rcp_f32_e32 v157, v157
	v_max_f32_e32 v130, 0xda24260, v130
	v_lshlrev_b32_e32 v173, 16, v159
	v_and_b32_e32 v174, 0xffff0000, v159
	v_rcp_f32_e32 v159, v130
	v_max_f32_e32 v130, v170, v170
	v_pk_mul_f32 v[156:157], v[156:157], v[168:169]
	v_lshlrev_b32_e32 v168, 16, v132
	v_and_b32_e32 v169, 0xffff0000, v132
	v_max_f32_e32 v130, 0xda24260, v130
	v_pk_mul_f32 v[158:159], v[158:159], v[168:169]
	v_rcp_f32_e32 v168, v130
	v_max_f32_e32 v130, v173, v173
	v_max_f32_e32 v132, v171, v171
	v_lshlrev_b32_e32 v170, 16, v131
	v_and_b32_e32 v171, 0xffff0000, v131
	v_max_f32_e32 v131, v174, v174
	v_max_f32_e32 v130, 0xda24260, v130
	v_max_f32_e32 v132, 0xda24260, v132
	v_max_f32_e32 v131, 0xda24260, v131
	v_rcp_f32_e32 v130, v130
	v_rcp_f32_e32 v169, v132
	v_rcp_f32_e32 v131, v131
	v_lshlrev_b32_e32 v132, 16, v133
	v_and_b32_e32 v133, 0xffff0000, v133
	v_pk_mul_f32 v[168:169], v[168:169], v[170:171]
	v_pk_mul_f32 v[130:131], v[130:131], v[132:133]
	v_pk_mul_f32 v[8:9], v[8:9], v[168:169]
	v_pk_mul_f32 v[6:7], v[6:7], v[156:157]
	v_pk_mul_f32 v[4:5], v[4:5], v[130:131]
	v_pk_mul_f32 v[2:3], v[2:3], v[158:159]
; #define PG8_STAGE(bufoff, gbase, voff) do { _Pragma("unroll") for (int _i = 0; _i < 2; ++_i) \
;         __builtin_amdgcn_global_load_lds((const unsigned*)((const char*)(gbase) + (voff)[_i]), (PG8_LAS unsigned*)(lds + (bufoff) + ldsw + _i * 8192), 16, 0, 0); } while (0)
; #define PG8_LDA(dst, b, h) do { _Pragma("unroll") for (int m = 0; m < 4; ++m) _Pragma("unroll") for (int k = 0; k < 2; ++k) dst[m][k] = *(const PG8_LAS bf16x8*)(lds + PG8_SA(b, h) + aoff + m * 2048 + k * 1024); } while (0)
; #define PG8_LDB(dst, b, h) do { _Pragma("unroll") for (int n = 0; n < 2; ++n) _Pragma("unroll") for (int k = 0; k < 2; ++k) dst[n][k] = *(const PG8_LAS bf16x8*)(lds + PG8_SB(b, h) + boff + n * 2048 + k * 1024); } while (0)
; template <class Epi, class Sched, bool ALIGN_EPI = false, bool SP2 = false>
; __device__ __forceinline__ void gemm_phase(PG8_LAS unsigned char* lds, const Gemm g, const Sched& S, const Epi& E) {
;     ...
;         for (; t < tend; t += 2) {
;             const bool last = (t == nt - 2);
;             const char* a1 = cA + (size_t)(t + 1) * kstep;
;             const char* a2 = last ? nA : cA + (size_t)(t + 2) * kstep; const char* b2 = last ? nB : cB + (size_t)(t + 2) * kstep;
;             const char* a3 = a2 + kstep; const char* b3 = b2 + kstep;
;             if (last && has_next) S.a_ready(nxt);
;             if constexpr (SP2) {
;             PG8_LDB(B0, 0, 0); PG8_LDB(B1, 0, 1); PG8_SCHED; PG8_LDA(At, 0, 0); PG8_STAGE(PG8_SA(1, 1), a1 + hstep, voffA);
;             PG8_WAIT_V(8); PG8_WAIT_L(0); PG8_BAR; PG8_MMA(0, 0, At, B0); PG8_MMA(0, 1, At, B1); PG8_BAR; PG8_SCHED;
;             PG8_LDA(At, 0, 1); PG8_STAGE(PG8_SB(0, 0), b2, voffB); PG8_STAGE(PG8_SB(0, 1), b2 + hstep, voffB); PG8_STAGE(PG8_SA(0, 0), a2, voffA);
;             PG8_WAIT_V(8); PG8_WAIT_L(0); PG8_BAR; PG8_MMA(1, 0, At, B0); PG8_MMA(1, 1, At, B1); PG8_BAR; PG8_SCHED;
;             PG8_LDB(B0, 1, 0); PG8_LDB(B1, 1, 1); PG8_SCHED; PG8_LDA(At, 1, 0); PG8_STAGE(PG8_SA(0, 1), a2 + hstep, voffA);
;             PG8_WAIT_V(8); PG8_WAIT_L(0); PG8_BAR; PG8_MMA(0, 0, At, B0); PG8_MMA(0, 1, At, B1); PG8_BAR; PG8_SCHED;
;             PG8_LDA(At, 1, 1); PG8_STAGE(PG8_SB(1, 0), b3, voffB); PG8_STAGE(PG8_SB(1, 1), b3 + hstep, voffB); PG8_STAGE(PG8_SA(1, 0), a3, voffA);
;             PG8_WAIT_V(8); PG8_WAIT_L(0); PG8_BAR; PG8_MMA(1, 0, At, B0); PG8_MMA(1, 1, At, B1); PG8_BAR; PG8_SCHED;
.LBB0_684:
	ds_read_b128 v[130:133], v163
	ds_read_b128 v[156:159], v163 offset:1024
	ds_read_b128 v[168:171], v163 offset:2048
	ds_read_b128 v[172:175], v163 offset:3072
	ds_read_b128 v[180:183], v164
	ds_read_b128 v[184:187], v164 offset:1024
	ds_read_b128 v[188:191], v164 offset:2048
	ds_read_b128 v[198:201], v164 offset:3072
	s_add_u32 s48, s50, 0x4000
	s_addc_u32 s49, s51, 0
	s_cmp_eq_u32 s56, 60
	s_cselect_b32 s72, s93, s48
	s_cselect_b32 s73, s41, s49
	s_cselect_b32 s70, s97, s26
	s_cselect_b32 s71, s27, s33
	s_add_u32 s48, s72, 0x8000
	s_addc_u32 s49, s73, 0
	s_mov_b32 m0, s83
	ds_read_b128 v[202:205], v165
	ds_read_b128 v[206:209], v165 offset:1024
	ds_read_b128 v[210:213], v165 offset:2048
	ds_read_b128 v[214:217], v165 offset:3072
	ds_read_b128 v[218:221], v165 offset:4096
	ds_read_b128 v[222:225], v165 offset:5120
	ds_read_b128 v[226:229], v165 offset:6144
	ds_read_b128 v[230:233], v165 offset:7168
	global_load_lds_dwordx4 v144, s[50:51]
	s_mov_b32 m0, s84
	s_nop 0
	global_load_lds_dwordx4 v146, s[50:51]
	s_waitcnt vmcnt(8)
	s_waitcnt lgkmcnt(0)
	s_barrier
	s_waitcnt lgkmcnt(0)
	v_mfma_f32_16x16x32_bf16 v[14:17], v[130:133], v[202:205], v[14:17]
	v_mfma_f32_16x16x32_bf16 v[14:17], v[156:159], v[206:209], v[14:17]
	v_mfma_f32_16x16x32_bf16 v[38:41], v[130:133], v[210:213], v[38:41]
	v_mfma_f32_16x16x32_bf16 v[38:41], v[156:159], v[214:217], v[38:41]
	v_mfma_f32_16x16x32_bf16 v[70:73], v[130:133], v[218:221], v[70:73]
	v_mfma_f32_16x16x32_bf16 v[70:73], v[156:159], v[222:225], v[70:73]
	v_mfma_f32_16x16x32_bf16 v[94:97], v[130:133], v[226:229], v[94:97]
	v_mfma_f32_16x16x32_bf16 v[94:97], v[156:159], v[230:233], v[94:97]
	v_mfma_f32_16x16x32_bf16 v[90:93], v[168:171], v[226:229], v[90:93]
	v_mfma_f32_16x16x32_bf16 v[90:93], v[172:175], v[230:233], v[90:93]
	v_mfma_f32_16x16x32_bf16 v[66:69], v[168:171], v[218:221], v[66:69]
	v_mfma_f32_16x16x32_bf16 v[66:69], v[172:175], v[222:225], v[66:69]
	v_mfma_f32_16x16x32_bf16 v[34:37], v[168:171], v[210:213], v[34:37]
	v_mfma_f32_16x16x32_bf16 v[34:37], v[172:175], v[214:217], v[34:37]
	v_mfma_f32_16x16x32_bf16 v[10:13], v[168:171], v[202:205], v[10:13]
	v_mfma_f32_16x16x32_bf16 v[10:13], v[172:175], v[206:209], v[10:13]
	v_mfma_f32_16x16x32_bf16 v[30:33], v[180:183], v[202:205], v[30:33]
	v_mfma_f32_16x16x32_bf16 v[30:33], v[184:187], v[206:209], v[30:33]
	v_mfma_f32_16x16x32_bf16 v[54:57], v[180:183], v[210:213], v[54:57]
	v_mfma_f32_16x16x32_bf16 v[54:57], v[184:187], v[214:217], v[54:57]
	v_mfma_f32_16x16x32_bf16 v[86:89], v[180:183], v[218:221], v[86:89]
	v_mfma_f32_16x16x32_bf16 v[86:89], v[184:187], v[222:225], v[86:89]
	v_mfma_f32_16x16x32_bf16 v[110:113], v[180:183], v[226:229], v[110:113]
	v_mfma_f32_16x16x32_bf16 v[110:113], v[184:187], v[230:233], v[110:113]
	v_mfma_f32_16x16x32_bf16 v[106:109], v[188:191], v[226:229], v[106:109]
	v_mfma_f32_16x16x32_bf16 v[106:109], v[198:201], v[230:233], v[106:109]
	v_mfma_f32_16x16x32_bf16 v[82:85], v[188:191], v[218:221], v[82:85]
	v_mfma_f32_16x16x32_bf16 v[82:85], v[198:201], v[222:225], v[82:85]
	v_mfma_f32_16x16x32_bf16 v[50:53], v[188:191], v[210:213], v[50:53]
	v_mfma_f32_16x16x32_bf16 v[50:53], v[198:201], v[214:217], v[50:53]
	v_mfma_f32_16x16x32_bf16 v[26:29], v[188:191], v[202:205], v[26:29]
	v_mfma_f32_16x16x32_bf16 v[26:29], v[198:201], v[206:209], v[26:29]
	s_barrier
	s_mov_b32 m0, s85
	s_add_u32 s58, s70, 0x4000
	ds_read_b128 v[202:205], v165 offset:16384
	ds_read_b128 v[206:209], v165 offset:17408
	ds_read_b128 v[210:213], v165 offset:18432
	ds_read_b128 v[214:217], v165 offset:19456
	ds_read_b128 v[218:221], v165 offset:20480
	ds_read_b128 v[222:225], v165 offset:21504
	ds_read_b128 v[226:229], v165 offset:22528
	ds_read_b128 v[230:233], v165 offset:23552
	global_load_lds_dwordx4 v136, s[70:71]
	s_mov_b32 m0, s86
	s_addc_u32 s59, s71, 0
	global_load_lds_dwordx4 v140, s[70:71]
	s_mov_b32 m0, s87
	s_nop 0
	global_load_lds_dwordx4 v136, s[58:59]
	s_mov_b32 m0, s88
	s_nop 0
	global_load_lds_dwordx4 v140, s[58:59]
	s_mov_b32 m0, s29
	s_nop 0
	global_load_lds_dwordx4 v134, s[72:73]
	s_mov_b32 m0, s30
	s_nop 0
	global_load_lds_dwordx4 v138, s[72:73]
	s_waitcnt vmcnt(8)
	s_waitcnt lgkmcnt(0)
	s_barrier
	s_waitcnt lgkmcnt(0)
	v_mfma_f32_16x16x32_bf16 v[126:129], v[130:133], v[202:205], v[126:129]
	v_mfma_f32_16x16x32_bf16 v[126:129], v[156:159], v[206:209], v[126:129]
	v_mfma_f32_16x16x32_bf16 v[102:105], v[130:133], v[210:213], v[102:105]
	v_mfma_f32_16x16x32_bf16 v[102:105], v[156:159], v[214:217], v[102:105]
	v_mfma_f32_16x16x32_bf16 v[62:65], v[130:133], v[218:221], v[62:65]
	v_mfma_f32_16x16x32_bf16 v[62:65], v[156:159], v[222:225], v[62:65]
	v_mfma_f32_16x16x32_bf16 v[22:25], v[130:133], v[226:229], v[22:25]
	v_mfma_f32_16x16x32_bf16 v[22:25], v[156:159], v[230:233], v[22:25]
	v_mfma_f32_16x16x32_bf16 v[18:21], v[168:171], v[226:229], v[18:21]
	v_mfma_f32_16x16x32_bf16 v[18:21], v[172:175], v[230:233], v[18:21]
	v_mfma_f32_16x16x32_bf16 v[58:61], v[168:171], v[218:221], v[58:61]
	v_mfma_f32_16x16x32_bf16 v[58:61], v[172:175], v[222:225], v[58:61]
	v_mfma_f32_16x16x32_bf16 v[98:101], v[168:171], v[210:213], v[98:101]
	v_mfma_f32_16x16x32_bf16 v[98:101], v[172:175], v[214:217], v[98:101]
	v_mfma_f32_16x16x32_bf16 v[122:125], v[168:171], v[202:205], v[122:125]
	v_mfma_f32_16x16x32_bf16 v[122:125], v[172:175], v[206:209], v[122:125]
	v_mfma_f32_16x16x32_bf16 v[118:121], v[180:183], v[202:205], v[118:121]
	v_mfma_f32_16x16x32_bf16 v[118:121], v[184:187], v[206:209], v[118:121]
	v_mfma_f32_16x16x32_bf16 v[78:81], v[180:183], v[210:213], v[78:81]
	v_mfma_f32_16x16x32_bf16 v[78:81], v[184:187], v[214:217], v[78:81]
	v_mfma_f32_16x16x32_bf16 v[46:49], v[180:183], v[218:221], v[46:49]
	v_mfma_f32_16x16x32_bf16 v[46:49], v[184:187], v[222:225], v[46:49]
	v_mfma_f32_16x16x32_bf16 v[6:9], v[180:183], v[226:229], v[6:9]
	v_mfma_f32_16x16x32_bf16 v[6:9], v[184:187], v[230:233], v[6:9]
	v_mfma_f32_16x16x32_bf16 v[2:5], v[188:191], v[226:229], v[2:5]
	v_mfma_f32_16x16x32_bf16 v[2:5], v[198:201], v[230:233], v[2:5]
	v_mfma_f32_16x16x32_bf16 v[42:45], v[188:191], v[218:221], v[42:45]
	v_mfma_f32_16x16x32_bf16 v[42:45], v[198:201], v[222:225], v[42:45]
	v_mfma_f32_16x16x32_bf16 v[74:77], v[188:191], v[210:213], v[74:77]
	v_mfma_f32_16x16x32_bf16 v[74:77], v[198:201], v[214:217], v[74:77]
	v_mfma_f32_16x16x32_bf16 v[114:117], v[188:191], v[202:205], v[114:117]
	v_mfma_f32_16x16x32_bf16 v[114:117], v[198:201], v[206:209], v[114:117]
	s_barrier
; #define PG8_STAGE(bufoff, gbase, voff) do { _Pragma("unroll") for (int _i = 0; _i < 2; ++_i) \
;         __builtin_amdgcn_global_load_lds((const unsigned*)((const char*)(gbase) + (voff)[_i]), (PG8_LAS unsigned*)(lds + (bufoff) + ldsw + _i * 8192), 16, 0, 0); } while (0)
; #define PG8_LDA(dst, b, h) do { _Pragma("unroll") for (int m = 0; m < 4; ++m) _Pragma("unroll") for (int k = 0; k < 2; ++k) dst[m][k] = *(const PG8_LAS bf16x8*)(lds + PG8_SA(b, h) + aoff + m * 2048 + k * 1024); } while (0)
; #define PG8_LDB(dst, b, h) do { _Pragma("unroll") for (int n = 0; n < 2; ++n) _Pragma("unroll") for (int k = 0; k < 2; ++k) dst[n][k] = *(const PG8_LAS bf16x8*)(lds + PG8_SB(b, h) + boff + n * 2048 + k * 1024); } while (0)
; template <class Epi, class Sched, bool ALIGN_EPI = false, bool SP2 = false>
; __device__ __forceinline__ void gemm_phase(PG8_LAS unsigned char* lds, const Gemm g, const Sched& S, const Epi& E) {
;     ...
;         for (; t < tend; t += 2) {
;             const bool last = (t == nt - 2);
;             const char* a1 = cA + (size_t)(t + 1) * kstep;
;             const char* a2 = last ? nA : cA + (size_t)(t + 2) * kstep; const char* b2 = last ? nB : cB + (size_t)(t + 2) * kstep;
;             const char* a3 = a2 + kstep; const char* b3 = b2 + kstep;
;             if (last && has_next) S.a_ready(nxt);
;             if constexpr (SP2) {
;             PG8_LDB(B0, 0, 0); PG8_LDB(B1, 0, 1); PG8_SCHED; PG8_LDA(At, 0, 0); PG8_STAGE(PG8_SA(1, 1), a1 + hstep, voffA);
;             PG8_WAIT_V(8); PG8_WAIT_L(0); PG8_BAR; PG8_MMA(0, 0, At, B0); PG8_MMA(0, 1, At, B1); PG8_BAR; PG8_SCHED;
;             PG8_LDA(At, 0, 1); PG8_STAGE(PG8_SB(0, 0), b2, voffB); PG8_STAGE(PG8_SB(0, 1), b2 + hstep, voffB); PG8_STAGE(PG8_SA(0, 0), a2, voffA);
;             PG8_WAIT_V(8); PG8_WAIT_L(0); PG8_BAR; PG8_MMA(1, 0, At, B0); PG8_MMA(1, 1, At, B1); PG8_BAR; PG8_SCHED;
;             PG8_LDB(B0, 1, 0); PG8_LDB(B1, 1, 1); PG8_SCHED; PG8_LDA(At, 1, 0); PG8_STAGE(PG8_SA(0, 1), a2 + hstep, voffA);
;             PG8_WAIT_V(8); PG8_WAIT_L(0); PG8_BAR; PG8_MMA(0, 0, At, B0); PG8_MMA(0, 1, At, B1); PG8_BAR; PG8_SCHED;
;             PG8_LDA(At, 1, 1); PG8_STAGE(PG8_SB(1, 0), b3, voffB); PG8_STAGE(PG8_SB(1, 1), b3 + hstep, voffB); PG8_STAGE(PG8_SA(1, 0), a3, voffA);
;             PG8_WAIT_V(8); PG8_WAIT_L(0); PG8_BAR; PG8_MMA(1, 0, At, B0); PG8_MMA(1, 1, At, B1); PG8_BAR; PG8_SCHED;
	ds_read_b128 v[130:133], v142
	ds_read_b128 v[156:159], v142 offset:1024
	ds_read_b128 v[168:171], v142 offset:2048
	ds_read_b128 v[172:175], v142 offset:3072
	ds_read_b128 v[180:183], v167
	ds_read_b128 v[184:187], v167 offset:1024
	ds_read_b128 v[188:191], v167 offset:2048
	ds_read_b128 v[198:201], v167 offset:3072
	s_add_u32 s58, s72, 0x4000
	s_addc_u32 s59, s73, 0
	s_mov_b32 m0, s31
	ds_read_b128 v[202:205], v165 offset:32768
	ds_read_b128 v[206:209], v165 offset:33792
	ds_read_b128 v[210:213], v165 offset:34816
	ds_read_b128 v[214:217], v165 offset:35840
	ds_read_b128 v[218:221], v165 offset:36864
	ds_read_b128 v[222:225], v165 offset:37888
	ds_read_b128 v[226:229], v165 offset:38912
	ds_read_b128 v[230:233], v165 offset:39936
	global_load_lds_dwordx4 v134, s[58:59]
	s_mov_b32 m0, s35
	s_nop 0
	global_load_lds_dwordx4 v138, s[58:59]
	s_waitcnt vmcnt(8)
	s_waitcnt lgkmcnt(0)
	s_barrier
	s_waitcnt lgkmcnt(0)
	v_mfma_f32_16x16x32_bf16 v[14:17], v[130:133], v[202:205], v[14:17]
	v_mfma_f32_16x16x32_bf16 v[14:17], v[156:159], v[206:209], v[14:17]
	v_mfma_f32_16x16x32_bf16 v[38:41], v[130:133], v[210:213], v[38:41]
	v_mfma_f32_16x16x32_bf16 v[38:41], v[156:159], v[214:217], v[38:41]
	v_mfma_f32_16x16x32_bf16 v[70:73], v[130:133], v[218:221], v[70:73]
	v_mfma_f32_16x16x32_bf16 v[70:73], v[156:159], v[222:225], v[70:73]
	v_mfma_f32_16x16x32_bf16 v[94:97], v[130:133], v[226:229], v[94:97]
	v_mfma_f32_16x16x32_bf16 v[94:97], v[156:159], v[230:233], v[94:97]
	v_mfma_f32_16x16x32_bf16 v[90:93], v[168:171], v[226:229], v[90:93]
	v_mfma_f32_16x16x32_bf16 v[90:93], v[172:175], v[230:233], v[90:93]
	v_mfma_f32_16x16x32_bf16 v[66:69], v[168:171], v[218:221], v[66:69]
	v_mfma_f32_16x16x32_bf16 v[66:69], v[172:175], v[222:225], v[66:69]
	v_mfma_f32_16x16x32_bf16 v[34:37], v[168:171], v[210:213], v[34:37]
	v_mfma_f32_16x16x32_bf16 v[34:37], v[172:175], v[214:217], v[34:37]
	v_mfma_f32_16x16x32_bf16 v[10:13], v[168:171], v[202:205], v[10:13]
	v_mfma_f32_16x16x32_bf16 v[10:13], v[172:175], v[206:209], v[10:13]
	v_mfma_f32_16x16x32_bf16 v[30:33], v[180:183], v[202:205], v[30:33]
	v_mfma_f32_16x16x32_bf16 v[30:33], v[184:187], v[206:209], v[30:33]
	v_mfma_f32_16x16x32_bf16 v[54:57], v[180:183], v[210:213], v[54:57]
	v_mfma_f32_16x16x32_bf16 v[54:57], v[184:187], v[214:217], v[54:57]
	v_mfma_f32_16x16x32_bf16 v[86:89], v[180:183], v[218:221], v[86:89]
	v_mfma_f32_16x16x32_bf16 v[86:89], v[184:187], v[222:225], v[86:89]
	v_mfma_f32_16x16x32_bf16 v[110:113], v[180:183], v[226:229], v[110:113]
	v_mfma_f32_16x16x32_bf16 v[110:113], v[184:187], v[230:233], v[110:113]
	v_mfma_f32_16x16x32_bf16 v[106:109], v[188:191], v[226:229], v[106:109]
	v_mfma_f32_16x16x32_bf16 v[106:109], v[198:201], v[230:233], v[106:109]
	v_mfma_f32_16x16x32_bf16 v[82:85], v[188:191], v[218:221], v[82:85]
	v_mfma_f32_16x16x32_bf16 v[82:85], v[198:201], v[222:225], v[82:85]
	v_mfma_f32_16x16x32_bf16 v[50:53], v[188:191], v[210:213], v[50:53]
	v_mfma_f32_16x16x32_bf16 v[50:53], v[198:201], v[214:217], v[50:53]
	v_mfma_f32_16x16x32_bf16 v[26:29], v[188:191], v[202:205], v[26:29]
	v_mfma_f32_16x16x32_bf16 v[26:29], v[198:201], v[206:209], v[26:29]
	s_barrier
	s_add_u32 s58, s70, 0x8000
	s_addc_u32 s59, s71, 0
	s_mov_b32 m0, s89
	ds_read_b128 v[202:205], v165 offset:49152
	ds_read_b128 v[206:209], v165 offset:50176
	ds_read_b128 v[210:213], v165 offset:51200
	ds_read_b128 v[214:217], v165 offset:52224
	ds_read_b128 v[218:221], v165 offset:53248
	ds_read_b128 v[222:225], v165 offset:54272
	ds_read_b128 v[226:229], v165 offset:55296
	ds_read_b128 v[230:233], v165 offset:56320
	global_load_lds_dwordx4 v136, s[58:59]
	v_lshl_add_u64 v[176:177], s[58:59], 0, v[140:141]
	s_add_u32 s58, s70, 0xc000
	s_mov_b32 m0, s90
	s_addc_u32 s59, s71, 0
	global_load_lds_dwordx4 v[176:177], off
	s_mov_b32 m0, s91
	s_nop 0
	global_load_lds_dwordx4 v136, s[58:59]
	s_mov_b32 m0, s92
	s_nop 0
	global_load_lds_dwordx4 v140, s[58:59]
	s_mov_b32 m0, s75
	s_nop 0
	global_load_lds_dwordx4 v134, s[48:49]
	s_mov_b32 m0, s76
	s_nop 0
	global_load_lds_dwordx4 v138, s[48:49]
	s_waitcnt vmcnt(8)
	s_waitcnt lgkmcnt(0)
	s_barrier
	s_waitcnt lgkmcnt(0)
	v_mfma_f32_16x16x32_bf16 v[126:129], v[130:133], v[202:205], v[126:129]
	v_mfma_f32_16x16x32_bf16 v[126:129], v[156:159], v[206:209], v[126:129]
	v_mfma_f32_16x16x32_bf16 v[102:105], v[130:133], v[210:213], v[102:105]
	v_mfma_f32_16x16x32_bf16 v[102:105], v[156:159], v[214:217], v[102:105]
	v_mfma_f32_16x16x32_bf16 v[62:65], v[130:133], v[218:221], v[62:65]
	v_mfma_f32_16x16x32_bf16 v[62:65], v[156:159], v[222:225], v[62:65]
	v_mfma_f32_16x16x32_bf16 v[22:25], v[130:133], v[226:229], v[22:25]
	v_mfma_f32_16x16x32_bf16 v[22:25], v[156:159], v[230:233], v[22:25]
	v_mfma_f32_16x16x32_bf16 v[18:21], v[168:171], v[226:229], v[18:21]
	v_mfma_f32_16x16x32_bf16 v[18:21], v[172:175], v[230:233], v[18:21]
	v_mfma_f32_16x16x32_bf16 v[58:61], v[168:171], v[218:221], v[58:61]
	v_mfma_f32_16x16x32_bf16 v[58:61], v[172:175], v[222:225], v[58:61]
	v_mfma_f32_16x16x32_bf16 v[98:101], v[168:171], v[210:213], v[98:101]
	v_mfma_f32_16x16x32_bf16 v[98:101], v[172:175], v[214:217], v[98:101]
	v_mfma_f32_16x16x32_bf16 v[122:125], v[168:171], v[202:205], v[122:125]
	v_mfma_f32_16x16x32_bf16 v[122:125], v[172:175], v[206:209], v[122:125]
	v_mfma_f32_16x16x32_bf16 v[118:121], v[180:183], v[202:205], v[118:121]
	v_mfma_f32_16x16x32_bf16 v[118:121], v[184:187], v[206:209], v[118:121]
	v_mfma_f32_16x16x32_bf16 v[78:81], v[180:183], v[210:213], v[78:81]
	v_mfma_f32_16x16x32_bf16 v[78:81], v[184:187], v[214:217], v[78:81]
	v_mfma_f32_16x16x32_bf16 v[46:49], v[180:183], v[218:221], v[46:49]
	v_mfma_f32_16x16x32_bf16 v[46:49], v[184:187], v[222:225], v[46:49]
	v_mfma_f32_16x16x32_bf16 v[6:9], v[180:183], v[226:229], v[6:9]
	v_mfma_f32_16x16x32_bf16 v[6:9], v[184:187], v[230:233], v[6:9]
	v_mfma_f32_16x16x32_bf16 v[2:5], v[188:191], v[226:229], v[2:5]
	v_mfma_f32_16x16x32_bf16 v[2:5], v[198:201], v[230:233], v[2:5]
	v_mfma_f32_16x16x32_bf16 v[42:45], v[188:191], v[218:221], v[42:45]
	v_mfma_f32_16x16x32_bf16 v[42:45], v[198:201], v[222:225], v[42:45]
	v_mfma_f32_16x16x32_bf16 v[74:77], v[188:191], v[210:213], v[74:77]
	v_mfma_f32_16x16x32_bf16 v[74:77], v[198:201], v[214:217], v[74:77]
	v_mfma_f32_16x16x32_bf16 v[114:117], v[188:191], v[202:205], v[114:117]
	v_mfma_f32_16x16x32_bf16 v[114:117], v[198:201], v[206:209], v[114:117]
	s_barrier
	s_add_i32 s56, s56, 2
	s_add_u32 s50, s50, 0x10000
	s_addc_u32 s51, s51, 0
	s_add_u32 s26, s26, 0x10000
	s_addc_u32 s33, s33, 0
	s_cmp_lt_u32 s56, 62
	s_cbranch_scc1 .LBB0_684
	s_andn2_b64 vcc, exec, s[12:13]
	s_cbranch_vccnz .LBB0_687
	s_barrier

; #define PG8_STAGE(bufoff, gbase, voff) do { _Pragma("unroll") for (int _i = 0; _i < 2; ++_i) \
;         __builtin_amdgcn_global_load_lds((const unsigned*)((const char*)(gbase) + (voff)[_i]), (PG8_LAS unsigned*)(lds + (bufoff) + ldsw + _i * 8192), 16, 0, 0); } while (0)
; #define PG8_LDA(dst, b, h) do { _Pragma("unroll") for (int m = 0; m < 4; ++m) _Pragma("unroll") for (int k = 0; k < 2; ++k) dst[m][k] = *(const PG8_LAS bf16x8*)(lds + PG8_SA(b, h) + aoff + m * 2048 + k * 1024); } while (0)
; #define PG8_LDB(dst, b, h) do { _Pragma("unroll") for (int n = 0; n < 2; ++n) _Pragma("unroll") for (int k = 0; k < 2; ++k) dst[n][k] = *(const PG8_LAS bf16x8*)(lds + PG8_SB(b, h) + boff + n * 2048 + k * 1024); } while (0)
; template <class Epi, class Sched, bool ALIGN_EPI = false, bool SP2 = false>
; __device__ __forceinline__ void gemm_phase(PG8_LAS unsigned char* lds, const Gemm g, const Sched& S, const Epi& E) {
;     ...
;         for (; t < tend; t += 2) {
;             const bool last = (t == nt - 2);
;             const char* a1 = cA + (size_t)(t + 1) * kstep;
;             const char* a2 = last ? nA : cA + (size_t)(t + 2) * kstep; const char* b2 = last ? nB : cB + (size_t)(t + 2) * kstep;
;             const char* a3 = a2 + kstep; const char* b3 = b2 + kstep;
;             if (last && has_next) S.a_ready(nxt);
;             if constexpr (SP2) {
;             PG8_LDB(B0, 0, 0); PG8_LDB(B1, 0, 1); PG8_SCHED; PG8_LDA(At, 0, 0); PG8_STAGE(PG8_SA(1, 1), a1 + hstep, voffA);
;             PG8_WAIT_V(8); PG8_WAIT_L(0); PG8_BAR; PG8_MMA(0, 0, At, B0); PG8_MMA(0, 1, At, B1); PG8_BAR; PG8_SCHED;
;             PG8_LDA(At, 0, 1); PG8_STAGE(PG8_SB(0, 0), b2, voffB); PG8_STAGE(PG8_SB(0, 1), b2 + hstep, voffB); PG8_STAGE(PG8_SA(0, 0), a2, voffA);
;             PG8_WAIT_V(8); PG8_WAIT_L(0); PG8_BAR; PG8_MMA(1, 0, At, B0); PG8_MMA(1, 1, At, B1); PG8_BAR; PG8_SCHED;
;             PG8_LDB(B0, 1, 0); PG8_LDB(B1, 1, 1); PG8_SCHED; PG8_LDA(At, 1, 0); PG8_STAGE(PG8_SA(0, 1), a2 + hstep, voffA);
;             PG8_WAIT_V(8); PG8_WAIT_L(0); PG8_BAR; PG8_MMA(0, 0, At, B0); PG8_MMA(0, 1, At, B1); PG8_BAR; PG8_SCHED;
;             PG8_LDA(At, 1, 1); PG8_STAGE(PG8_SB(1, 0), b3, voffB); PG8_STAGE(PG8_SB(1, 1), b3 + hstep, voffB); PG8_STAGE(PG8_SA(1, 0), a3, voffA);
;             PG8_WAIT_V(8); PG8_WAIT_L(0); PG8_BAR; PG8_MMA(1, 0, At, B0); PG8_MMA(1, 1, At, B1); PG8_BAR; PG8_SCHED;
.LBB0_757:
	ds_read_b128 v[154:157], v149
	ds_read_b128 v[158:161], v149 offset:1024
	ds_read_b128 v[162:165], v149 offset:2048
	ds_read_b128 v[166:169], v149 offset:3072
	ds_read_b128 v[170:173], v150
	ds_read_b128 v[174:177], v150 offset:1024
	ds_read_b128 v[180:183], v150 offset:2048
	ds_read_b128 v[184:187], v150 offset:3072
	s_add_u32 s46, s44, 0x4000
	s_addc_u32 s47, s45, 0
	s_cmp_eq_u32 s70, 60
	s_cselect_b32 s50, s39, s46
	s_cselect_b32 s51, s17, s47
	s_cselect_b32 s48, s41, s68
	s_cselect_b32 s49, s15, s69
	s_add_u32 s46, s50, 0x8000
	s_addc_u32 s47, s51, 0
	s_sub_u32 s46, s44, 0x4000
	s_subb_u32 s47, s45, 0
	s_mov_b32 m0, s57
	s_nop 0
	global_load_lds_dwordx4 v130, s[46:47]
	s_mov_b32 m0, s58
	s_nop 0
	global_load_lds_dwordx4 v134, s[46:47]
	s_add_i32 m0, s26, 0xc000
	ds_read_b128 v[188:191], v151
	ds_read_b128 v[198:201], v151 offset:1024
	ds_read_b128 v[202:205], v151 offset:2048
	ds_read_b128 v[206:209], v151 offset:3072
	ds_read_b128 v[210:213], v151 offset:4096
	ds_read_b128 v[214:217], v151 offset:5120
	ds_read_b128 v[218:221], v151 offset:6144
	ds_read_b128 v[222:225], v151 offset:7168
	global_load_lds_dwordx4 v138, s[44:45]
	s_add_i32 m0, s26, 0xe000
	s_nop 0
	global_load_lds_dwordx4 v140, s[44:45]
	s_waitcnt vmcnt(8)
	s_waitcnt lgkmcnt(0)
	s_barrier
	s_waitcnt lgkmcnt(0)
	v_mfma_f32_16x16x32_bf16 v[126:129], v[154:157], v[188:191], v[126:129]
	v_mfma_f32_16x16x32_bf16 v[126:129], v[158:161], v[198:201], v[126:129]
	v_mfma_f32_16x16x32_bf16 v[110:113], v[154:157], v[202:205], v[110:113]
	v_mfma_f32_16x16x32_bf16 v[110:113], v[158:161], v[206:209], v[110:113]
	v_mfma_f32_16x16x32_bf16 v[94:97], v[154:157], v[210:213], v[94:97]
	v_mfma_f32_16x16x32_bf16 v[94:97], v[158:161], v[214:217], v[94:97]
	v_mfma_f32_16x16x32_bf16 v[78:81], v[154:157], v[218:221], v[78:81]
	v_mfma_f32_16x16x32_bf16 v[78:81], v[158:161], v[222:225], v[78:81]
	v_mfma_f32_16x16x32_bf16 v[74:77], v[162:165], v[218:221], v[74:77]
	v_mfma_f32_16x16x32_bf16 v[74:77], v[166:169], v[222:225], v[74:77]
	v_mfma_f32_16x16x32_bf16 v[90:93], v[162:165], v[210:213], v[90:93]
	v_mfma_f32_16x16x32_bf16 v[90:93], v[166:169], v[214:217], v[90:93]
	v_mfma_f32_16x16x32_bf16 v[106:109], v[162:165], v[202:205], v[106:109]
	v_mfma_f32_16x16x32_bf16 v[106:109], v[166:169], v[206:209], v[106:109]
	v_mfma_f32_16x16x32_bf16 v[122:125], v[162:165], v[188:191], v[122:125]
	v_mfma_f32_16x16x32_bf16 v[122:125], v[166:169], v[198:201], v[122:125]
	v_mfma_f32_16x16x32_bf16 v[118:121], v[170:173], v[188:191], v[118:121]
	v_mfma_f32_16x16x32_bf16 v[118:121], v[174:177], v[198:201], v[118:121]
	v_mfma_f32_16x16x32_bf16 v[102:105], v[170:173], v[202:205], v[102:105]
	v_mfma_f32_16x16x32_bf16 v[102:105], v[174:177], v[206:209], v[102:105]
	v_mfma_f32_16x16x32_bf16 v[86:89], v[170:173], v[210:213], v[86:89]
	v_mfma_f32_16x16x32_bf16 v[86:89], v[174:177], v[214:217], v[86:89]
	v_mfma_f32_16x16x32_bf16 v[70:73], v[170:173], v[218:221], v[70:73]
	v_mfma_f32_16x16x32_bf16 v[70:73], v[174:177], v[222:225], v[70:73]
	v_mfma_f32_16x16x32_bf16 v[66:69], v[180:183], v[218:221], v[66:69]
	v_mfma_f32_16x16x32_bf16 v[66:69], v[184:187], v[222:225], v[66:69]
	v_mfma_f32_16x16x32_bf16 v[82:85], v[180:183], v[210:213], v[82:85]
	v_mfma_f32_16x16x32_bf16 v[82:85], v[184:187], v[214:217], v[82:85]
	v_mfma_f32_16x16x32_bf16 v[98:101], v[180:183], v[202:205], v[98:101]
	v_mfma_f32_16x16x32_bf16 v[98:101], v[184:187], v[206:209], v[98:101]
	v_mfma_f32_16x16x32_bf16 v[114:117], v[180:183], v[188:191], v[114:117]
	v_mfma_f32_16x16x32_bf16 v[114:117], v[184:187], v[198:201], v[114:117]
	s_barrier
	s_add_i32 s71, s59, s3
	s_mov_b32 m0, s71
	ds_read_b128 v[188:191], v151 offset:16384
	ds_read_b128 v[198:201], v151 offset:17408
	ds_read_b128 v[202:205], v151 offset:18432
	ds_read_b128 v[206:209], v151 offset:19456
	ds_read_b128 v[210:213], v151 offset:20480
	ds_read_b128 v[214:217], v151 offset:21504
	ds_read_b128 v[218:221], v151 offset:22528
	ds_read_b128 v[222:225], v151 offset:23552
	global_load_lds_dwordx4 v132, s[48:49]
	s_add_i32 m0, s71, 0x2000
	s_add_u32 s72, s48, 0x4000
	s_addc_u32 s73, s49, 0
	s_add_i32 s71, s61, s3
	global_load_lds_dwordx4 v136, s[48:49]
	s_mov_b32 m0, s71
	s_nop 0
	global_load_lds_dwordx4 v132, s[72:73]
	s_add_i32 m0, s71, 0x2000
	s_nop 0
	global_load_lds_dwordx4 v136, s[72:73]
	s_waitcnt vmcnt(6)
	s_waitcnt lgkmcnt(0)
	s_barrier
	s_waitcnt lgkmcnt(0)
	v_mfma_f32_16x16x32_bf16 v[62:65], v[154:157], v[188:191], v[62:65]
	v_mfma_f32_16x16x32_bf16 v[62:65], v[158:161], v[198:201], v[62:65]
	v_mfma_f32_16x16x32_bf16 v[46:49], v[154:157], v[202:205], v[46:49]
	v_mfma_f32_16x16x32_bf16 v[46:49], v[158:161], v[206:209], v[46:49]
	v_mfma_f32_16x16x32_bf16 v[30:33], v[154:157], v[210:213], v[30:33]
	v_mfma_f32_16x16x32_bf16 v[30:33], v[158:161], v[214:217], v[30:33]
	v_mfma_f32_16x16x32_bf16 v[14:17], v[154:157], v[218:221], v[14:17]
	v_mfma_f32_16x16x32_bf16 v[14:17], v[158:161], v[222:225], v[14:17]
	v_mfma_f32_16x16x32_bf16 v[10:13], v[162:165], v[218:221], v[10:13]
	v_mfma_f32_16x16x32_bf16 v[10:13], v[166:169], v[222:225], v[10:13]
	v_mfma_f32_16x16x32_bf16 v[26:29], v[162:165], v[210:213], v[26:29]
	v_mfma_f32_16x16x32_bf16 v[26:29], v[166:169], v[214:217], v[26:29]
	v_mfma_f32_16x16x32_bf16 v[42:45], v[162:165], v[202:205], v[42:45]
	v_mfma_f32_16x16x32_bf16 v[42:45], v[166:169], v[206:209], v[42:45]
	v_mfma_f32_16x16x32_bf16 v[58:61], v[162:165], v[188:191], v[58:61]
	v_mfma_f32_16x16x32_bf16 v[58:61], v[166:169], v[198:201], v[58:61]
	v_mfma_f32_16x16x32_bf16 v[54:57], v[170:173], v[188:191], v[54:57]
	v_mfma_f32_16x16x32_bf16 v[54:57], v[174:177], v[198:201], v[54:57]
	v_mfma_f32_16x16x32_bf16 v[38:41], v[170:173], v[202:205], v[38:41]
	v_mfma_f32_16x16x32_bf16 v[38:41], v[174:177], v[206:209], v[38:41]
	v_mfma_f32_16x16x32_bf16 v[22:25], v[170:173], v[210:213], v[22:25]
	v_mfma_f32_16x16x32_bf16 v[22:25], v[174:177], v[214:217], v[22:25]
	v_mfma_f32_16x16x32_bf16 v[6:9], v[170:173], v[218:221], v[6:9]
	v_mfma_f32_16x16x32_bf16 v[6:9], v[174:177], v[222:225], v[6:9]
	v_mfma_f32_16x16x32_bf16 v[2:5], v[180:183], v[218:221], v[2:5]
	v_mfma_f32_16x16x32_bf16 v[2:5], v[184:187], v[222:225], v[2:5]
	v_mfma_f32_16x16x32_bf16 v[18:21], v[180:183], v[210:213], v[18:21]
	v_mfma_f32_16x16x32_bf16 v[18:21], v[184:187], v[214:217], v[18:21]
	v_mfma_f32_16x16x32_bf16 v[34:37], v[180:183], v[202:205], v[34:37]
	v_mfma_f32_16x16x32_bf16 v[34:37], v[184:187], v[206:209], v[34:37]
	v_mfma_f32_16x16x32_bf16 v[50:53], v[180:183], v[188:191], v[50:53]
	v_mfma_f32_16x16x32_bf16 v[50:53], v[184:187], v[198:201], v[50:53]
	s_barrier
; #define PG8_STAGE(bufoff, gbase, voff) do { _Pragma("unroll") for (int _i = 0; _i < 2; ++_i) \
;         __builtin_amdgcn_global_load_lds((const unsigned*)((const char*)(gbase) + (voff)[_i]), (PG8_LAS unsigned*)(lds + (bufoff) + ldsw + _i * 8192), 16, 0, 0); } while (0)
; #define PG8_LDA(dst, b, h) do { _Pragma("unroll") for (int m = 0; m < 4; ++m) _Pragma("unroll") for (int k = 0; k < 2; ++k) dst[m][k] = *(const PG8_LAS bf16x8*)(lds + PG8_SA(b, h) + aoff + m * 2048 + k * 1024); } while (0)
; #define PG8_LDB(dst, b, h) do { _Pragma("unroll") for (int n = 0; n < 2; ++n) _Pragma("unroll") for (int k = 0; k < 2; ++k) dst[n][k] = *(const PG8_LAS bf16x8*)(lds + PG8_SB(b, h) + boff + n * 2048 + k * 1024); } while (0)
; template <class Epi, class Sched, bool ALIGN_EPI = false, bool SP2 = false>
; __device__ __forceinline__ void gemm_phase(PG8_LAS unsigned char* lds, const Gemm g, const Sched& S, const Epi& E) {
;     ...
;         for (; t < tend; t += 2) {
;             const bool last = (t == nt - 2);
;             const char* a1 = cA + (size_t)(t + 1) * kstep;
;             const char* a2 = last ? nA : cA + (size_t)(t + 2) * kstep; const char* b2 = last ? nB : cB + (size_t)(t + 2) * kstep;
;             const char* a3 = a2 + kstep; const char* b3 = b2 + kstep;
;             if (last && has_next) S.a_ready(nxt);
;             if constexpr (SP2) {
;             PG8_LDB(B0, 0, 0); PG8_LDB(B1, 0, 1); PG8_SCHED; PG8_LDA(At, 0, 0); PG8_STAGE(PG8_SA(1, 1), a1 + hstep, voffA);
;             PG8_WAIT_V(8); PG8_WAIT_L(0); PG8_BAR; PG8_MMA(0, 0, At, B0); PG8_MMA(0, 1, At, B1); PG8_BAR; PG8_SCHED;
;             PG8_LDA(At, 0, 1); PG8_STAGE(PG8_SB(0, 0), b2, voffB); PG8_STAGE(PG8_SB(0, 1), b2 + hstep, voffB); PG8_STAGE(PG8_SA(0, 0), a2, voffA);
;             PG8_WAIT_V(8); PG8_WAIT_L(0); PG8_BAR; PG8_MMA(1, 0, At, B0); PG8_MMA(1, 1, At, B1); PG8_BAR; PG8_SCHED;
;             PG8_LDB(B0, 1, 0); PG8_LDB(B1, 1, 1); PG8_SCHED; PG8_LDA(At, 1, 0); PG8_STAGE(PG8_SA(0, 1), a2 + hstep, voffA);
;             PG8_WAIT_V(8); PG8_WAIT_L(0); PG8_BAR; PG8_MMA(0, 0, At, B0); PG8_MMA(0, 1, At, B1); PG8_BAR; PG8_SCHED;
;             PG8_LDA(At, 1, 1); PG8_STAGE(PG8_SB(1, 0), b3, voffB); PG8_STAGE(PG8_SB(1, 1), b3 + hstep, voffB); PG8_STAGE(PG8_SA(1, 0), a3, voffA);
;             PG8_WAIT_V(8); PG8_WAIT_L(0); PG8_BAR; PG8_MMA(1, 0, At, B0); PG8_MMA(1, 1, At, B1); PG8_BAR; PG8_SCHED;
	s_add_i32 s71, 0, 0x18000
	v_add_u32_e32 v146, s71, v1
	s_add_i32 s72, 0, 0x1c000
	ds_read_b128 v[154:157], v146
	ds_read_b128 v[158:161], v146 offset:1024
	ds_read_b128 v[162:165], v146 offset:2048
	ds_read_b128 v[166:169], v146 offset:3072
	v_add_u32_e32 v146, s72, v1
	ds_read_b128 v[170:173], v146
	ds_read_b128 v[174:177], v146 offset:1024
	ds_read_b128 v[180:183], v146 offset:2048
	ds_read_b128 v[184:187], v146 offset:3072
	s_mov_b32 m0, s26
	s_nop 0
	global_load_lds_dwordx4 v130, s[50:51]
	s_mov_b32 m0, s27
	s_nop 0
	global_load_lds_dwordx4 v134, s[50:51]
	s_add_u32 s50, s50, 0x4000
	s_addc_u32 s51, s51, 0
	s_mov_b32 m0, s28
	ds_read_b128 v[188:191], v151 offset:32768
	ds_read_b128 v[198:201], v151 offset:33792
	ds_read_b128 v[202:205], v151 offset:34816
	ds_read_b128 v[206:209], v151 offset:35840
	ds_read_b128 v[210:213], v151 offset:36864
	ds_read_b128 v[214:217], v151 offset:37888
	ds_read_b128 v[218:221], v151 offset:38912
	ds_read_b128 v[222:225], v151 offset:39936
	global_load_lds_dwordx4 v130, s[50:51]
	s_mov_b32 m0, s29
	s_nop 0
	global_load_lds_dwordx4 v134, s[50:51]
	s_waitcnt vmcnt(8)
	s_waitcnt lgkmcnt(0)
	s_barrier
	s_waitcnt lgkmcnt(0)
	v_mfma_f32_16x16x32_bf16 v[126:129], v[154:157], v[188:191], v[126:129]
	v_mfma_f32_16x16x32_bf16 v[126:129], v[158:161], v[198:201], v[126:129]
	v_mfma_f32_16x16x32_bf16 v[110:113], v[154:157], v[202:205], v[110:113]
	v_mfma_f32_16x16x32_bf16 v[110:113], v[158:161], v[206:209], v[110:113]
	v_mfma_f32_16x16x32_bf16 v[94:97], v[154:157], v[210:213], v[94:97]
	v_mfma_f32_16x16x32_bf16 v[94:97], v[158:161], v[214:217], v[94:97]
	v_mfma_f32_16x16x32_bf16 v[78:81], v[154:157], v[218:221], v[78:81]
	v_mfma_f32_16x16x32_bf16 v[78:81], v[158:161], v[222:225], v[78:81]
	v_mfma_f32_16x16x32_bf16 v[74:77], v[162:165], v[218:221], v[74:77]
	v_mfma_f32_16x16x32_bf16 v[74:77], v[166:169], v[222:225], v[74:77]
	v_mfma_f32_16x16x32_bf16 v[90:93], v[162:165], v[210:213], v[90:93]
	v_mfma_f32_16x16x32_bf16 v[90:93], v[166:169], v[214:217], v[90:93]
	v_mfma_f32_16x16x32_bf16 v[106:109], v[162:165], v[202:205], v[106:109]
	v_mfma_f32_16x16x32_bf16 v[106:109], v[166:169], v[206:209], v[106:109]
	v_mfma_f32_16x16x32_bf16 v[122:125], v[162:165], v[188:191], v[122:125]
	v_mfma_f32_16x16x32_bf16 v[122:125], v[166:169], v[198:201], v[122:125]
	v_mfma_f32_16x16x32_bf16 v[118:121], v[170:173], v[188:191], v[118:121]
	v_mfma_f32_16x16x32_bf16 v[118:121], v[174:177], v[198:201], v[118:121]
	v_mfma_f32_16x16x32_bf16 v[102:105], v[170:173], v[202:205], v[102:105]
	v_mfma_f32_16x16x32_bf16 v[102:105], v[174:177], v[206:209], v[102:105]
	v_mfma_f32_16x16x32_bf16 v[86:89], v[170:173], v[210:213], v[86:89]
	v_mfma_f32_16x16x32_bf16 v[86:89], v[174:177], v[214:217], v[86:89]
	v_mfma_f32_16x16x32_bf16 v[70:73], v[170:173], v[218:221], v[70:73]
	v_mfma_f32_16x16x32_bf16 v[70:73], v[174:177], v[222:225], v[70:73]
	v_mfma_f32_16x16x32_bf16 v[66:69], v[180:183], v[218:221], v[66:69]
	v_mfma_f32_16x16x32_bf16 v[66:69], v[184:187], v[222:225], v[66:69]
	v_mfma_f32_16x16x32_bf16 v[82:85], v[180:183], v[210:213], v[82:85]
	v_mfma_f32_16x16x32_bf16 v[82:85], v[184:187], v[214:217], v[82:85]
	v_mfma_f32_16x16x32_bf16 v[98:101], v[180:183], v[202:205], v[98:101]
	v_mfma_f32_16x16x32_bf16 v[98:101], v[184:187], v[206:209], v[98:101]
	v_mfma_f32_16x16x32_bf16 v[114:117], v[180:183], v[188:191], v[114:117]
	v_mfma_f32_16x16x32_bf16 v[114:117], v[184:187], v[198:201], v[114:117]
	s_barrier
	s_add_u32 s50, s48, 0x8000
	s_addc_u32 s51, s49, 0
	s_add_i32 s71, s71, s3
	s_mov_b32 m0, s71
	ds_read_b128 v[188:191], v151 offset:49152
	ds_read_b128 v[198:201], v151 offset:50176
	ds_read_b128 v[202:205], v151 offset:51200
	ds_read_b128 v[206:209], v151 offset:52224
	ds_read_b128 v[210:213], v151 offset:53248
	ds_read_b128 v[214:217], v151 offset:54272
	ds_read_b128 v[218:221], v151 offset:55296
	ds_read_b128 v[222:225], v151 offset:56320
	global_load_lds_dwordx4 v132, s[50:51]
	s_add_i32 m0, s71, 0x2000
	s_add_u32 s48, s48, 0xc000
	v_lshl_add_u64 v[146:147], s[50:51], 0, v[136:137]
	s_addc_u32 s49, s49, 0
	s_add_i32 s50, s72, s3
	global_load_lds_dwordx4 v[146:147], off
	s_mov_b32 m0, s50
	s_nop 0
	global_load_lds_dwordx4 v132, s[48:49]
	s_add_i32 m0, s50, 0x2000
	s_nop 0
	global_load_lds_dwordx4 v136, s[48:49]
	s_waitcnt vmcnt(6)
	s_waitcnt lgkmcnt(0)
	s_barrier
	s_waitcnt lgkmcnt(0)
	v_mfma_f32_16x16x32_bf16 v[62:65], v[154:157], v[188:191], v[62:65]
	v_mfma_f32_16x16x32_bf16 v[62:65], v[158:161], v[198:201], v[62:65]
	v_mfma_f32_16x16x32_bf16 v[46:49], v[154:157], v[202:205], v[46:49]
	v_mfma_f32_16x16x32_bf16 v[46:49], v[158:161], v[206:209], v[46:49]
	v_mfma_f32_16x16x32_bf16 v[30:33], v[154:157], v[210:213], v[30:33]
	v_mfma_f32_16x16x32_bf16 v[30:33], v[158:161], v[214:217], v[30:33]
	v_mfma_f32_16x16x32_bf16 v[14:17], v[154:157], v[218:221], v[14:17]
	v_mfma_f32_16x16x32_bf16 v[14:17], v[158:161], v[222:225], v[14:17]
	v_mfma_f32_16x16x32_bf16 v[10:13], v[162:165], v[218:221], v[10:13]
	v_mfma_f32_16x16x32_bf16 v[10:13], v[166:169], v[222:225], v[10:13]
	v_mfma_f32_16x16x32_bf16 v[26:29], v[162:165], v[210:213], v[26:29]
	v_mfma_f32_16x16x32_bf16 v[26:29], v[166:169], v[214:217], v[26:29]
	v_mfma_f32_16x16x32_bf16 v[42:45], v[162:165], v[202:205], v[42:45]
	v_mfma_f32_16x16x32_bf16 v[42:45], v[166:169], v[206:209], v[42:45]
	v_mfma_f32_16x16x32_bf16 v[58:61], v[162:165], v[188:191], v[58:61]
	v_mfma_f32_16x16x32_bf16 v[58:61], v[166:169], v[198:201], v[58:61]
	v_mfma_f32_16x16x32_bf16 v[54:57], v[170:173], v[188:191], v[54:57]
	v_mfma_f32_16x16x32_bf16 v[54:57], v[174:177], v[198:201], v[54:57]
	v_mfma_f32_16x16x32_bf16 v[38:41], v[170:173], v[202:205], v[38:41]
	v_mfma_f32_16x16x32_bf16 v[38:41], v[174:177], v[206:209], v[38:41]
	v_mfma_f32_16x16x32_bf16 v[22:25], v[170:173], v[210:213], v[22:25]
	v_mfma_f32_16x16x32_bf16 v[22:25], v[174:177], v[214:217], v[22:25]
	v_mfma_f32_16x16x32_bf16 v[6:9], v[170:173], v[218:221], v[6:9]
	v_mfma_f32_16x16x32_bf16 v[6:9], v[174:177], v[222:225], v[6:9]
	v_mfma_f32_16x16x32_bf16 v[2:5], v[180:183], v[218:221], v[2:5]
	v_mfma_f32_16x16x32_bf16 v[2:5], v[184:187], v[222:225], v[2:5]
	v_mfma_f32_16x16x32_bf16 v[18:21], v[180:183], v[210:213], v[18:21]
	v_mfma_f32_16x16x32_bf16 v[18:21], v[184:187], v[214:217], v[18:21]
	v_mfma_f32_16x16x32_bf16 v[34:37], v[180:183], v[202:205], v[34:37]
	v_mfma_f32_16x16x32_bf16 v[34:37], v[184:187], v[206:209], v[34:37]
	v_mfma_f32_16x16x32_bf16 v[50:53], v[180:183], v[188:191], v[50:53]
	v_mfma_f32_16x16x32_bf16 v[50:53], v[184:187], v[198:201], v[50:53]
	s_barrier
	s_add_i32 s70, s70, 2
	s_add_u32 s44, s44, 0x10000
	s_addc_u32 s45, s45, 0
	s_add_u32 s68, s68, 0x10000
	s_addc_u32 s69, s69, 0
	s_cmp_gt_u32 s70, 61
	s_cbranch_scc0 .LBB0_757
	s_and_b64 vcc, exec, s[12:13]
	s_cbranch_vccz .LBB0_760
	s_barrier

; #define PG8_STAGE(bufoff, gbase, voff) do { _Pragma("unroll") for (int _i = 0; _i < 2; ++_i) \
;         __builtin_amdgcn_global_load_lds((const unsigned*)((const char*)(gbase) + (voff)[_i]), (PG8_LAS unsigned*)(lds + (bufoff) + ldsw + _i * 8192), 16, 0, 0); } while (0)
; #define PG8_LDA(dst, b, h) do { _Pragma("unroll") for (int m = 0; m < 4; ++m) _Pragma("unroll") for (int k = 0; k < 2; ++k) dst[m][k] = *(const PG8_LAS bf16x8*)(lds + PG8_SA(b, h) + aoff + m * 2048 + k * 1024); } while (0)
; #define PG8_LDB(dst, b, h) do { _Pragma("unroll") for (int n = 0; n < 2; ++n) _Pragma("unroll") for (int k = 0; k < 2; ++k) dst[n][k] = *(const PG8_LAS bf16x8*)(lds + PG8_SB(b, h) + boff + n * 2048 + k * 1024); } while (0)
; template <class Epi, class Sched, bool ALIGN_EPI = false, bool SP2 = false>
; __device__ __forceinline__ void gemm_phase(PG8_LAS unsigned char* lds, const Gemm g, const Sched& S, const Epi& E) {
;     ...
;         for (; t < tend; t += 2) {
;             const bool last = (t == nt - 2);
;             const char* a1 = cA + (size_t)(t + 1) * kstep;
;             const char* a2 = last ? nA : cA + (size_t)(t + 2) * kstep; const char* b2 = last ? nB : cB + (size_t)(t + 2) * kstep;
;             const char* a3 = a2 + kstep; const char* b3 = b2 + kstep;
;             if (last && has_next) S.a_ready(nxt);
;             if constexpr (SP2) {
;             PG8_LDB(B0, 0, 0); PG8_LDB(B1, 0, 1); PG8_SCHED; PG8_LDA(At, 0, 0); PG8_STAGE(PG8_SA(1, 1), a1 + hstep, voffA);
;             PG8_WAIT_V(8); PG8_WAIT_L(0); PG8_BAR; PG8_MMA(0, 0, At, B0); PG8_MMA(0, 1, At, B1); PG8_BAR; PG8_SCHED;
;             PG8_LDA(At, 0, 1); PG8_STAGE(PG8_SB(0, 0), b2, voffB); PG8_STAGE(PG8_SB(0, 1), b2 + hstep, voffB); PG8_STAGE(PG8_SA(0, 0), a2, voffA);
;             PG8_WAIT_V(8); PG8_WAIT_L(0); PG8_BAR; PG8_MMA(1, 0, At, B0); PG8_MMA(1, 1, At, B1); PG8_BAR; PG8_SCHED;
;             PG8_LDB(B0, 1, 0); PG8_LDB(B1, 1, 1); PG8_SCHED; PG8_LDA(At, 1, 0); PG8_STAGE(PG8_SA(0, 1), a2 + hstep, voffA);
;             PG8_WAIT_V(8); PG8_WAIT_L(0); PG8_BAR; PG8_MMA(0, 0, At, B0); PG8_MMA(0, 1, At, B1); PG8_BAR; PG8_SCHED;
;             PG8_LDA(At, 1, 1); PG8_STAGE(PG8_SB(1, 0), b3, voffB); PG8_STAGE(PG8_SB(1, 1), b3 + hstep, voffB); PG8_STAGE(PG8_SA(1, 0), a3, voffA);
;             PG8_WAIT_V(8); PG8_WAIT_L(0); PG8_BAR; PG8_MMA(1, 0, At, B0); PG8_MMA(1, 1, At, B1); PG8_BAR; PG8_SCHED;
.LBB0_840:
	ds_read_b128 v[148:151], v153
	ds_read_b128 v[158:161], v153 offset:1024
	ds_read_b128 v[162:165], v153 offset:2048
	ds_read_b128 v[166:169], v153 offset:3072
	ds_read_b128 v[170:173], v154
	ds_read_b128 v[174:177], v154 offset:1024
	ds_read_b128 v[180:183], v154 offset:2048
	ds_read_b128 v[184:187], v154 offset:3072
	s_add_u32 s42, s40, 0x4000
	s_addc_u32 s43, s41, 0
	s_cmp_eq_u32 s69, 60
	s_cselect_b32 s46, s65, s42
	s_cselect_b32 s47, s23, s43
	s_cselect_b32 s44, s66, s67
	s_cselect_b32 s45, s17, s68
	s_add_u32 s42, s46, 0x8000
	s_addc_u32 s43, s47, 0
	s_sub_u32 s42, s40, 0x4000
	s_subb_u32 s43, s41, 0
	s_mov_b32 m0, s50
	s_nop 0
	global_load_lds_dwordx4 v130, s[42:43]
	s_mov_b32 m0, s51
	s_nop 0
	global_load_lds_dwordx4 v134, s[42:43]
	s_add_i32 m0, s28, 0xc000
	ds_read_b128 v[188:191], v155
	ds_read_b128 v[198:201], v155 offset:1024
	ds_read_b128 v[202:205], v155 offset:2048
	ds_read_b128 v[206:209], v155 offset:3072
	ds_read_b128 v[210:213], v155 offset:4096
	ds_read_b128 v[214:217], v155 offset:5120
	ds_read_b128 v[218:221], v155 offset:6144
	ds_read_b128 v[222:225], v155 offset:7168
	global_load_lds_dwordx4 v140, s[40:41]
	s_add_i32 m0, s28, 0xe000
	s_nop 0
	global_load_lds_dwordx4 v142, s[40:41]
	s_waitcnt vmcnt(8)
	s_waitcnt lgkmcnt(0)
	s_barrier
	s_waitcnt lgkmcnt(0)
	v_mfma_f32_16x16x32_bf16 v[126:129], v[148:151], v[188:191], v[126:129]
	v_mfma_f32_16x16x32_bf16 v[126:129], v[158:161], v[198:201], v[126:129]
	v_mfma_f32_16x16x32_bf16 v[110:113], v[148:151], v[202:205], v[110:113]
	v_mfma_f32_16x16x32_bf16 v[110:113], v[158:161], v[206:209], v[110:113]
	v_mfma_f32_16x16x32_bf16 v[94:97], v[148:151], v[210:213], v[94:97]
	v_mfma_f32_16x16x32_bf16 v[94:97], v[158:161], v[214:217], v[94:97]
	v_mfma_f32_16x16x32_bf16 v[78:81], v[148:151], v[218:221], v[78:81]
	v_mfma_f32_16x16x32_bf16 v[78:81], v[158:161], v[222:225], v[78:81]
	v_mfma_f32_16x16x32_bf16 v[74:77], v[162:165], v[218:221], v[74:77]
	v_mfma_f32_16x16x32_bf16 v[74:77], v[166:169], v[222:225], v[74:77]
	v_mfma_f32_16x16x32_bf16 v[90:93], v[162:165], v[210:213], v[90:93]
	v_mfma_f32_16x16x32_bf16 v[90:93], v[166:169], v[214:217], v[90:93]
	v_mfma_f32_16x16x32_bf16 v[106:109], v[162:165], v[202:205], v[106:109]
	v_mfma_f32_16x16x32_bf16 v[106:109], v[166:169], v[206:209], v[106:109]
	v_mfma_f32_16x16x32_bf16 v[122:125], v[162:165], v[188:191], v[122:125]
	v_mfma_f32_16x16x32_bf16 v[122:125], v[166:169], v[198:201], v[122:125]
	v_mfma_f32_16x16x32_bf16 v[118:121], v[170:173], v[188:191], v[118:121]
	v_mfma_f32_16x16x32_bf16 v[118:121], v[174:177], v[198:201], v[118:121]
	v_mfma_f32_16x16x32_bf16 v[102:105], v[170:173], v[202:205], v[102:105]
	v_mfma_f32_16x16x32_bf16 v[102:105], v[174:177], v[206:209], v[102:105]
	v_mfma_f32_16x16x32_bf16 v[86:89], v[170:173], v[210:213], v[86:89]
	v_mfma_f32_16x16x32_bf16 v[86:89], v[174:177], v[214:217], v[86:89]
	v_mfma_f32_16x16x32_bf16 v[70:73], v[170:173], v[218:221], v[70:73]
	v_mfma_f32_16x16x32_bf16 v[70:73], v[174:177], v[222:225], v[70:73]
	v_mfma_f32_16x16x32_bf16 v[66:69], v[180:183], v[218:221], v[66:69]
	v_mfma_f32_16x16x32_bf16 v[66:69], v[184:187], v[222:225], v[66:69]
	v_mfma_f32_16x16x32_bf16 v[82:85], v[180:183], v[210:213], v[82:85]
	v_mfma_f32_16x16x32_bf16 v[82:85], v[184:187], v[214:217], v[82:85]
	v_mfma_f32_16x16x32_bf16 v[98:101], v[180:183], v[202:205], v[98:101]
	v_mfma_f32_16x16x32_bf16 v[98:101], v[184:187], v[206:209], v[98:101]
	v_mfma_f32_16x16x32_bf16 v[114:117], v[180:183], v[188:191], v[114:117]
	v_mfma_f32_16x16x32_bf16 v[114:117], v[184:187], v[198:201], v[114:117]
	s_barrier
	s_add_i32 s70, s56, s3
	s_mov_b32 m0, s70
	ds_read_b128 v[188:191], v155 offset:16384
	ds_read_b128 v[198:201], v155 offset:17408
	ds_read_b128 v[202:205], v155 offset:18432
	ds_read_b128 v[206:209], v155 offset:19456
	ds_read_b128 v[210:213], v155 offset:20480
	ds_read_b128 v[214:217], v155 offset:21504
	ds_read_b128 v[218:221], v155 offset:22528
	ds_read_b128 v[222:225], v155 offset:23552
	global_load_lds_dwordx4 v132, s[44:45]
	s_add_i32 m0, s70, 0x2000
	s_add_u32 s70, s44, 0x4000
	s_addc_u32 s71, s45, 0
	s_add_i32 s72, s57, s3
	global_load_lds_dwordx4 v136, s[44:45]
	s_mov_b32 m0, s72
	s_nop 0
	global_load_lds_dwordx4 v132, s[70:71]
	s_add_i32 m0, s72, 0x2000
	s_nop 0
	global_load_lds_dwordx4 v136, s[70:71]
	s_waitcnt vmcnt(6)
	s_waitcnt lgkmcnt(0)
	s_barrier
	s_waitcnt lgkmcnt(0)
	v_mfma_f32_16x16x32_bf16 v[62:65], v[148:151], v[188:191], v[62:65]
	v_mfma_f32_16x16x32_bf16 v[62:65], v[158:161], v[198:201], v[62:65]
	v_mfma_f32_16x16x32_bf16 v[46:49], v[148:151], v[202:205], v[46:49]
	v_mfma_f32_16x16x32_bf16 v[46:49], v[158:161], v[206:209], v[46:49]
	v_mfma_f32_16x16x32_bf16 v[30:33], v[148:151], v[210:213], v[30:33]
	v_mfma_f32_16x16x32_bf16 v[30:33], v[158:161], v[214:217], v[30:33]
	v_mfma_f32_16x16x32_bf16 v[14:17], v[148:151], v[218:221], v[14:17]
	v_mfma_f32_16x16x32_bf16 v[14:17], v[158:161], v[222:225], v[14:17]
	v_mfma_f32_16x16x32_bf16 v[10:13], v[162:165], v[218:221], v[10:13]
	v_mfma_f32_16x16x32_bf16 v[10:13], v[166:169], v[222:225], v[10:13]
	v_mfma_f32_16x16x32_bf16 v[26:29], v[162:165], v[210:213], v[26:29]
	v_mfma_f32_16x16x32_bf16 v[26:29], v[166:169], v[214:217], v[26:29]
	v_mfma_f32_16x16x32_bf16 v[42:45], v[162:165], v[202:205], v[42:45]
	v_mfma_f32_16x16x32_bf16 v[42:45], v[166:169], v[206:209], v[42:45]
	v_mfma_f32_16x16x32_bf16 v[58:61], v[162:165], v[188:191], v[58:61]
	v_mfma_f32_16x16x32_bf16 v[58:61], v[166:169], v[198:201], v[58:61]
	v_mfma_f32_16x16x32_bf16 v[54:57], v[170:173], v[188:191], v[54:57]
	v_mfma_f32_16x16x32_bf16 v[54:57], v[174:177], v[198:201], v[54:57]
	v_mfma_f32_16x16x32_bf16 v[38:41], v[170:173], v[202:205], v[38:41]
	v_mfma_f32_16x16x32_bf16 v[38:41], v[174:177], v[206:209], v[38:41]
	v_mfma_f32_16x16x32_bf16 v[22:25], v[170:173], v[210:213], v[22:25]
	v_mfma_f32_16x16x32_bf16 v[22:25], v[174:177], v[214:217], v[22:25]
	v_mfma_f32_16x16x32_bf16 v[6:9], v[170:173], v[218:221], v[6:9]
	v_mfma_f32_16x16x32_bf16 v[6:9], v[174:177], v[222:225], v[6:9]
	v_mfma_f32_16x16x32_bf16 v[2:5], v[180:183], v[218:221], v[2:5]
	v_mfma_f32_16x16x32_bf16 v[2:5], v[184:187], v[222:225], v[2:5]
	v_mfma_f32_16x16x32_bf16 v[18:21], v[180:183], v[210:213], v[18:21]
	v_mfma_f32_16x16x32_bf16 v[18:21], v[184:187], v[214:217], v[18:21]
	v_mfma_f32_16x16x32_bf16 v[34:37], v[180:183], v[202:205], v[34:37]
	v_mfma_f32_16x16x32_bf16 v[34:37], v[184:187], v[206:209], v[34:37]
	v_mfma_f32_16x16x32_bf16 v[50:53], v[180:183], v[188:191], v[50:53]
	v_mfma_f32_16x16x32_bf16 v[50:53], v[184:187], v[198:201], v[50:53]
	s_barrier
; #define PG8_STAGE(bufoff, gbase, voff) do { _Pragma("unroll") for (int _i = 0; _i < 2; ++_i) \
;         __builtin_amdgcn_global_load_lds((const unsigned*)((const char*)(gbase) + (voff)[_i]), (PG8_LAS unsigned*)(lds + (bufoff) + ldsw + _i * 8192), 16, 0, 0); } while (0)
; #define PG8_LDA(dst, b, h) do { _Pragma("unroll") for (int m = 0; m < 4; ++m) _Pragma("unroll") for (int k = 0; k < 2; ++k) dst[m][k] = *(const PG8_LAS bf16x8*)(lds + PG8_SA(b, h) + aoff + m * 2048 + k * 1024); } while (0)
; #define PG8_LDB(dst, b, h) do { _Pragma("unroll") for (int n = 0; n < 2; ++n) _Pragma("unroll") for (int k = 0; k < 2; ++k) dst[n][k] = *(const PG8_LAS bf16x8*)(lds + PG8_SB(b, h) + boff + n * 2048 + k * 1024); } while (0)
; template <class Epi, class Sched, bool ALIGN_EPI = false, bool SP2 = false>
; __device__ __forceinline__ void gemm_phase(PG8_LAS unsigned char* lds, const Gemm g, const Sched& S, const Epi& E) {
;     ...
;         for (; t < tend; t += 2) {
;             const bool last = (t == nt - 2);
;             const char* a1 = cA + (size_t)(t + 1) * kstep;
;             const char* a2 = last ? nA : cA + (size_t)(t + 2) * kstep; const char* b2 = last ? nB : cB + (size_t)(t + 2) * kstep;
;             const char* a3 = a2 + kstep; const char* b3 = b2 + kstep;
;             if (last && has_next) S.a_ready(nxt);
;             if constexpr (SP2) {
;             PG8_LDB(B0, 0, 0); PG8_LDB(B1, 0, 1); PG8_SCHED; PG8_LDA(At, 0, 0); PG8_STAGE(PG8_SA(1, 1), a1 + hstep, voffA);
;             PG8_WAIT_V(8); PG8_WAIT_L(0); PG8_BAR; PG8_MMA(0, 0, At, B0); PG8_MMA(0, 1, At, B1); PG8_BAR; PG8_SCHED;
;             PG8_LDA(At, 0, 1); PG8_STAGE(PG8_SB(0, 0), b2, voffB); PG8_STAGE(PG8_SB(0, 1), b2 + hstep, voffB); PG8_STAGE(PG8_SA(0, 0), a2, voffA);
;             PG8_WAIT_V(8); PG8_WAIT_L(0); PG8_BAR; PG8_MMA(1, 0, At, B0); PG8_MMA(1, 1, At, B1); PG8_BAR; PG8_SCHED;
;             PG8_LDB(B0, 1, 0); PG8_LDB(B1, 1, 1); PG8_SCHED; PG8_LDA(At, 1, 0); PG8_STAGE(PG8_SA(0, 1), a2 + hstep, voffA);
;             PG8_WAIT_V(8); PG8_WAIT_L(0); PG8_BAR; PG8_MMA(0, 0, At, B0); PG8_MMA(0, 1, At, B1); PG8_BAR; PG8_SCHED;
;             PG8_LDA(At, 1, 1); PG8_STAGE(PG8_SB(1, 0), b3, voffB); PG8_STAGE(PG8_SB(1, 1), b3 + hstep, voffB); PG8_STAGE(PG8_SA(1, 0), a3, voffA);
;             PG8_WAIT_V(8); PG8_WAIT_L(0); PG8_BAR; PG8_MMA(1, 0, At, B0); PG8_MMA(1, 1, At, B1); PG8_BAR; PG8_SCHED;
	s_add_i32 s70, 0, 0x18000
	v_add_u32_e32 v138, s70, v1
	s_add_i32 s71, 0, 0x1c000
	ds_read_b128 v[148:151], v138
	ds_read_b128 v[158:161], v138 offset:1024
	ds_read_b128 v[162:165], v138 offset:2048
	ds_read_b128 v[166:169], v138 offset:3072
	v_add_u32_e32 v138, s71, v1
	ds_read_b128 v[170:173], v138
	ds_read_b128 v[174:177], v138 offset:1024
	ds_read_b128 v[180:183], v138 offset:2048
	ds_read_b128 v[184:187], v138 offset:3072
	s_mov_b32 m0, s28
	s_nop 0
	global_load_lds_dwordx4 v130, s[46:47]
	s_mov_b32 m0, s29
	s_nop 0
	global_load_lds_dwordx4 v134, s[46:47]
	s_add_u32 s46, s46, 0x4000
	s_addc_u32 s47, s47, 0
	s_mov_b32 m0, s30
	ds_read_b128 v[188:191], v155 offset:32768
	ds_read_b128 v[198:201], v155 offset:33792
	ds_read_b128 v[202:205], v155 offset:34816
	ds_read_b128 v[206:209], v155 offset:35840
	ds_read_b128 v[210:213], v155 offset:36864
	ds_read_b128 v[214:217], v155 offset:37888
	ds_read_b128 v[218:221], v155 offset:38912
	ds_read_b128 v[222:225], v155 offset:39936
	global_load_lds_dwordx4 v130, s[46:47]
	s_mov_b32 m0, s31
	s_nop 0
	global_load_lds_dwordx4 v134, s[46:47]
	s_waitcnt vmcnt(8)
	s_waitcnt lgkmcnt(0)
	s_barrier
	s_waitcnt lgkmcnt(0)
	v_mfma_f32_16x16x32_bf16 v[126:129], v[148:151], v[188:191], v[126:129]
	v_mfma_f32_16x16x32_bf16 v[126:129], v[158:161], v[198:201], v[126:129]
	v_mfma_f32_16x16x32_bf16 v[110:113], v[148:151], v[202:205], v[110:113]
	v_mfma_f32_16x16x32_bf16 v[110:113], v[158:161], v[206:209], v[110:113]
	v_mfma_f32_16x16x32_bf16 v[94:97], v[148:151], v[210:213], v[94:97]
	v_mfma_f32_16x16x32_bf16 v[94:97], v[158:161], v[214:217], v[94:97]
	v_mfma_f32_16x16x32_bf16 v[78:81], v[148:151], v[218:221], v[78:81]
	v_mfma_f32_16x16x32_bf16 v[78:81], v[158:161], v[222:225], v[78:81]
	v_mfma_f32_16x16x32_bf16 v[74:77], v[162:165], v[218:221], v[74:77]
	v_mfma_f32_16x16x32_bf16 v[74:77], v[166:169], v[222:225], v[74:77]
	v_mfma_f32_16x16x32_bf16 v[90:93], v[162:165], v[210:213], v[90:93]
	v_mfma_f32_16x16x32_bf16 v[90:93], v[166:169], v[214:217], v[90:93]
	v_mfma_f32_16x16x32_bf16 v[106:109], v[162:165], v[202:205], v[106:109]
	v_mfma_f32_16x16x32_bf16 v[106:109], v[166:169], v[206:209], v[106:109]
	v_mfma_f32_16x16x32_bf16 v[122:125], v[162:165], v[188:191], v[122:125]
	v_mfma_f32_16x16x32_bf16 v[122:125], v[166:169], v[198:201], v[122:125]
	v_mfma_f32_16x16x32_bf16 v[118:121], v[170:173], v[188:191], v[118:121]
	v_mfma_f32_16x16x32_bf16 v[118:121], v[174:177], v[198:201], v[118:121]
	v_mfma_f32_16x16x32_bf16 v[102:105], v[170:173], v[202:205], v[102:105]
	v_mfma_f32_16x16x32_bf16 v[102:105], v[174:177], v[206:209], v[102:105]
	v_mfma_f32_16x16x32_bf16 v[86:89], v[170:173], v[210:213], v[86:89]
	v_mfma_f32_16x16x32_bf16 v[86:89], v[174:177], v[214:217], v[86:89]
	v_mfma_f32_16x16x32_bf16 v[70:73], v[170:173], v[218:221], v[70:73]
	v_mfma_f32_16x16x32_bf16 v[70:73], v[174:177], v[222:225], v[70:73]
	v_mfma_f32_16x16x32_bf16 v[66:69], v[180:183], v[218:221], v[66:69]
	v_mfma_f32_16x16x32_bf16 v[66:69], v[184:187], v[222:225], v[66:69]
	v_mfma_f32_16x16x32_bf16 v[82:85], v[180:183], v[210:213], v[82:85]
	v_mfma_f32_16x16x32_bf16 v[82:85], v[184:187], v[214:217], v[82:85]
	v_mfma_f32_16x16x32_bf16 v[98:101], v[180:183], v[202:205], v[98:101]
	v_mfma_f32_16x16x32_bf16 v[98:101], v[184:187], v[206:209], v[98:101]
	v_mfma_f32_16x16x32_bf16 v[114:117], v[180:183], v[188:191], v[114:117]
	v_mfma_f32_16x16x32_bf16 v[114:117], v[184:187], v[198:201], v[114:117]
	s_barrier
	s_add_u32 s46, s44, 0x8000
	s_addc_u32 s47, s45, 0
	s_add_i32 s70, s70, s3
	s_mov_b32 m0, s70
	ds_read_b128 v[188:191], v155 offset:49152
	ds_read_b128 v[198:201], v155 offset:50176
	ds_read_b128 v[202:205], v155 offset:51200
	ds_read_b128 v[206:209], v155 offset:52224
	ds_read_b128 v[210:213], v155 offset:53248
	ds_read_b128 v[214:217], v155 offset:54272
	ds_read_b128 v[218:221], v155 offset:55296
	ds_read_b128 v[222:225], v155 offset:56320
	global_load_lds_dwordx4 v132, s[46:47]
	s_add_i32 m0, s70, 0x2000
	s_add_u32 s44, s44, 0xc000
	v_lshl_add_u64 v[226:227], s[46:47], 0, v[136:137]
	s_addc_u32 s45, s45, 0
	s_add_i32 s46, s71, s3
	global_load_lds_dwordx4 v[226:227], off
	s_mov_b32 m0, s46
	s_nop 0
	global_load_lds_dwordx4 v132, s[44:45]
	s_add_i32 m0, s46, 0x2000
	s_nop 0
	global_load_lds_dwordx4 v136, s[44:45]
	s_waitcnt vmcnt(6)
	s_waitcnt lgkmcnt(0)
	s_barrier
	s_waitcnt lgkmcnt(0)
	v_mfma_f32_16x16x32_bf16 v[62:65], v[148:151], v[188:191], v[62:65]
	v_mfma_f32_16x16x32_bf16 v[62:65], v[158:161], v[198:201], v[62:65]
	v_mfma_f32_16x16x32_bf16 v[46:49], v[148:151], v[202:205], v[46:49]
	v_mfma_f32_16x16x32_bf16 v[46:49], v[158:161], v[206:209], v[46:49]
	v_mfma_f32_16x16x32_bf16 v[30:33], v[148:151], v[210:213], v[30:33]
	v_mfma_f32_16x16x32_bf16 v[30:33], v[158:161], v[214:217], v[30:33]
	v_mfma_f32_16x16x32_bf16 v[14:17], v[148:151], v[218:221], v[14:17]
	v_mfma_f32_16x16x32_bf16 v[14:17], v[158:161], v[222:225], v[14:17]
	v_mfma_f32_16x16x32_bf16 v[10:13], v[162:165], v[218:221], v[10:13]
	v_mfma_f32_16x16x32_bf16 v[10:13], v[166:169], v[222:225], v[10:13]
	v_mfma_f32_16x16x32_bf16 v[26:29], v[162:165], v[210:213], v[26:29]
	v_mfma_f32_16x16x32_bf16 v[26:29], v[166:169], v[214:217], v[26:29]
	v_mfma_f32_16x16x32_bf16 v[42:45], v[162:165], v[202:205], v[42:45]
	v_mfma_f32_16x16x32_bf16 v[42:45], v[166:169], v[206:209], v[42:45]
	v_mfma_f32_16x16x32_bf16 v[58:61], v[162:165], v[188:191], v[58:61]
	v_mfma_f32_16x16x32_bf16 v[58:61], v[166:169], v[198:201], v[58:61]
	v_mfma_f32_16x16x32_bf16 v[54:57], v[170:173], v[188:191], v[54:57]
	v_mfma_f32_16x16x32_bf16 v[54:57], v[174:177], v[198:201], v[54:57]
	v_mfma_f32_16x16x32_bf16 v[38:41], v[170:173], v[202:205], v[38:41]
	v_mfma_f32_16x16x32_bf16 v[38:41], v[174:177], v[206:209], v[38:41]
	v_mfma_f32_16x16x32_bf16 v[22:25], v[170:173], v[210:213], v[22:25]
	v_mfma_f32_16x16x32_bf16 v[22:25], v[174:177], v[214:217], v[22:25]
	v_mfma_f32_16x16x32_bf16 v[6:9], v[170:173], v[218:221], v[6:9]
	v_mfma_f32_16x16x32_bf16 v[6:9], v[174:177], v[222:225], v[6:9]
	v_mfma_f32_16x16x32_bf16 v[2:5], v[180:183], v[218:221], v[2:5]
	v_mfma_f32_16x16x32_bf16 v[2:5], v[184:187], v[222:225], v[2:5]
	v_mfma_f32_16x16x32_bf16 v[18:21], v[180:183], v[210:213], v[18:21]
	v_mfma_f32_16x16x32_bf16 v[18:21], v[184:187], v[214:217], v[18:21]
	v_mfma_f32_16x16x32_bf16 v[34:37], v[180:183], v[202:205], v[34:37]
	v_mfma_f32_16x16x32_bf16 v[34:37], v[184:187], v[206:209], v[34:37]
	v_mfma_f32_16x16x32_bf16 v[50:53], v[180:183], v[188:191], v[50:53]
	v_mfma_f32_16x16x32_bf16 v[50:53], v[184:187], v[198:201], v[50:53]
	s_barrier
	s_add_i32 s69, s69, 2
	s_add_u32 s40, s40, 0x10000
	s_addc_u32 s41, s41, 0
	s_add_u32 s67, s67, 0x10000
	s_addc_u32 s68, s68, 0
	s_cmp_gt_u32 s69, 61
	s_cbranch_scc0 .LBB0_840
	s_and_b64 vcc, exec, s[14:15]
	s_cbranch_vccz .LBB0_843
	s_barrier

; #define PG8_STAGE(bufoff, gbase, voff) do { _Pragma("unroll") for (int _i = 0; _i < 2; ++_i) \
;         __builtin_amdgcn_global_load_lds((const unsigned*)((const char*)(gbase) + (voff)[_i]), (PG8_LAS unsigned*)(lds + (bufoff) + ldsw + _i * 8192), 16, 0, 0); } while (0)
; #define PG8_LDA(dst, b, h) do { _Pragma("unroll") for (int m = 0; m < 4; ++m) _Pragma("unroll") for (int k = 0; k < 2; ++k) dst[m][k] = *(const PG8_LAS bf16x8*)(lds + PG8_SA(b, h) + aoff + m * 2048 + k * 1024); } while (0)
; #define PG8_LDB(dst, b, h) do { _Pragma("unroll") for (int n = 0; n < 2; ++n) _Pragma("unroll") for (int k = 0; k < 2; ++k) dst[n][k] = *(const PG8_LAS bf16x8*)(lds + PG8_SB(b, h) + boff + n * 2048 + k * 1024); } while (0)
; template <class Epi, class Sched, bool ALIGN_EPI = false, bool SP2 = false>
; __device__ __forceinline__ void gemm_phase(PG8_LAS unsigned char* lds, const Gemm g, const Sched& S, const Epi& E) {
;     ...
;         for (; t < tend; t += 2) {
;             const bool last = (t == nt - 2);
;             const char* a1 = cA + (size_t)(t + 1) * kstep;
;             const char* a2 = last ? nA : cA + (size_t)(t + 2) * kstep; const char* b2 = last ? nB : cB + (size_t)(t + 2) * kstep;
;             const char* a3 = a2 + kstep; const char* b3 = b2 + kstep;
;             if (last && has_next) S.a_ready(nxt);
;             if constexpr (SP2) {
;             PG8_LDB(B0, 0, 0); PG8_LDB(B1, 0, 1); PG8_SCHED; PG8_LDA(At, 0, 0); PG8_STAGE(PG8_SA(1, 1), a1 + hstep, voffA);
;             PG8_WAIT_V(8); PG8_WAIT_L(0); PG8_BAR; PG8_MMA(0, 0, At, B0); PG8_MMA(0, 1, At, B1); PG8_BAR; PG8_SCHED;
;             PG8_LDA(At, 0, 1); PG8_STAGE(PG8_SB(0, 0), b2, voffB); PG8_STAGE(PG8_SB(0, 1), b2 + hstep, voffB); PG8_STAGE(PG8_SA(0, 0), a2, voffA);
;             PG8_WAIT_V(8); PG8_WAIT_L(0); PG8_BAR; PG8_MMA(1, 0, At, B0); PG8_MMA(1, 1, At, B1); PG8_BAR; PG8_SCHED;
;             PG8_LDB(B0, 1, 0); PG8_LDB(B1, 1, 1); PG8_SCHED; PG8_LDA(At, 1, 0); PG8_STAGE(PG8_SA(0, 1), a2 + hstep, voffA);
;             PG8_WAIT_V(8); PG8_WAIT_L(0); PG8_BAR; PG8_MMA(0, 0, At, B0); PG8_MMA(0, 1, At, B1); PG8_BAR; PG8_SCHED;
;             PG8_LDA(At, 1, 1); PG8_STAGE(PG8_SB(1, 0), b3, voffB); PG8_STAGE(PG8_SB(1, 1), b3 + hstep, voffB); PG8_STAGE(PG8_SA(1, 0), a3, voffA);
;             PG8_WAIT_V(8); PG8_WAIT_L(0); PG8_BAR; PG8_MMA(1, 0, At, B0); PG8_MMA(1, 1, At, B1); PG8_BAR; PG8_SCHED;
.LBB0_939:
	s_or_b32 s24, s59, 1
	s_lshl_b64 s[62:63], s[24:25], 15
	s_add_i32 s24, s59, 2
	ds_read_b128 v[156:159], v193
	ds_read_b128 v[160:163], v193 offset:1024
	ds_read_b128 v[196:199], v193 offset:2048
	ds_read_b128 v[200:203], v193 offset:3072
	ds_read_b128 v[204:207], v194
	ds_read_b128 v[208:211], v194 offset:1024
	ds_read_b128 v[212:215], v194 offset:2048
	ds_read_b128 v[216:219], v194 offset:3072
	s_lshl_b64 s[8:9], s[24:25], 15
	s_add_u32 s44, s6, s8
	s_addc_u32 s45, s7, s9
	s_cmpk_eq_i32 s59, 0xaa
	s_cselect_b32 s46, s58, s44
	s_cselect_b32 s47, s56, s45
	s_cselect_b32 s44, 0, s8
	s_cselect_b32 s45, 0, s9
	s_add_u32 s8, s46, 0x8000
	s_addc_u32 s9, s47, 0
	s_add_u32 s44, s14, s44
	s_addc_u32 s45, s15, s45
	s_add_u32 s62, s6, s62
	s_addc_u32 s63, s7, s63
	s_add_u32 s62, s62, 0x4000
	s_addc_u32 s63, s63, 0
	s_sub_u32 s8, s62, 0x4000
	s_subb_u32 s9, s63, 0
	s_mov_b32 m0, s51
	s_nop 0
	global_load_lds_dwordx4 v130, s[8:9]
	s_mov_b32 m0, s57
	s_nop 0
	global_load_lds_dwordx4 v134, s[8:9]
	s_add_i32 m0, s30, 0xc000
	ds_read_b128 v[220:223], v186
	ds_read_b128 v[224:227], v186 offset:1024
	ds_read_b128 v[228:231], v186 offset:2048
	ds_read_b128 v[232:235], v186 offset:3072
	ds_read_b128 v[236:239], v186 offset:4096
	ds_read_b128 v[240:243], v186 offset:5120
	ds_read_b128 v[244:247], v186 offset:6144
	ds_read_b128 v[248:251], v186 offset:7168
	global_load_lds_dwordx4 v130, s[62:63]
	s_add_i32 m0, s30, 0xe000
	s_nop 0
	global_load_lds_dwordx4 v134, s[62:63]
	s_waitcnt vmcnt(8)
	s_waitcnt lgkmcnt(0)
	s_barrier
	s_waitcnt lgkmcnt(0)
	v_mfma_f32_16x16x32_bf16 v[126:129], v[156:159], v[220:223], v[126:129]
	v_mfma_f32_16x16x32_bf16 v[126:129], v[160:163], v[224:227], v[126:129]
	v_mfma_f32_16x16x32_bf16 v[110:113], v[156:159], v[228:231], v[110:113]
	v_mfma_f32_16x16x32_bf16 v[110:113], v[160:163], v[232:235], v[110:113]
	v_mfma_f32_16x16x32_bf16 v[94:97], v[156:159], v[236:239], v[94:97]
	v_mfma_f32_16x16x32_bf16 v[94:97], v[160:163], v[240:243], v[94:97]
	v_mfma_f32_16x16x32_bf16 v[78:81], v[156:159], v[244:247], v[78:81]
	v_mfma_f32_16x16x32_bf16 v[78:81], v[160:163], v[248:251], v[78:81]
	v_mfma_f32_16x16x32_bf16 v[74:77], v[196:199], v[244:247], v[74:77]
	v_mfma_f32_16x16x32_bf16 v[74:77], v[200:203], v[248:251], v[74:77]
	v_mfma_f32_16x16x32_bf16 v[90:93], v[196:199], v[236:239], v[90:93]
	v_mfma_f32_16x16x32_bf16 v[90:93], v[200:203], v[240:243], v[90:93]
	v_mfma_f32_16x16x32_bf16 v[106:109], v[196:199], v[228:231], v[106:109]
	v_mfma_f32_16x16x32_bf16 v[106:109], v[200:203], v[232:235], v[106:109]
	v_mfma_f32_16x16x32_bf16 v[122:125], v[196:199], v[220:223], v[122:125]
	v_mfma_f32_16x16x32_bf16 v[122:125], v[200:203], v[224:227], v[122:125]
	v_mfma_f32_16x16x32_bf16 v[118:121], v[204:207], v[220:223], v[118:121]
	v_mfma_f32_16x16x32_bf16 v[118:121], v[208:211], v[224:227], v[118:121]
	v_mfma_f32_16x16x32_bf16 v[102:105], v[204:207], v[228:231], v[102:105]
	v_mfma_f32_16x16x32_bf16 v[102:105], v[208:211], v[232:235], v[102:105]
	v_mfma_f32_16x16x32_bf16 v[86:89], v[204:207], v[236:239], v[86:89]
	v_mfma_f32_16x16x32_bf16 v[86:89], v[208:211], v[240:243], v[86:89]
	v_mfma_f32_16x16x32_bf16 v[70:73], v[204:207], v[244:247], v[70:73]
	v_mfma_f32_16x16x32_bf16 v[70:73], v[208:211], v[248:251], v[70:73]
	v_mfma_f32_16x16x32_bf16 v[66:69], v[212:215], v[244:247], v[66:69]
	v_mfma_f32_16x16x32_bf16 v[66:69], v[216:219], v[248:251], v[66:69]
	v_mfma_f32_16x16x32_bf16 v[82:85], v[212:215], v[236:239], v[82:85]
	v_mfma_f32_16x16x32_bf16 v[82:85], v[216:219], v[240:243], v[82:85]
	v_mfma_f32_16x16x32_bf16 v[98:101], v[212:215], v[228:231], v[98:101]
	v_mfma_f32_16x16x32_bf16 v[98:101], v[216:219], v[232:235], v[98:101]
	v_mfma_f32_16x16x32_bf16 v[114:117], v[212:215], v[220:223], v[114:117]
	v_mfma_f32_16x16x32_bf16 v[114:117], v[216:219], v[224:227], v[114:117]
	s_barrier
	s_add_i32 s62, s67, s29
	s_mov_b32 m0, s62
	ds_read_b128 v[220:223], v186 offset:16384
	ds_read_b128 v[224:227], v186 offset:17408
	ds_read_b128 v[228:231], v186 offset:18432
	ds_read_b128 v[232:235], v186 offset:19456
	ds_read_b128 v[236:239], v186 offset:20480
	ds_read_b128 v[240:243], v186 offset:21504
	ds_read_b128 v[244:247], v186 offset:22528
	ds_read_b128 v[248:251], v186 offset:23552
	global_load_lds_dwordx4 v132, s[44:45]
	s_add_i32 m0, s62, 0x2000
	s_add_u32 s62, s44, 0x4000
	s_addc_u32 s63, s45, 0
	s_add_i32 s72, s68, s29
	global_load_lds_dwordx4 v136, s[44:45]
	s_mov_b32 m0, s72
	s_nop 0
	global_load_lds_dwordx4 v132, s[62:63]
	s_add_i32 m0, s72, 0x2000
	s_nop 0
	global_load_lds_dwordx4 v136, s[62:63]
	s_waitcnt vmcnt(6)
	s_waitcnt lgkmcnt(0)
	s_barrier
; #define PG8_STAGE(bufoff, gbase, voff) do { _Pragma("unroll") for (int _i = 0; _i < 2; ++_i) \
;         __builtin_amdgcn_global_load_lds((const unsigned*)((const char*)(gbase) + (voff)[_i]), (PG8_LAS unsigned*)(lds + (bufoff) + ldsw + _i * 8192), 16, 0, 0); } while (0)
; #define PG8_LDA(dst, b, h) do { _Pragma("unroll") for (int m = 0; m < 4; ++m) _Pragma("unroll") for (int k = 0; k < 2; ++k) dst[m][k] = *(const PG8_LAS bf16x8*)(lds + PG8_SA(b, h) + aoff + m * 2048 + k * 1024); } while (0)
; #define PG8_LDB(dst, b, h) do { _Pragma("unroll") for (int n = 0; n < 2; ++n) _Pragma("unroll") for (int k = 0; k < 2; ++k) dst[n][k] = *(const PG8_LAS bf16x8*)(lds + PG8_SB(b, h) + boff + n * 2048 + k * 1024); } while (0)
; template <class Epi, class Sched, bool ALIGN_EPI = false, bool SP2 = false>
; __device__ __forceinline__ void gemm_phase(PG8_LAS unsigned char* lds, const Gemm g, const Sched& S, const Epi& E) {
;     ...
;         for (; t < tend; t += 2) {
;             const bool last = (t == nt - 2);
;             const char* a1 = cA + (size_t)(t + 1) * kstep;
;             const char* a2 = last ? nA : cA + (size_t)(t + 2) * kstep; const char* b2 = last ? nB : cB + (size_t)(t + 2) * kstep;
;             const char* a3 = a2 + kstep; const char* b3 = b2 + kstep;
;             if (last && has_next) S.a_ready(nxt);
;             if constexpr (SP2) {
;             PG8_LDB(B0, 0, 0); PG8_LDB(B1, 0, 1); PG8_SCHED; PG8_LDA(At, 0, 0); PG8_STAGE(PG8_SA(1, 1), a1 + hstep, voffA);
;             PG8_WAIT_V(8); PG8_WAIT_L(0); PG8_BAR; PG8_MMA(0, 0, At, B0); PG8_MMA(0, 1, At, B1); PG8_BAR; PG8_SCHED;
;             PG8_LDA(At, 0, 1); PG8_STAGE(PG8_SB(0, 0), b2, voffB); PG8_STAGE(PG8_SB(0, 1), b2 + hstep, voffB); PG8_STAGE(PG8_SA(0, 0), a2, voffA);
;             PG8_WAIT_V(8); PG8_WAIT_L(0); PG8_BAR; PG8_MMA(1, 0, At, B0); PG8_MMA(1, 1, At, B1); PG8_BAR; PG8_SCHED;
;             PG8_LDB(B0, 1, 0); PG8_LDB(B1, 1, 1); PG8_SCHED; PG8_LDA(At, 1, 0); PG8_STAGE(PG8_SA(0, 1), a2 + hstep, voffA);
;             PG8_WAIT_V(8); PG8_WAIT_L(0); PG8_BAR; PG8_MMA(0, 0, At, B0); PG8_MMA(0, 1, At, B1); PG8_BAR; PG8_SCHED;
;             PG8_LDA(At, 1, 1); PG8_STAGE(PG8_SB(1, 0), b3, voffB); PG8_STAGE(PG8_SB(1, 1), b3 + hstep, voffB); PG8_STAGE(PG8_SA(1, 0), a3, voffA);
;             PG8_WAIT_V(8); PG8_WAIT_L(0); PG8_BAR; PG8_MMA(1, 0, At, B0); PG8_MMA(1, 1, At, B1); PG8_BAR; PG8_SCHED;
	s_waitcnt lgkmcnt(0)
	v_mfma_f32_16x16x32_bf16 v[62:65], v[156:159], v[220:223], v[62:65]
	v_mfma_f32_16x16x32_bf16 v[62:65], v[160:163], v[224:227], v[62:65]
	v_mfma_f32_16x16x32_bf16 v[46:49], v[156:159], v[228:231], v[46:49]
	v_mfma_f32_16x16x32_bf16 v[46:49], v[160:163], v[232:235], v[46:49]
	v_mfma_f32_16x16x32_bf16 v[30:33], v[156:159], v[236:239], v[30:33]
	v_mfma_f32_16x16x32_bf16 v[30:33], v[160:163], v[240:243], v[30:33]
	v_mfma_f32_16x16x32_bf16 v[14:17], v[156:159], v[244:247], v[14:17]
	v_mfma_f32_16x16x32_bf16 v[14:17], v[160:163], v[248:251], v[14:17]
	v_mfma_f32_16x16x32_bf16 v[10:13], v[196:199], v[244:247], v[10:13]
	v_mfma_f32_16x16x32_bf16 v[10:13], v[200:203], v[248:251], v[10:13]
	v_mfma_f32_16x16x32_bf16 v[26:29], v[196:199], v[236:239], v[26:29]
	v_mfma_f32_16x16x32_bf16 v[26:29], v[200:203], v[240:243], v[26:29]
	v_mfma_f32_16x16x32_bf16 v[42:45], v[196:199], v[228:231], v[42:45]
	v_mfma_f32_16x16x32_bf16 v[42:45], v[200:203], v[232:235], v[42:45]
	v_mfma_f32_16x16x32_bf16 v[58:61], v[196:199], v[220:223], v[58:61]
	v_mfma_f32_16x16x32_bf16 v[58:61], v[200:203], v[224:227], v[58:61]
	v_mfma_f32_16x16x32_bf16 v[54:57], v[204:207], v[220:223], v[54:57]
	v_mfma_f32_16x16x32_bf16 v[54:57], v[208:211], v[224:227], v[54:57]
	v_mfma_f32_16x16x32_bf16 v[38:41], v[204:207], v[228:231], v[38:41]
	v_mfma_f32_16x16x32_bf16 v[38:41], v[208:211], v[232:235], v[38:41]
	v_mfma_f32_16x16x32_bf16 v[22:25], v[204:207], v[236:239], v[22:25]
	v_mfma_f32_16x16x32_bf16 v[22:25], v[208:211], v[240:243], v[22:25]
	v_mfma_f32_16x16x32_bf16 v[6:9], v[204:207], v[244:247], v[6:9]
	v_mfma_f32_16x16x32_bf16 v[6:9], v[208:211], v[248:251], v[6:9]
	v_mfma_f32_16x16x32_bf16 v[2:5], v[212:215], v[244:247], v[2:5]
	v_mfma_f32_16x16x32_bf16 v[2:5], v[216:219], v[248:251], v[2:5]
	v_mfma_f32_16x16x32_bf16 v[18:21], v[212:215], v[236:239], v[18:21]
	v_mfma_f32_16x16x32_bf16 v[18:21], v[216:219], v[240:243], v[18:21]
	v_mfma_f32_16x16x32_bf16 v[34:37], v[212:215], v[228:231], v[34:37]
	v_mfma_f32_16x16x32_bf16 v[34:37], v[216:219], v[232:235], v[34:37]
	v_mfma_f32_16x16x32_bf16 v[50:53], v[212:215], v[220:223], v[50:53]
	v_mfma_f32_16x16x32_bf16 v[50:53], v[216:219], v[224:227], v[50:53]
	s_barrier
	s_add_i32 s62, 0, 0x18000
	v_add_u32_e32 v145, s62, v166
	s_add_i32 s63, 0, 0x1c000
	ds_read_b128 v[156:159], v145
	ds_read_b128 v[160:163], v145 offset:1024
	ds_read_b128 v[196:199], v145 offset:2048
	ds_read_b128 v[200:203], v145 offset:3072
	v_add_u32_e32 v145, s63, v166
	ds_read_b128 v[204:207], v145
	ds_read_b128 v[208:211], v145 offset:1024
	ds_read_b128 v[212:215], v145 offset:2048
	ds_read_b128 v[216:219], v145 offset:3072
	s_mov_b32 m0, s30
	s_nop 0
	global_load_lds_dwordx4 v130, s[46:47]
	s_mov_b32 m0, s31
	s_nop 0
	global_load_lds_dwordx4 v134, s[46:47]
	s_add_u32 s46, s46, 0x4000
	s_addc_u32 s47, s47, 0
	s_mov_b32 m0, s35
	ds_read_b128 v[220:223], v186 offset:32768
	ds_read_b128 v[224:227], v186 offset:33792
	ds_read_b128 v[228:231], v186 offset:34816
	ds_read_b128 v[232:235], v186 offset:35840
	ds_read_b128 v[236:239], v186 offset:36864
	ds_read_b128 v[240:243], v186 offset:37888
	ds_read_b128 v[244:247], v186 offset:38912
	ds_read_b128 v[248:251], v186 offset:39936
	global_load_lds_dwordx4 v130, s[46:47]
	s_mov_b32 m0, s48
	s_nop 0
	global_load_lds_dwordx4 v134, s[46:47]
	s_waitcnt vmcnt(8)
	s_waitcnt lgkmcnt(0)
	s_barrier
; #define PG8_STAGE(bufoff, gbase, voff) do { _Pragma("unroll") for (int _i = 0; _i < 2; ++_i) \
;         __builtin_amdgcn_global_load_lds((const unsigned*)((const char*)(gbase) + (voff)[_i]), (PG8_LAS unsigned*)(lds + (bufoff) + ldsw + _i * 8192), 16, 0, 0); } while (0)
; #define PG8_LDA(dst, b, h) do { _Pragma("unroll") for (int m = 0; m < 4; ++m) _Pragma("unroll") for (int k = 0; k < 2; ++k) dst[m][k] = *(const PG8_LAS bf16x8*)(lds + PG8_SA(b, h) + aoff + m * 2048 + k * 1024); } while (0)
; #define PG8_LDB(dst, b, h) do { _Pragma("unroll") for (int n = 0; n < 2; ++n) _Pragma("unroll") for (int k = 0; k < 2; ++k) dst[n][k] = *(const PG8_LAS bf16x8*)(lds + PG8_SB(b, h) + boff + n * 2048 + k * 1024); } while (0)
; template <class Epi, class Sched, bool ALIGN_EPI = false, bool SP2 = false>
; __device__ __forceinline__ void gemm_phase(PG8_LAS unsigned char* lds, const Gemm g, const Sched& S, const Epi& E) {
;     ...
;         for (; t < tend; t += 2) {
;             const bool last = (t == nt - 2);
;             const char* a1 = cA + (size_t)(t + 1) * kstep;
;             const char* a2 = last ? nA : cA + (size_t)(t + 2) * kstep; const char* b2 = last ? nB : cB + (size_t)(t + 2) * kstep;
;             const char* a3 = a2 + kstep; const char* b3 = b2 + kstep;
;             if (last && has_next) S.a_ready(nxt);
;             if constexpr (SP2) {
;             PG8_LDB(B0, 0, 0); PG8_LDB(B1, 0, 1); PG8_SCHED; PG8_LDA(At, 0, 0); PG8_STAGE(PG8_SA(1, 1), a1 + hstep, voffA);
;             PG8_WAIT_V(8); PG8_WAIT_L(0); PG8_BAR; PG8_MMA(0, 0, At, B0); PG8_MMA(0, 1, At, B1); PG8_BAR; PG8_SCHED;
;             PG8_LDA(At, 0, 1); PG8_STAGE(PG8_SB(0, 0), b2, voffB); PG8_STAGE(PG8_SB(0, 1), b2 + hstep, voffB); PG8_STAGE(PG8_SA(0, 0), a2, voffA);
;             PG8_WAIT_V(8); PG8_WAIT_L(0); PG8_BAR; PG8_MMA(1, 0, At, B0); PG8_MMA(1, 1, At, B1); PG8_BAR; PG8_SCHED;
;             PG8_LDB(B0, 1, 0); PG8_LDB(B1, 1, 1); PG8_SCHED; PG8_LDA(At, 1, 0); PG8_STAGE(PG8_SA(0, 1), a2 + hstep, voffA);
;             PG8_WAIT_V(8); PG8_WAIT_L(0); PG8_BAR; PG8_MMA(0, 0, At, B0); PG8_MMA(0, 1, At, B1); PG8_BAR; PG8_SCHED;
;             PG8_LDA(At, 1, 1); PG8_STAGE(PG8_SB(1, 0), b3, voffB); PG8_STAGE(PG8_SB(1, 1), b3 + hstep, voffB); PG8_STAGE(PG8_SA(1, 0), a3, voffA);
;             PG8_WAIT_V(8); PG8_WAIT_L(0); PG8_BAR; PG8_MMA(1, 0, At, B0); PG8_MMA(1, 1, At, B1); PG8_BAR; PG8_SCHED;
	s_waitcnt lgkmcnt(0)
	v_mfma_f32_16x16x32_bf16 v[126:129], v[156:159], v[220:223], v[126:129]
	v_mfma_f32_16x16x32_bf16 v[126:129], v[160:163], v[224:227], v[126:129]
	v_mfma_f32_16x16x32_bf16 v[110:113], v[156:159], v[228:231], v[110:113]
	v_mfma_f32_16x16x32_bf16 v[110:113], v[160:163], v[232:235], v[110:113]
	v_mfma_f32_16x16x32_bf16 v[94:97], v[156:159], v[236:239], v[94:97]
	v_mfma_f32_16x16x32_bf16 v[94:97], v[160:163], v[240:243], v[94:97]
	v_mfma_f32_16x16x32_bf16 v[78:81], v[156:159], v[244:247], v[78:81]
	v_mfma_f32_16x16x32_bf16 v[78:81], v[160:163], v[248:251], v[78:81]
	v_mfma_f32_16x16x32_bf16 v[74:77], v[196:199], v[244:247], v[74:77]
	v_mfma_f32_16x16x32_bf16 v[74:77], v[200:203], v[248:251], v[74:77]
	v_mfma_f32_16x16x32_bf16 v[90:93], v[196:199], v[236:239], v[90:93]
	v_mfma_f32_16x16x32_bf16 v[90:93], v[200:203], v[240:243], v[90:93]
	v_mfma_f32_16x16x32_bf16 v[106:109], v[196:199], v[228:231], v[106:109]
	v_mfma_f32_16x16x32_bf16 v[106:109], v[200:203], v[232:235], v[106:109]
	v_mfma_f32_16x16x32_bf16 v[122:125], v[196:199], v[220:223], v[122:125]
	v_mfma_f32_16x16x32_bf16 v[122:125], v[200:203], v[224:227], v[122:125]
	v_mfma_f32_16x16x32_bf16 v[118:121], v[204:207], v[220:223], v[118:121]
	v_mfma_f32_16x16x32_bf16 v[118:121], v[208:211], v[224:227], v[118:121]
	v_mfma_f32_16x16x32_bf16 v[102:105], v[204:207], v[228:231], v[102:105]
	v_mfma_f32_16x16x32_bf16 v[102:105], v[208:211], v[232:235], v[102:105]
	v_mfma_f32_16x16x32_bf16 v[86:89], v[204:207], v[236:239], v[86:89]
	v_mfma_f32_16x16x32_bf16 v[86:89], v[208:211], v[240:243], v[86:89]
	v_mfma_f32_16x16x32_bf16 v[70:73], v[204:207], v[244:247], v[70:73]
	v_mfma_f32_16x16x32_bf16 v[70:73], v[208:211], v[248:251], v[70:73]
	v_mfma_f32_16x16x32_bf16 v[66:69], v[212:215], v[244:247], v[66:69]
	v_mfma_f32_16x16x32_bf16 v[66:69], v[216:219], v[248:251], v[66:69]
	v_mfma_f32_16x16x32_bf16 v[82:85], v[212:215], v[236:239], v[82:85]
	v_mfma_f32_16x16x32_bf16 v[82:85], v[216:219], v[240:243], v[82:85]
	v_mfma_f32_16x16x32_bf16 v[98:101], v[212:215], v[228:231], v[98:101]
	v_mfma_f32_16x16x32_bf16 v[98:101], v[216:219], v[232:235], v[98:101]
	v_mfma_f32_16x16x32_bf16 v[114:117], v[212:215], v[220:223], v[114:117]
	v_mfma_f32_16x16x32_bf16 v[114:117], v[216:219], v[224:227], v[114:117]
	s_barrier
	s_add_u32 s46, s44, 0x8000
	s_addc_u32 s47, s45, 0
	s_add_i32 s62, s62, s29
	s_mov_b32 m0, s62
	ds_read_b128 v[220:223], v186 offset:49152
	ds_read_b128 v[224:227], v186 offset:50176
	ds_read_b128 v[228:231], v186 offset:51200
	ds_read_b128 v[232:235], v186 offset:52224
	ds_read_b128 v[236:239], v186 offset:53248
	ds_read_b128 v[240:243], v186 offset:54272
	ds_read_b128 v[244:247], v186 offset:55296
	ds_read_b128 v[248:251], v186 offset:56320
	global_load_lds_dwordx4 v132, s[46:47]
	s_add_i32 m0, s62, 0x2000
	s_add_u32 s44, s44, 0xc000
	v_lshl_add_u64 v[164:165], s[46:47], 0, v[136:137]
	s_addc_u32 s45, s45, 0
	s_add_i32 s46, s63, s29
	global_load_lds_dwordx4 v[164:165], off
	s_mov_b32 m0, s46
	s_nop 0
	global_load_lds_dwordx4 v132, s[44:45]
	s_add_i32 m0, s46, 0x2000
	s_nop 0
	global_load_lds_dwordx4 v136, s[44:45]
	s_waitcnt vmcnt(6)
	s_waitcnt lgkmcnt(0)
	s_barrier
	s_waitcnt lgkmcnt(0)
	v_mfma_f32_16x16x32_bf16 v[62:65], v[156:159], v[220:223], v[62:65]
	v_mfma_f32_16x16x32_bf16 v[62:65], v[160:163], v[224:227], v[62:65]
	v_mfma_f32_16x16x32_bf16 v[46:49], v[156:159], v[228:231], v[46:49]
	v_mfma_f32_16x16x32_bf16 v[46:49], v[160:163], v[232:235], v[46:49]
	v_mfma_f32_16x16x32_bf16 v[30:33], v[156:159], v[236:239], v[30:33]
	v_mfma_f32_16x16x32_bf16 v[30:33], v[160:163], v[240:243], v[30:33]
	v_mfma_f32_16x16x32_bf16 v[14:17], v[156:159], v[244:247], v[14:17]
	v_mfma_f32_16x16x32_bf16 v[14:17], v[160:163], v[248:251], v[14:17]
	v_mfma_f32_16x16x32_bf16 v[10:13], v[196:199], v[244:247], v[10:13]
	v_mfma_f32_16x16x32_bf16 v[10:13], v[200:203], v[248:251], v[10:13]
	v_mfma_f32_16x16x32_bf16 v[26:29], v[196:199], v[236:239], v[26:29]
	v_mfma_f32_16x16x32_bf16 v[26:29], v[200:203], v[240:243], v[26:29]
	v_mfma_f32_16x16x32_bf16 v[42:45], v[196:199], v[228:231], v[42:45]
	v_mfma_f32_16x16x32_bf16 v[42:45], v[200:203], v[232:235], v[42:45]
	v_mfma_f32_16x16x32_bf16 v[58:61], v[196:199], v[220:223], v[58:61]
	v_mfma_f32_16x16x32_bf16 v[58:61], v[200:203], v[224:227], v[58:61]
	v_mfma_f32_16x16x32_bf16 v[54:57], v[204:207], v[220:223], v[54:57]
	v_mfma_f32_16x16x32_bf16 v[54:57], v[208:211], v[224:227], v[54:57]
	v_mfma_f32_16x16x32_bf16 v[38:41], v[204:207], v[228:231], v[38:41]
	v_mfma_f32_16x16x32_bf16 v[38:41], v[208:211], v[232:235], v[38:41]
	v_mfma_f32_16x16x32_bf16 v[22:25], v[204:207], v[236:239], v[22:25]
	v_mfma_f32_16x16x32_bf16 v[22:25], v[208:211], v[240:243], v[22:25]
	v_mfma_f32_16x16x32_bf16 v[6:9], v[204:207], v[244:247], v[6:9]
	v_mfma_f32_16x16x32_bf16 v[6:9], v[208:211], v[248:251], v[6:9]
	v_mfma_f32_16x16x32_bf16 v[2:5], v[212:215], v[244:247], v[2:5]
	v_mfma_f32_16x16x32_bf16 v[2:5], v[216:219], v[248:251], v[2:5]
	v_mfma_f32_16x16x32_bf16 v[18:21], v[212:215], v[236:239], v[18:21]
	v_mfma_f32_16x16x32_bf16 v[18:21], v[216:219], v[240:243], v[18:21]
	v_mfma_f32_16x16x32_bf16 v[34:37], v[212:215], v[228:231], v[34:37]
	v_mfma_f32_16x16x32_bf16 v[34:37], v[216:219], v[232:235], v[34:37]
	v_mfma_f32_16x16x32_bf16 v[50:53], v[212:215], v[220:223], v[50:53]
	v_mfma_f32_16x16x32_bf16 v[50:53], v[216:219], v[224:227], v[50:53]
	s_barrier
	s_cmpk_gt_u32 s59, 0xa9
	s_mov_b32 s59, s24
	s_cbranch_scc0 .LBB0_939
	s_and_b64 vcc, exec, s[38:39]
	s_cbranch_vccz .LBB0_942
	s_barrier
